# non-temporal hint on the elementwise phase's read-once streams (conv z rows, f32 weights being converted)
# speedup vs baseline: 1.0149x; 1.0074x over previous
; __device__ __forceinline__ float bf_lo(unsigned w) { return __uint_as_float(w << 16); }
; __global__ void __launch_bounds__(512, 2) trunk_fwd(Args args) {
;     ...
;                 if (t0 != 0) {
;                     const u32x4 c1 = *(const u32x4*)(Z + (size_t)(r0 - 1) * INP + 1280 + c0), c2 = *(const u32x4*)(Z + (size_t)(r0 - 2) * INP + 1280 + c0);
; #pragma unroll
;                     for (int i = 0; i < 4; ++i) { u1[2 * i] = bf_lo(c1[i]); u1[2 * i + 1] = bf_hi(c1[i]); u2[2 * i] = bf_lo(c2[i]); u2[2 * i + 1] = bf_hi(c2[i]); }
;                 }
;                 u32x4 gb_n = *(const u32x4*)(Z + (size_t)r0 * INP + 768 + c0), gu_n = *(const u32x4*)(Z + (size_t)r0 * INP + 1280 + c0);
;                 f32x4 pv_n = *(const f32x4*)(pl + (size_t)r0 * PLE + lane * 4);
; #pragma nounroll
;                 for (int rr = 0; rr < 16; ++rr) {
;                     const int r = r0 + rr;
;                     const u32x4 gb = gb_n, gu = gu_n; const f32x4 pv4 = pv_n;
;                     if (rr < 15) { gb_n = *(const u32x4*)(Z + (size_t)(r + 1) * INP + 768 + c0); gu_n = *(const u32x4*)(Z + (size_t)(r + 1) * INP + 1280 + c0);
;                                    pv_n = *(const f32x4*)(pl + (size_t)(r + 1) * PLE + lane * 4); }
;                     float cv[8], uu[8]; float ss = 0.f;
; #pragma unroll
;                     for (int i = 0; i < 4; ++i) {
;                         uu[2 * i] = bf_lo(gu[i]); uu[2 * i + 1] = bf_hi(gu[i]);
;                         cv[2 * i] = bf_lo(gb[i]) * (w0[2 * i] * uu[2 * i] + w1[2 * i] * u1[2 * i] + w2[2 * i] * u2[2 * i]);
;                         cv[2 * i + 1] = bf_hi(gb[i]) * (w0[2 * i + 1] * uu[2 * i + 1] + w1[2 * i + 1] * u1[2 * i + 1] + w2[2 * i + 1] * u2[2 * i + 1]);
;                     }
; #pragma unroll
;                     for (int i = 0; i < 8; ++i) { ss += cv[i] * cv[i]; u2[i] = u1[i]; u1[i] = uu[i]; }
;                     ss = wave_sum(ss);
;                     const float rc = rsqrtf(ss * (1.0f / 512.0f) + EPS);
;                     u32x4 oc;
; #pragma unroll
;                     for (int i = 0; i < 4; ++i) oc[i] = cvt_pk_bf16(cv[2 * i] * rc, cv[2 * i + 1] * rc);
;                     *(u32x4*)(MIX + (size_t)r * 1024 + 512 + c0) = oc;
;                     u32x2 pw; pw.x = cvt_pk_bf16(pv4[0], pv4[1]); pw.y = cvt_pk_bf16(pv4[2], pv4[3]);
;                     *(u32x2*)(PB + (size_t)r * PLE + lane * 4) = pw;
.Lcv_taps_ok:
	v_mad_i64_i32 v[152:153], vcc, s41, v221, v[58:59]
	s_add_u32 s41, s41, 1
	global_load_dwordx4 v[2:5], v[152:153], off offset:1536 nt
	global_load_dwordx4 v[18:21], v[152:153], off offset:2560 nt
	v_mad_i64_i32 v[152:153], vcc, s41, v221, v[58:59]
	s_add_u32 s41, s41, 1
	global_load_dwordx4 v[6:9], v[152:153], off offset:1536 nt
	global_load_dwordx4 v[22:25], v[152:153], off offset:2560 nt
	v_mad_i64_i32 v[152:153], vcc, s41, v221, v[58:59]
	s_add_u32 s41, s41, 1
	global_load_dwordx4 v[10:13], v[152:153], off offset:1536 nt
	global_load_dwordx4 v[26:29], v[152:153], off offset:2560 nt
	v_mad_i64_i32 v[152:153], vcc, s41, v221, v[58:59]
	s_add_u32 s41, s41, 1
	global_load_dwordx4 v[14:17], v[152:153], off offset:1536 nt
	global_load_dwordx4 v[30:33], v[152:153], off offset:2560 nt
	s_waitcnt vmcnt(6)
	v_lshlrev_b32_e32 v188, 16, v18
	v_and_b32_e32 v189, 0xffff0000, v18
	v_lshlrev_b32_e32 v190, 16, v19
	v_and_b32_e32 v191, 0xffff0000, v19
	v_lshlrev_b32_e32 v192, 16, v20
	v_and_b32_e32 v193, 0xffff0000, v20
	v_lshlrev_b32_e32 v194, 16, v21
	v_and_b32_e32 v195, 0xffff0000, v21
	v_mul_f32_e32 v140, v164, v188
	v_mul_f32_e32 v141, v165, v189
	v_mul_f32_e32 v142, v166, v190
	v_mul_f32_e32 v143, v167, v191
	v_mul_f32_e32 v144, v168, v192
	v_mul_f32_e32 v145, v169, v193
	v_mul_f32_e32 v146, v170, v194
	v_mul_f32_e32 v147, v171, v195
	v_fmac_f32_e32 v140, v172, v204
	v_fmac_f32_e32 v141, v173, v205
	v_fmac_f32_e32 v142, v174, v206
	v_fmac_f32_e32 v143, v175, v207
	v_fmac_f32_e32 v144, v176, v208
	v_fmac_f32_e32 v145, v177, v209
	v_fmac_f32_e32 v146, v178, v210
	v_fmac_f32_e32 v147, v179, v211
	v_fmac_f32_e32 v140, v180, v196
	v_fmac_f32_e32 v141, v181, v197
	v_fmac_f32_e32 v142, v182, v198
	v_fmac_f32_e32 v143, v183, v199
	v_fmac_f32_e32 v144, v184, v200
	v_fmac_f32_e32 v145, v185, v201
	v_fmac_f32_e32 v146, v186, v202
	v_fmac_f32_e32 v147, v187, v203
	v_lshlrev_b32_e32 v150, 16, v2
	v_and_b32_e32 v151, 0xffff0000, v2
	v_mul_f32_e32 v140, v150, v140
	v_mul_f32_e32 v141, v151, v141
	v_lshlrev_b32_e32 v150, 16, v3
	v_and_b32_e32 v151, 0xffff0000, v3
	v_mul_f32_e32 v142, v150, v142
	v_mul_f32_e32 v143, v151, v143
	v_lshlrev_b32_e32 v150, 16, v4
	v_and_b32_e32 v151, 0xffff0000, v4
	v_mul_f32_e32 v144, v150, v144
	v_mul_f32_e32 v145, v151, v145
	v_lshlrev_b32_e32 v150, 16, v5
	v_and_b32_e32 v151, 0xffff0000, v5
	v_mul_f32_e32 v146, v150, v146
	v_mul_f32_e32 v147, v151, v147
	v_mul_f32_e32 v148, v140, v140
	v_fmac_f32_e32 v148, v141, v141
	v_fmac_f32_e32 v148, v142, v142
	v_fmac_f32_e32 v148, v143, v143
	v_fmac_f32_e32 v148, v144, v144
	v_fmac_f32_e32 v148, v145, v145
	v_fmac_f32_e32 v148, v146, v146
	v_fmac_f32_e32 v148, v147, v147
	v_mad_i64_i32 v[152:153], vcc, s41, v221, v[58:59]
	s_add_u32 s41, s41, 1
	global_load_dwordx4 v[2:5], v[152:153], off offset:1536 nt
	global_load_dwordx4 v[18:21], v[152:153], off offset:2560 nt
	s_nop 1
	v_add_f32_dpp v148, v148, v148 quad_perm:[1,0,3,2] row_mask:0xf bank_mask:0xf
	s_nop 1
	v_add_f32_dpp v148, v148, v148 quad_perm:[2,3,0,1] row_mask:0xf bank_mask:0xf
	s_nop 1
	v_add_f32_dpp v148, v148, v148 row_half_mirror row_mask:0xf bank_mask:0xf
	s_nop 1
	v_add_f32_dpp v148, v148, v148 row_mirror row_mask:0xf bank_mask:0xf
	s_nop 1
	v_add_f32_dpp v148, v148, v148 row_bcast:15 row_mask:0xa bank_mask:0xf
	s_nop 1
	v_add_f32_dpp v148, v148, v148 row_bcast:31 row_mask:0xc bank_mask:0xf
	s_nop 0
	v_readlane_b32 s0, v148, 63
	s_nop 1
	v_mov_b32_e32 v148, s0
	v_fmamk_f32 v148, v148, 0x3b000000, v162
	v_mul_f32_e32 v150, 0x4b800000, v148
	v_cmp_gt_f32_e32 vcc, s31, v148
	s_nop 1
	v_cndmask_b32_e32 v148, v148, v150, vcc
	v_rsq_f32_e32 v148, v148
	s_nop 0
	v_mul_f32_e32 v150, 0x45800000, v148
	v_cndmask_b32_e32 v149, v148, v150, vcc
	v_mul_f32_e32 v140, v149, v140
	v_mul_f32_e32 v141, v149, v141
	v_mul_f32_e32 v142, v149, v142
	v_mul_f32_e32 v143, v149, v143
	v_mul_f32_e32 v144, v149, v144
	v_mul_f32_e32 v145, v149, v145
	v_mul_f32_e32 v146, v149, v146
	v_mul_f32_e32 v147, v149, v147
	v_cvt_pk_bf16_f32 v140, v140, v141
	v_cvt_pk_bf16_f32 v141, v142, v143
	v_cvt_pk_bf16_f32 v142, v144, v145
	v_cvt_pk_bf16_f32 v143, v146, v147
	global_store_dwordx4 v[156:157], v[140:143], off sc1
	s_waitcnt vmcnt(7)
	v_lshlrev_b32_e32 v196, 16, v22
	v_and_b32_e32 v197, 0xffff0000, v22
	v_lshlrev_b32_e32 v198, 16, v23
	v_and_b32_e32 v199, 0xffff0000, v23
	v_lshlrev_b32_e32 v200, 16, v24
	v_and_b32_e32 v201, 0xffff0000, v24
	v_lshlrev_b32_e32 v202, 16, v25
	v_and_b32_e32 v203, 0xffff0000, v25
	v_mul_f32_e32 v140, v164, v196
	v_mul_f32_e32 v141, v165, v197
	v_mul_f32_e32 v142, v166, v198
	v_mul_f32_e32 v143, v167, v199
	v_mul_f32_e32 v144, v168, v200
	v_mul_f32_e32 v145, v169, v201
	v_mul_f32_e32 v146, v170, v202
	v_mul_f32_e32 v147, v171, v203
	v_fmac_f32_e32 v140, v172, v188
	v_fmac_f32_e32 v141, v173, v189
	v_fmac_f32_e32 v142, v174, v190
	v_fmac_f32_e32 v143, v175, v191
	v_fmac_f32_e32 v144, v176, v192
	v_fmac_f32_e32 v145, v177, v193
	v_fmac_f32_e32 v146, v178, v194
	v_fmac_f32_e32 v147, v179, v195
	v_fmac_f32_e32 v140, v180, v204
	v_fmac_f32_e32 v141, v181, v205
	v_fmac_f32_e32 v142, v182, v206
	v_fmac_f32_e32 v143, v183, v207
	v_fmac_f32_e32 v144, v184, v208
	v_fmac_f32_e32 v145, v185, v209
	v_fmac_f32_e32 v146, v186, v210
	v_fmac_f32_e32 v147, v187, v211
	v_lshlrev_b32_e32 v150, 16, v6
	v_and_b32_e32 v151, 0xffff0000, v6
	v_mul_f32_e32 v140, v150, v140
	v_mul_f32_e32 v141, v151, v141
	v_lshlrev_b32_e32 v150, 16, v7
	v_and_b32_e32 v151, 0xffff0000, v7
	v_mul_f32_e32 v142, v150, v142
	v_mul_f32_e32 v143, v151, v143
	v_lshlrev_b32_e32 v150, 16, v8
	v_and_b32_e32 v151, 0xffff0000, v8
	v_mul_f32_e32 v144, v150, v144
; __device__ __forceinline__ unsigned cvt_pk_bf16(float lo, float hi) { unsigned r; asm volatile("v_cvt_pk_bf16_f32 %0, %1, %2" : "=v"(r) : "v"(lo), "v"(hi)); return r; }
; __device__ __forceinline__ float bf_lo(unsigned w) { return __uint_as_float(w << 16); }
; __device__ __forceinline__ float bf_hi(unsigned w) { return __uint_as_float(w & 0xffff0000u); }
; __global__ void __launch_bounds__(512, 2) trunk_fwd(Args args) {
;     ...
;                 for (int rr = 0; rr < 16; ++rr) {
;                     const int r = r0 + rr;
;                     const u32x4 gb = gb_n, gu = gu_n; const f32x4 pv4 = pv_n;
;                     if (rr < 15) { gb_n = *(const u32x4*)(Z + (size_t)(r + 1) * INP + 768 + c0); gu_n = *(const u32x4*)(Z + (size_t)(r + 1) * INP + 1280 + c0);
;                                    pv_n = *(const f32x4*)(pl + (size_t)(r + 1) * PLE + lane * 4); }
;                     float cv[8], uu[8]; float ss = 0.f;
; #pragma unroll
;                     for (int i = 0; i < 4; ++i) {
;                         uu[2 * i] = bf_lo(gu[i]); uu[2 * i + 1] = bf_hi(gu[i]);
;                         cv[2 * i] = bf_lo(gb[i]) * (w0[2 * i] * uu[2 * i] + w1[2 * i] * u1[2 * i] + w2[2 * i] * u2[2 * i]);
;                         cv[2 * i + 1] = bf_hi(gb[i]) * (w0[2 * i + 1] * uu[2 * i + 1] + w1[2 * i + 1] * u1[2 * i + 1] + w2[2 * i + 1] * u2[2 * i + 1]);
;                     }
; #pragma unroll
;                     for (int i = 0; i < 8; ++i) { ss += cv[i] * cv[i]; u2[i] = u1[i]; u1[i] = uu[i]; }
;                     ss = wave_sum(ss);
;                     const float rc = rsqrtf(ss * (1.0f / 512.0f) + EPS);
;                     u32x4 oc;
; #pragma unroll
;                     for (int i = 0; i < 4; ++i) oc[i] = cvt_pk_bf16(cv[2 * i] * rc, cv[2 * i + 1] * rc);
;                     *(u32x4*)(MIX + (size_t)r * 1024 + 512 + c0) = oc;
;                     u32x2 pw; pw.x = cvt_pk_bf16(pv4[0], pv4[1]); pw.y = cvt_pk_bf16(pv4[2], pv4[3]);
;                     *(u32x2*)(PB + (size_t)r * PLE + lane * 4) = pw;
	v_mul_f32_e32 v145, v151, v145
	v_lshlrev_b32_e32 v150, 16, v9
	v_and_b32_e32 v151, 0xffff0000, v9
	v_mul_f32_e32 v146, v150, v146
	v_mul_f32_e32 v147, v151, v147
	v_mul_f32_e32 v148, v140, v140
	v_fmac_f32_e32 v148, v141, v141
	v_fmac_f32_e32 v148, v142, v142
	v_fmac_f32_e32 v148, v143, v143
	v_fmac_f32_e32 v148, v144, v144
	v_fmac_f32_e32 v148, v145, v145
	v_fmac_f32_e32 v148, v146, v146
	v_fmac_f32_e32 v148, v147, v147
	v_mad_i64_i32 v[152:153], vcc, s41, v221, v[58:59]
	s_add_u32 s41, s41, 1
	global_load_dwordx4 v[6:9], v[152:153], off offset:1536 nt
	global_load_dwordx4 v[22:25], v[152:153], off offset:2560 nt
	s_nop 1
	v_add_f32_dpp v148, v148, v148 quad_perm:[1,0,3,2] row_mask:0xf bank_mask:0xf
	s_nop 1
	v_add_f32_dpp v148, v148, v148 quad_perm:[2,3,0,1] row_mask:0xf bank_mask:0xf
	s_nop 1
	v_add_f32_dpp v148, v148, v148 row_half_mirror row_mask:0xf bank_mask:0xf
	s_nop 1
	v_add_f32_dpp v148, v148, v148 row_mirror row_mask:0xf bank_mask:0xf
	s_nop 1
	v_add_f32_dpp v148, v148, v148 row_bcast:15 row_mask:0xa bank_mask:0xf
	s_nop 1
	v_add_f32_dpp v148, v148, v148 row_bcast:31 row_mask:0xc bank_mask:0xf
	s_nop 0
	v_readlane_b32 s0, v148, 63
	s_nop 1
	v_mov_b32_e32 v148, s0
	v_fmamk_f32 v148, v148, 0x3b000000, v162
	v_mul_f32_e32 v150, 0x4b800000, v148
	v_cmp_gt_f32_e32 vcc, s31, v148
	s_nop 1
	v_cndmask_b32_e32 v148, v148, v150, vcc
	v_rsq_f32_e32 v148, v148
	s_nop 0
	v_mul_f32_e32 v150, 0x45800000, v148
	v_cndmask_b32_e32 v149, v148, v150, vcc
	v_mul_f32_e32 v140, v149, v140
	v_mul_f32_e32 v141, v149, v141
	v_mul_f32_e32 v142, v149, v142
	v_mul_f32_e32 v143, v149, v143
	v_mul_f32_e32 v144, v149, v144
	v_mul_f32_e32 v145, v149, v145
	v_mul_f32_e32 v146, v149, v146
	v_mul_f32_e32 v147, v149, v147
	v_cvt_pk_bf16_f32 v140, v140, v141
	v_cvt_pk_bf16_f32 v141, v142, v143
	v_cvt_pk_bf16_f32 v142, v144, v145
	v_cvt_pk_bf16_f32 v143, v146, v147
	global_store_dwordx4 v[156:157], v[140:143], off offset:2048 sc1
	v_lshl_add_u64 v[156:157], v[156:157], 0, s[20:21]
	s_waitcnt vmcnt(8)
	v_lshlrev_b32_e32 v204, 16, v26
	v_and_b32_e32 v205, 0xffff0000, v26
	v_lshlrev_b32_e32 v206, 16, v27
	v_and_b32_e32 v207, 0xffff0000, v27
	v_lshlrev_b32_e32 v208, 16, v28
	v_and_b32_e32 v209, 0xffff0000, v28
	v_lshlrev_b32_e32 v210, 16, v29
	v_and_b32_e32 v211, 0xffff0000, v29
	v_mul_f32_e32 v140, v164, v204
	v_mul_f32_e32 v141, v165, v205
	v_mul_f32_e32 v142, v166, v206
	v_mul_f32_e32 v143, v167, v207
	v_mul_f32_e32 v144, v168, v208
	v_mul_f32_e32 v145, v169, v209
	v_mul_f32_e32 v146, v170, v210
	v_mul_f32_e32 v147, v171, v211
	v_fmac_f32_e32 v140, v172, v196
	v_fmac_f32_e32 v141, v173, v197
	v_fmac_f32_e32 v142, v174, v198
	v_fmac_f32_e32 v143, v175, v199
	v_fmac_f32_e32 v144, v176, v200
	v_fmac_f32_e32 v145, v177, v201
	v_fmac_f32_e32 v146, v178, v202
	v_fmac_f32_e32 v147, v179, v203
	v_fmac_f32_e32 v140, v180, v188
	v_fmac_f32_e32 v141, v181, v189
	v_fmac_f32_e32 v142, v182, v190
	v_fmac_f32_e32 v143, v183, v191
	v_fmac_f32_e32 v144, v184, v192
	v_fmac_f32_e32 v145, v185, v193
	v_fmac_f32_e32 v146, v186, v194
	v_fmac_f32_e32 v147, v187, v195
	v_lshlrev_b32_e32 v150, 16, v10
	v_and_b32_e32 v151, 0xffff0000, v10
	v_mul_f32_e32 v140, v150, v140
	v_mul_f32_e32 v141, v151, v141
	v_lshlrev_b32_e32 v150, 16, v11
	v_and_b32_e32 v151, 0xffff0000, v11
	v_mul_f32_e32 v142, v150, v142
	v_mul_f32_e32 v143, v151, v143
	v_lshlrev_b32_e32 v150, 16, v12
	v_and_b32_e32 v151, 0xffff0000, v12
	v_mul_f32_e32 v144, v150, v144
	v_mul_f32_e32 v145, v151, v145
	v_lshlrev_b32_e32 v150, 16, v13
	v_and_b32_e32 v151, 0xffff0000, v13
	v_mul_f32_e32 v146, v150, v146
	v_mul_f32_e32 v147, v151, v147
	v_mul_f32_e32 v148, v140, v140
	v_fmac_f32_e32 v148, v141, v141
	v_fmac_f32_e32 v148, v142, v142
	v_fmac_f32_e32 v148, v143, v143
	v_fmac_f32_e32 v148, v144, v144
	v_fmac_f32_e32 v148, v145, v145
	v_fmac_f32_e32 v148, v146, v146
	v_fmac_f32_e32 v148, v147, v147
	v_mad_i64_i32 v[152:153], vcc, s41, v221, v[58:59]
	s_add_u32 s41, s41, 1
	global_load_dwordx4 v[10:13], v[152:153], off offset:1536 nt
	global_load_dwordx4 v[26:29], v[152:153], off offset:2560 nt
	s_nop 1
	v_add_f32_dpp v148, v148, v148 quad_perm:[1,0,3,2] row_mask:0xf bank_mask:0xf
	s_nop 1
	v_add_f32_dpp v148, v148, v148 quad_perm:[2,3,0,1] row_mask:0xf bank_mask:0xf
	s_nop 1
	v_add_f32_dpp v148, v148, v148 row_half_mirror row_mask:0xf bank_mask:0xf
	s_nop 1
	v_add_f32_dpp v148, v148, v148 row_mirror row_mask:0xf bank_mask:0xf
	s_nop 1
	v_add_f32_dpp v148, v148, v148 row_bcast:15 row_mask:0xa bank_mask:0xf
	s_nop 1
	v_add_f32_dpp v148, v148, v148 row_bcast:31 row_mask:0xc bank_mask:0xf
	s_nop 0
	v_readlane_b32 s0, v148, 63
	s_nop 1
	v_mov_b32_e32 v148, s0
	v_fmamk_f32 v148, v148, 0x3b000000, v162
	v_mul_f32_e32 v150, 0x4b800000, v148
	v_cmp_gt_f32_e32 vcc, s31, v148
	s_nop 1
	v_cndmask_b32_e32 v148, v148, v150, vcc
	v_rsq_f32_e32 v148, v148
	s_nop 0
	v_mul_f32_e32 v150, 0x45800000, v148
	v_cndmask_b32_e32 v149, v148, v150, vcc
	v_mul_f32_e32 v140, v149, v140
	v_mul_f32_e32 v141, v149, v141
	v_mul_f32_e32 v142, v149, v142
	v_mul_f32_e32 v143, v149, v143
	v_mul_f32_e32 v144, v149, v144
	v_mul_f32_e32 v145, v149, v145
	v_mul_f32_e32 v146, v149, v146
	v_mul_f32_e32 v147, v149, v147
	v_cvt_pk_bf16_f32 v140, v140, v141
	v_cvt_pk_bf16_f32 v141, v142, v143
	v_cvt_pk_bf16_f32 v142, v144, v145
	v_cvt_pk_bf16_f32 v143, v146, v147
	global_store_dwordx4 v[156:157], v[140:143], off sc1
	s_waitcnt vmcnt(9)
; __device__ __forceinline__ unsigned cvt_pk_bf16(float lo, float hi) { unsigned r; asm volatile("v_cvt_pk_bf16_f32 %0, %1, %2" : "=v"(r) : "v"(lo), "v"(hi)); return r; }
; __device__ __forceinline__ float bf_lo(unsigned w) { return __uint_as_float(w << 16); }
; __device__ __forceinline__ float bf_hi(unsigned w) { return __uint_as_float(w & 0xffff0000u); }
; __global__ void __launch_bounds__(512, 2) trunk_fwd(Args args) {
;     ...
;                 for (int rr = 0; rr < 16; ++rr) {
;                     const int r = r0 + rr;
;                     const u32x4 gb = gb_n, gu = gu_n; const f32x4 pv4 = pv_n;
;                     if (rr < 15) { gb_n = *(const u32x4*)(Z + (size_t)(r + 1) * INP + 768 + c0); gu_n = *(const u32x4*)(Z + (size_t)(r + 1) * INP + 1280 + c0);
;                                    pv_n = *(const f32x4*)(pl + (size_t)(r + 1) * PLE + lane * 4); }
;                     float cv[8], uu[8]; float ss = 0.f;
; #pragma unroll
;                     for (int i = 0; i < 4; ++i) {
;                         uu[2 * i] = bf_lo(gu[i]); uu[2 * i + 1] = bf_hi(gu[i]);
;                         cv[2 * i] = bf_lo(gb[i]) * (w0[2 * i] * uu[2 * i] + w1[2 * i] * u1[2 * i] + w2[2 * i] * u2[2 * i]);
;                         cv[2 * i + 1] = bf_hi(gb[i]) * (w0[2 * i + 1] * uu[2 * i + 1] + w1[2 * i + 1] * u1[2 * i + 1] + w2[2 * i + 1] * u2[2 * i + 1]);
;                     }
; #pragma unroll
;                     for (int i = 0; i < 8; ++i) { ss += cv[i] * cv[i]; u2[i] = u1[i]; u1[i] = uu[i]; }
;                     ss = wave_sum(ss);
;                     const float rc = rsqrtf(ss * (1.0f / 512.0f) + EPS);
;                     u32x4 oc;
; #pragma unroll
;                     for (int i = 0; i < 4; ++i) oc[i] = cvt_pk_bf16(cv[2 * i] * rc, cv[2 * i + 1] * rc);
;                     *(u32x4*)(MIX + (size_t)r * 1024 + 512 + c0) = oc;
;                     u32x2 pw; pw.x = cvt_pk_bf16(pv4[0], pv4[1]); pw.y = cvt_pk_bf16(pv4[2], pv4[3]);
;                     *(u32x2*)(PB + (size_t)r * PLE + lane * 4) = pw;
	v_lshlrev_b32_e32 v188, 16, v30
	v_and_b32_e32 v189, 0xffff0000, v30
	v_lshlrev_b32_e32 v190, 16, v31
	v_and_b32_e32 v191, 0xffff0000, v31
	v_lshlrev_b32_e32 v192, 16, v32
	v_and_b32_e32 v193, 0xffff0000, v32
	v_lshlrev_b32_e32 v194, 16, v33
	v_and_b32_e32 v195, 0xffff0000, v33
	v_mul_f32_e32 v140, v164, v188
	v_mul_f32_e32 v141, v165, v189
	v_mul_f32_e32 v142, v166, v190
	v_mul_f32_e32 v143, v167, v191
	v_mul_f32_e32 v144, v168, v192
	v_mul_f32_e32 v145, v169, v193
	v_mul_f32_e32 v146, v170, v194
	v_mul_f32_e32 v147, v171, v195
	v_fmac_f32_e32 v140, v172, v204
	v_fmac_f32_e32 v141, v173, v205
	v_fmac_f32_e32 v142, v174, v206
	v_fmac_f32_e32 v143, v175, v207
	v_fmac_f32_e32 v144, v176, v208
	v_fmac_f32_e32 v145, v177, v209
	v_fmac_f32_e32 v146, v178, v210
	v_fmac_f32_e32 v147, v179, v211
	v_fmac_f32_e32 v140, v180, v196
	v_fmac_f32_e32 v141, v181, v197
	v_fmac_f32_e32 v142, v182, v198
	v_fmac_f32_e32 v143, v183, v199
	v_fmac_f32_e32 v144, v184, v200
	v_fmac_f32_e32 v145, v185, v201
	v_fmac_f32_e32 v146, v186, v202
	v_fmac_f32_e32 v147, v187, v203
	v_lshlrev_b32_e32 v150, 16, v14
	v_and_b32_e32 v151, 0xffff0000, v14
	v_mul_f32_e32 v140, v150, v140
	v_mul_f32_e32 v141, v151, v141
	v_lshlrev_b32_e32 v150, 16, v15
	v_and_b32_e32 v151, 0xffff0000, v15
	v_mul_f32_e32 v142, v150, v142
	v_mul_f32_e32 v143, v151, v143
	v_lshlrev_b32_e32 v150, 16, v16
	v_and_b32_e32 v151, 0xffff0000, v16
	v_mul_f32_e32 v144, v150, v144
	v_mul_f32_e32 v145, v151, v145
	v_lshlrev_b32_e32 v150, 16, v17
	v_and_b32_e32 v151, 0xffff0000, v17
	v_mul_f32_e32 v146, v150, v146
	v_mul_f32_e32 v147, v151, v147
	v_mul_f32_e32 v148, v140, v140
	v_fmac_f32_e32 v148, v141, v141
	v_fmac_f32_e32 v148, v142, v142
	v_fmac_f32_e32 v148, v143, v143
	v_fmac_f32_e32 v148, v144, v144
	v_fmac_f32_e32 v148, v145, v145
	v_fmac_f32_e32 v148, v146, v146
	v_fmac_f32_e32 v148, v147, v147
	v_mad_i64_i32 v[152:153], vcc, s41, v221, v[58:59]
	s_add_u32 s41, s41, 1
	global_load_dwordx4 v[14:17], v[152:153], off offset:1536 nt
	global_load_dwordx4 v[30:33], v[152:153], off offset:2560 nt
	s_nop 1
	v_add_f32_dpp v148, v148, v148 quad_perm:[1,0,3,2] row_mask:0xf bank_mask:0xf
	s_nop 1
	v_add_f32_dpp v148, v148, v148 quad_perm:[2,3,0,1] row_mask:0xf bank_mask:0xf
	s_nop 1
	v_add_f32_dpp v148, v148, v148 row_half_mirror row_mask:0xf bank_mask:0xf
	s_nop 1
	v_add_f32_dpp v148, v148, v148 row_mirror row_mask:0xf bank_mask:0xf
	s_nop 1
	v_add_f32_dpp v148, v148, v148 row_bcast:15 row_mask:0xa bank_mask:0xf
	s_nop 1
	v_add_f32_dpp v148, v148, v148 row_bcast:31 row_mask:0xc bank_mask:0xf
	s_nop 0
	v_readlane_b32 s0, v148, 63
	s_nop 1
	v_mov_b32_e32 v148, s0
	v_fmamk_f32 v148, v148, 0x3b000000, v162
	v_mul_f32_e32 v150, 0x4b800000, v148
	v_cmp_gt_f32_e32 vcc, s31, v148
	s_nop 1
	v_cndmask_b32_e32 v148, v148, v150, vcc
	v_rsq_f32_e32 v148, v148
	s_nop 0
	v_mul_f32_e32 v150, 0x45800000, v148
	v_cndmask_b32_e32 v149, v148, v150, vcc
	v_mul_f32_e32 v140, v149, v140
	v_mul_f32_e32 v141, v149, v141
	v_mul_f32_e32 v142, v149, v142
	v_mul_f32_e32 v143, v149, v143
	v_mul_f32_e32 v144, v149, v144
	v_mul_f32_e32 v145, v149, v145
	v_mul_f32_e32 v146, v149, v146
	v_mul_f32_e32 v147, v149, v147
	v_cvt_pk_bf16_f32 v140, v140, v141
	v_cvt_pk_bf16_f32 v141, v142, v143
	v_cvt_pk_bf16_f32 v142, v144, v145
	v_cvt_pk_bf16_f32 v143, v146, v147
	global_store_dwordx4 v[156:157], v[140:143], off offset:2048 sc1
	v_lshl_add_u64 v[156:157], v[156:157], 0, s[20:21]
	s_waitcnt vmcnt(10)
	v_lshlrev_b32_e32 v196, 16, v18
	v_and_b32_e32 v197, 0xffff0000, v18
	v_lshlrev_b32_e32 v198, 16, v19
	v_and_b32_e32 v199, 0xffff0000, v19
	v_lshlrev_b32_e32 v200, 16, v20
	v_and_b32_e32 v201, 0xffff0000, v20
	v_lshlrev_b32_e32 v202, 16, v21
	v_and_b32_e32 v203, 0xffff0000, v21
	v_mul_f32_e32 v140, v164, v196
	v_mul_f32_e32 v141, v165, v197
	v_mul_f32_e32 v142, v166, v198
	v_mul_f32_e32 v143, v167, v199
	v_mul_f32_e32 v144, v168, v200
	v_mul_f32_e32 v145, v169, v201
	v_mul_f32_e32 v146, v170, v202
	v_mul_f32_e32 v147, v171, v203
	v_fmac_f32_e32 v140, v172, v188
	v_fmac_f32_e32 v141, v173, v189
	v_fmac_f32_e32 v142, v174, v190
	v_fmac_f32_e32 v143, v175, v191
	v_fmac_f32_e32 v144, v176, v192
	v_fmac_f32_e32 v145, v177, v193
	v_fmac_f32_e32 v146, v178, v194
	v_fmac_f32_e32 v147, v179, v195
	v_fmac_f32_e32 v140, v180, v204
	v_fmac_f32_e32 v141, v181, v205
	v_fmac_f32_e32 v142, v182, v206
	v_fmac_f32_e32 v143, v183, v207
	v_fmac_f32_e32 v144, v184, v208
	v_fmac_f32_e32 v145, v185, v209
	v_fmac_f32_e32 v146, v186, v210
	v_fmac_f32_e32 v147, v187, v211
	v_lshlrev_b32_e32 v150, 16, v2
	v_and_b32_e32 v151, 0xffff0000, v2
	v_mul_f32_e32 v140, v150, v140
	v_mul_f32_e32 v141, v151, v141
	v_lshlrev_b32_e32 v150, 16, v3
	v_and_b32_e32 v151, 0xffff0000, v3
	v_mul_f32_e32 v142, v150, v142
	v_mul_f32_e32 v143, v151, v143
	v_lshlrev_b32_e32 v150, 16, v4
	v_and_b32_e32 v151, 0xffff0000, v4
	v_mul_f32_e32 v144, v150, v144
	v_mul_f32_e32 v145, v151, v145
	v_lshlrev_b32_e32 v150, 16, v5
	v_and_b32_e32 v151, 0xffff0000, v5
	v_mul_f32_e32 v146, v150, v146
	v_mul_f32_e32 v147, v151, v147
	v_mul_f32_e32 v148, v140, v140
	v_fmac_f32_e32 v148, v141, v141
	v_fmac_f32_e32 v148, v142, v142
	v_fmac_f32_e32 v148, v143, v143
	v_fmac_f32_e32 v148, v144, v144
	v_fmac_f32_e32 v148, v145, v145
	v_fmac_f32_e32 v148, v146, v146
	v_fmac_f32_e32 v148, v147, v147
	v_mad_i64_i32 v[152:153], vcc, s41, v221, v[58:59]
	s_add_u32 s41, s41, 1
	global_load_dwordx4 v[2:5], v[152:153], off offset:1536 nt
	global_load_dwordx4 v[18:21], v[152:153], off offset:2560 nt
	s_nop 1
	v_add_f32_dpp v148, v148, v148 quad_perm:[1,0,3,2] row_mask:0xf bank_mask:0xf
	s_nop 1
	v_add_f32_dpp v148, v148, v148 quad_perm:[2,3,0,1] row_mask:0xf bank_mask:0xf
	s_nop 1
	v_add_f32_dpp v148, v148, v148 row_half_mirror row_mask:0xf bank_mask:0xf
	s_nop 1
	v_add_f32_dpp v148, v148, v148 row_mirror row_mask:0xf bank_mask:0xf
	s_nop 1
	v_add_f32_dpp v148, v148, v148 row_bcast:15 row_mask:0xa bank_mask:0xf
	s_nop 1
	v_add_f32_dpp v148, v148, v148 row_bcast:31 row_mask:0xc bank_mask:0xf
	s_nop 0
	v_readlane_b32 s0, v148, 63
	s_nop 1
	v_mov_b32_e32 v148, s0
	v_fmamk_f32 v148, v148, 0x3b000000, v162
	v_mul_f32_e32 v150, 0x4b800000, v148
	v_cmp_gt_f32_e32 vcc, s31, v148
	s_nop 1
	v_cndmask_b32_e32 v148, v148, v150, vcc
	v_rsq_f32_e32 v148, v148
	s_nop 0
	v_mul_f32_e32 v150, 0x45800000, v148
	v_cndmask_b32_e32 v149, v148, v150, vcc
	v_mul_f32_e32 v140, v149, v140
	v_mul_f32_e32 v141, v149, v141
	v_mul_f32_e32 v142, v149, v142
	v_mul_f32_e32 v143, v149, v143
	v_mul_f32_e32 v144, v149, v144
	v_mul_f32_e32 v145, v149, v145
	v_mul_f32_e32 v146, v149, v146
	v_mul_f32_e32 v147, v149, v147
	v_cvt_pk_bf16_f32 v140, v140, v141
	v_cvt_pk_bf16_f32 v141, v142, v143
	v_cvt_pk_bf16_f32 v142, v144, v145
	v_cvt_pk_bf16_f32 v143, v146, v147
	global_store_dwordx4 v[156:157], v[140:143], off sc1
	s_waitcnt vmcnt(10)
; __device__ __forceinline__ unsigned cvt_pk_bf16(float lo, float hi) { unsigned r; asm volatile("v_cvt_pk_bf16_f32 %0, %1, %2" : "=v"(r) : "v"(lo), "v"(hi)); return r; }
; __device__ __forceinline__ float bf_lo(unsigned w) { return __uint_as_float(w << 16); }
; __device__ __forceinline__ float bf_hi(unsigned w) { return __uint_as_float(w & 0xffff0000u); }
; __global__ void __launch_bounds__(512, 2) trunk_fwd(Args args) {
;     ...
;                 for (int rr = 0; rr < 16; ++rr) {
;                     const int r = r0 + rr;
;                     const u32x4 gb = gb_n, gu = gu_n; const f32x4 pv4 = pv_n;
;                     if (rr < 15) { gb_n = *(const u32x4*)(Z + (size_t)(r + 1) * INP + 768 + c0); gu_n = *(const u32x4*)(Z + (size_t)(r + 1) * INP + 1280 + c0);
;                                    pv_n = *(const f32x4*)(pl + (size_t)(r + 1) * PLE + lane * 4); }
;                     float cv[8], uu[8]; float ss = 0.f;
; #pragma unroll
;                     for (int i = 0; i < 4; ++i) {
;                         uu[2 * i] = bf_lo(gu[i]); uu[2 * i + 1] = bf_hi(gu[i]);
;                         cv[2 * i] = bf_lo(gb[i]) * (w0[2 * i] * uu[2 * i] + w1[2 * i] * u1[2 * i] + w2[2 * i] * u2[2 * i]);
;                         cv[2 * i + 1] = bf_hi(gb[i]) * (w0[2 * i + 1] * uu[2 * i + 1] + w1[2 * i + 1] * u1[2 * i + 1] + w2[2 * i + 1] * u2[2 * i + 1]);
;                     }
; #pragma unroll
;                     for (int i = 0; i < 8; ++i) { ss += cv[i] * cv[i]; u2[i] = u1[i]; u1[i] = uu[i]; }
;                     ss = wave_sum(ss);
;                     const float rc = rsqrtf(ss * (1.0f / 512.0f) + EPS);
;                     u32x4 oc;
; #pragma unroll
;                     for (int i = 0; i < 4; ++i) oc[i] = cvt_pk_bf16(cv[2 * i] * rc, cv[2 * i + 1] * rc);
;                     *(u32x4*)(MIX + (size_t)r * 1024 + 512 + c0) = oc;
;                     u32x2 pw; pw.x = cvt_pk_bf16(pv4[0], pv4[1]); pw.y = cvt_pk_bf16(pv4[2], pv4[3]);
;                     *(u32x2*)(PB + (size_t)r * PLE + lane * 4) = pw;
	v_lshlrev_b32_e32 v204, 16, v22
	v_and_b32_e32 v205, 0xffff0000, v22
	v_lshlrev_b32_e32 v206, 16, v23
	v_and_b32_e32 v207, 0xffff0000, v23
	v_lshlrev_b32_e32 v208, 16, v24
	v_and_b32_e32 v209, 0xffff0000, v24
	v_lshlrev_b32_e32 v210, 16, v25
	v_and_b32_e32 v211, 0xffff0000, v25
	v_mul_f32_e32 v140, v164, v204
	v_mul_f32_e32 v141, v165, v205
	v_mul_f32_e32 v142, v166, v206
	v_mul_f32_e32 v143, v167, v207
	v_mul_f32_e32 v144, v168, v208
	v_mul_f32_e32 v145, v169, v209
	v_mul_f32_e32 v146, v170, v210
	v_mul_f32_e32 v147, v171, v211
	v_fmac_f32_e32 v140, v172, v196
	v_fmac_f32_e32 v141, v173, v197
	v_fmac_f32_e32 v142, v174, v198
	v_fmac_f32_e32 v143, v175, v199
	v_fmac_f32_e32 v144, v176, v200
	v_fmac_f32_e32 v145, v177, v201
	v_fmac_f32_e32 v146, v178, v202
	v_fmac_f32_e32 v147, v179, v203
	v_fmac_f32_e32 v140, v180, v188
	v_fmac_f32_e32 v141, v181, v189
	v_fmac_f32_e32 v142, v182, v190
	v_fmac_f32_e32 v143, v183, v191
	v_fmac_f32_e32 v144, v184, v192
	v_fmac_f32_e32 v145, v185, v193
	v_fmac_f32_e32 v146, v186, v194
	v_fmac_f32_e32 v147, v187, v195
	v_lshlrev_b32_e32 v150, 16, v6
	v_and_b32_e32 v151, 0xffff0000, v6
	v_mul_f32_e32 v140, v150, v140
	v_mul_f32_e32 v141, v151, v141
	v_lshlrev_b32_e32 v150, 16, v7
	v_and_b32_e32 v151, 0xffff0000, v7
	v_mul_f32_e32 v142, v150, v142
	v_mul_f32_e32 v143, v151, v143
	v_lshlrev_b32_e32 v150, 16, v8
	v_and_b32_e32 v151, 0xffff0000, v8
	v_mul_f32_e32 v144, v150, v144
	v_mul_f32_e32 v145, v151, v145
	v_lshlrev_b32_e32 v150, 16, v9
	v_and_b32_e32 v151, 0xffff0000, v9
	v_mul_f32_e32 v146, v150, v146
	v_mul_f32_e32 v147, v151, v147
	v_mul_f32_e32 v148, v140, v140
	v_fmac_f32_e32 v148, v141, v141
	v_fmac_f32_e32 v148, v142, v142
	v_fmac_f32_e32 v148, v143, v143
	v_fmac_f32_e32 v148, v144, v144
	v_fmac_f32_e32 v148, v145, v145
	v_fmac_f32_e32 v148, v146, v146
	v_fmac_f32_e32 v148, v147, v147
	v_mad_i64_i32 v[152:153], vcc, s41, v221, v[58:59]
	s_add_u32 s41, s41, 1
	global_load_dwordx4 v[6:9], v[152:153], off offset:1536 nt
	global_load_dwordx4 v[22:25], v[152:153], off offset:2560 nt
	s_nop 1
	v_add_f32_dpp v148, v148, v148 quad_perm:[1,0,3,2] row_mask:0xf bank_mask:0xf
	s_nop 1
	v_add_f32_dpp v148, v148, v148 quad_perm:[2,3,0,1] row_mask:0xf bank_mask:0xf
	s_nop 1
	v_add_f32_dpp v148, v148, v148 row_half_mirror row_mask:0xf bank_mask:0xf
	s_nop 1
	v_add_f32_dpp v148, v148, v148 row_mirror row_mask:0xf bank_mask:0xf
	s_nop 1
	v_add_f32_dpp v148, v148, v148 row_bcast:15 row_mask:0xa bank_mask:0xf
	s_nop 1
	v_add_f32_dpp v148, v148, v148 row_bcast:31 row_mask:0xc bank_mask:0xf
	s_nop 0
	v_readlane_b32 s0, v148, 63
	s_nop 1
	v_mov_b32_e32 v148, s0
	v_fmamk_f32 v148, v148, 0x3b000000, v162
	v_mul_f32_e32 v150, 0x4b800000, v148
	v_cmp_gt_f32_e32 vcc, s31, v148
	s_nop 1
	v_cndmask_b32_e32 v148, v148, v150, vcc
	v_rsq_f32_e32 v148, v148
	s_nop 0
	v_mul_f32_e32 v150, 0x45800000, v148
	v_cndmask_b32_e32 v149, v148, v150, vcc
	v_mul_f32_e32 v140, v149, v140
	v_mul_f32_e32 v141, v149, v141
	v_mul_f32_e32 v142, v149, v142
	v_mul_f32_e32 v143, v149, v143
	v_mul_f32_e32 v144, v149, v144
	v_mul_f32_e32 v145, v149, v145
	v_mul_f32_e32 v146, v149, v146
	v_mul_f32_e32 v147, v149, v147
	v_cvt_pk_bf16_f32 v140, v140, v141
	v_cvt_pk_bf16_f32 v141, v142, v143
	v_cvt_pk_bf16_f32 v142, v144, v145
	v_cvt_pk_bf16_f32 v143, v146, v147
	global_store_dwordx4 v[156:157], v[140:143], off offset:2048 sc1
	v_lshl_add_u64 v[156:157], v[156:157], 0, s[20:21]
	s_waitcnt vmcnt(10)
	v_lshlrev_b32_e32 v188, 16, v26
	v_and_b32_e32 v189, 0xffff0000, v26
	v_lshlrev_b32_e32 v190, 16, v27
	v_and_b32_e32 v191, 0xffff0000, v27
	v_lshlrev_b32_e32 v192, 16, v28
	v_and_b32_e32 v193, 0xffff0000, v28
	v_lshlrev_b32_e32 v194, 16, v29
	v_and_b32_e32 v195, 0xffff0000, v29
	v_mul_f32_e32 v140, v164, v188
	v_mul_f32_e32 v141, v165, v189
	v_mul_f32_e32 v142, v166, v190
	v_mul_f32_e32 v143, v167, v191
	v_mul_f32_e32 v144, v168, v192
	v_mul_f32_e32 v145, v169, v193
	v_mul_f32_e32 v146, v170, v194
	v_mul_f32_e32 v147, v171, v195
	v_fmac_f32_e32 v140, v172, v204
	v_fmac_f32_e32 v141, v173, v205
	v_fmac_f32_e32 v142, v174, v206
	v_fmac_f32_e32 v143, v175, v207
	v_fmac_f32_e32 v144, v176, v208
	v_fmac_f32_e32 v145, v177, v209
	v_fmac_f32_e32 v146, v178, v210
	v_fmac_f32_e32 v147, v179, v211
	v_fmac_f32_e32 v140, v180, v196
	v_fmac_f32_e32 v141, v181, v197
	v_fmac_f32_e32 v142, v182, v198
	v_fmac_f32_e32 v143, v183, v199
	v_fmac_f32_e32 v144, v184, v200
	v_fmac_f32_e32 v145, v185, v201
	v_fmac_f32_e32 v146, v186, v202
	v_fmac_f32_e32 v147, v187, v203
	v_lshlrev_b32_e32 v150, 16, v10
	v_and_b32_e32 v151, 0xffff0000, v10
	v_mul_f32_e32 v140, v150, v140
	v_mul_f32_e32 v141, v151, v141
	v_lshlrev_b32_e32 v150, 16, v11
	v_and_b32_e32 v151, 0xffff0000, v11
	v_mul_f32_e32 v142, v150, v142
	v_mul_f32_e32 v143, v151, v143
	v_lshlrev_b32_e32 v150, 16, v12
	v_and_b32_e32 v151, 0xffff0000, v12
	v_mul_f32_e32 v144, v150, v144
	v_mul_f32_e32 v145, v151, v145
	v_lshlrev_b32_e32 v150, 16, v13
	v_and_b32_e32 v151, 0xffff0000, v13
	v_mul_f32_e32 v146, v150, v146
	v_mul_f32_e32 v147, v151, v147
	v_mul_f32_e32 v148, v140, v140
	v_fmac_f32_e32 v148, v141, v141
	v_fmac_f32_e32 v148, v142, v142
	v_fmac_f32_e32 v148, v143, v143
	v_fmac_f32_e32 v148, v144, v144
	v_fmac_f32_e32 v148, v145, v145
	v_fmac_f32_e32 v148, v146, v146
	v_fmac_f32_e32 v148, v147, v147
	v_mad_i64_i32 v[152:153], vcc, s41, v221, v[58:59]
	s_add_u32 s41, s41, 1
	global_load_dwordx4 v[10:13], v[152:153], off offset:1536 nt
	global_load_dwordx4 v[26:29], v[152:153], off offset:2560 nt
	s_nop 1
	v_add_f32_dpp v148, v148, v148 quad_perm:[1,0,3,2] row_mask:0xf bank_mask:0xf
	s_nop 1
	v_add_f32_dpp v148, v148, v148 quad_perm:[2,3,0,1] row_mask:0xf bank_mask:0xf
	s_nop 1
	v_add_f32_dpp v148, v148, v148 row_half_mirror row_mask:0xf bank_mask:0xf
	s_nop 1
	v_add_f32_dpp v148, v148, v148 row_mirror row_mask:0xf bank_mask:0xf
	s_nop 1
	v_add_f32_dpp v148, v148, v148 row_bcast:15 row_mask:0xa bank_mask:0xf
	s_nop 1
	v_add_f32_dpp v148, v148, v148 row_bcast:31 row_mask:0xc bank_mask:0xf
	s_nop 0
	v_readlane_b32 s0, v148, 63
	s_nop 1
	v_mov_b32_e32 v148, s0
	v_fmamk_f32 v148, v148, 0x3b000000, v162
	v_mul_f32_e32 v150, 0x4b800000, v148
	v_cmp_gt_f32_e32 vcc, s31, v148
	s_nop 1
	v_cndmask_b32_e32 v148, v148, v150, vcc
	v_rsq_f32_e32 v148, v148
	s_nop 0
	v_mul_f32_e32 v150, 0x45800000, v148
	v_cndmask_b32_e32 v149, v148, v150, vcc
	v_mul_f32_e32 v140, v149, v140
	v_mul_f32_e32 v141, v149, v141
	v_mul_f32_e32 v142, v149, v142
	v_mul_f32_e32 v143, v149, v143
	v_mul_f32_e32 v144, v149, v144
	v_mul_f32_e32 v145, v149, v145
	v_mul_f32_e32 v146, v149, v146
	v_mul_f32_e32 v147, v149, v147
	v_cvt_pk_bf16_f32 v140, v140, v141
	v_cvt_pk_bf16_f32 v141, v142, v143
	v_cvt_pk_bf16_f32 v142, v144, v145
	v_cvt_pk_bf16_f32 v143, v146, v147
	global_store_dwordx4 v[156:157], v[140:143], off sc1
	s_waitcnt vmcnt(10)
; __device__ __forceinline__ unsigned cvt_pk_bf16(float lo, float hi) { unsigned r; asm volatile("v_cvt_pk_bf16_f32 %0, %1, %2" : "=v"(r) : "v"(lo), "v"(hi)); return r; }
; __device__ __forceinline__ float bf_lo(unsigned w) { return __uint_as_float(w << 16); }
; __device__ __forceinline__ float bf_hi(unsigned w) { return __uint_as_float(w & 0xffff0000u); }
; __global__ void __launch_bounds__(512, 2) trunk_fwd(Args args) {
;     ...
;                 for (int rr = 0; rr < 16; ++rr) {
;                     const int r = r0 + rr;
;                     const u32x4 gb = gb_n, gu = gu_n; const f32x4 pv4 = pv_n;
;                     if (rr < 15) { gb_n = *(const u32x4*)(Z + (size_t)(r + 1) * INP + 768 + c0); gu_n = *(const u32x4*)(Z + (size_t)(r + 1) * INP + 1280 + c0);
;                                    pv_n = *(const f32x4*)(pl + (size_t)(r + 1) * PLE + lane * 4); }
;                     float cv[8], uu[8]; float ss = 0.f;
; #pragma unroll
;                     for (int i = 0; i < 4; ++i) {
;                         uu[2 * i] = bf_lo(gu[i]); uu[2 * i + 1] = bf_hi(gu[i]);
;                         cv[2 * i] = bf_lo(gb[i]) * (w0[2 * i] * uu[2 * i] + w1[2 * i] * u1[2 * i] + w2[2 * i] * u2[2 * i]);
;                         cv[2 * i + 1] = bf_hi(gb[i]) * (w0[2 * i + 1] * uu[2 * i + 1] + w1[2 * i + 1] * u1[2 * i + 1] + w2[2 * i + 1] * u2[2 * i + 1]);
;                     }
; #pragma unroll
;                     for (int i = 0; i < 8; ++i) { ss += cv[i] * cv[i]; u2[i] = u1[i]; u1[i] = uu[i]; }
;                     ss = wave_sum(ss);
;                     const float rc = rsqrtf(ss * (1.0f / 512.0f) + EPS);
;                     u32x4 oc;
; #pragma unroll
;                     for (int i = 0; i < 4; ++i) oc[i] = cvt_pk_bf16(cv[2 * i] * rc, cv[2 * i + 1] * rc);
;                     *(u32x4*)(MIX + (size_t)r * 1024 + 512 + c0) = oc;
;                     u32x2 pw; pw.x = cvt_pk_bf16(pv4[0], pv4[1]); pw.y = cvt_pk_bf16(pv4[2], pv4[3]);
;                     *(u32x2*)(PB + (size_t)r * PLE + lane * 4) = pw;
	v_lshlrev_b32_e32 v196, 16, v30
	v_and_b32_e32 v197, 0xffff0000, v30
	v_lshlrev_b32_e32 v198, 16, v31
	v_and_b32_e32 v199, 0xffff0000, v31
	v_lshlrev_b32_e32 v200, 16, v32
	v_and_b32_e32 v201, 0xffff0000, v32
	v_lshlrev_b32_e32 v202, 16, v33
	v_and_b32_e32 v203, 0xffff0000, v33
	v_mul_f32_e32 v140, v164, v196
	v_mul_f32_e32 v141, v165, v197
	v_mul_f32_e32 v142, v166, v198
	v_mul_f32_e32 v143, v167, v199
	v_mul_f32_e32 v144, v168, v200
	v_mul_f32_e32 v145, v169, v201
	v_mul_f32_e32 v146, v170, v202
	v_mul_f32_e32 v147, v171, v203
	v_fmac_f32_e32 v140, v172, v188
	v_fmac_f32_e32 v141, v173, v189
	v_fmac_f32_e32 v142, v174, v190
	v_fmac_f32_e32 v143, v175, v191
	v_fmac_f32_e32 v144, v176, v192
	v_fmac_f32_e32 v145, v177, v193
	v_fmac_f32_e32 v146, v178, v194
	v_fmac_f32_e32 v147, v179, v195
	v_fmac_f32_e32 v140, v180, v204
	v_fmac_f32_e32 v141, v181, v205
	v_fmac_f32_e32 v142, v182, v206
	v_fmac_f32_e32 v143, v183, v207
	v_fmac_f32_e32 v144, v184, v208
	v_fmac_f32_e32 v145, v185, v209
	v_fmac_f32_e32 v146, v186, v210
	v_fmac_f32_e32 v147, v187, v211
	v_lshlrev_b32_e32 v150, 16, v14
	v_and_b32_e32 v151, 0xffff0000, v14
	v_mul_f32_e32 v140, v150, v140
	v_mul_f32_e32 v141, v151, v141
	v_lshlrev_b32_e32 v150, 16, v15
	v_and_b32_e32 v151, 0xffff0000, v15
	v_mul_f32_e32 v142, v150, v142
	v_mul_f32_e32 v143, v151, v143
	v_lshlrev_b32_e32 v150, 16, v16
	v_and_b32_e32 v151, 0xffff0000, v16
	v_mul_f32_e32 v144, v150, v144
	v_mul_f32_e32 v145, v151, v145
	v_lshlrev_b32_e32 v150, 16, v17
	v_and_b32_e32 v151, 0xffff0000, v17
	v_mul_f32_e32 v146, v150, v146
	v_mul_f32_e32 v147, v151, v147
	v_mul_f32_e32 v148, v140, v140
	v_fmac_f32_e32 v148, v141, v141
	v_fmac_f32_e32 v148, v142, v142
	v_fmac_f32_e32 v148, v143, v143
	v_fmac_f32_e32 v148, v144, v144
	v_fmac_f32_e32 v148, v145, v145
	v_fmac_f32_e32 v148, v146, v146
	v_fmac_f32_e32 v148, v147, v147
	v_mad_i64_i32 v[152:153], vcc, s41, v221, v[58:59]
	s_add_u32 s41, s41, 1
	global_load_dwordx4 v[14:17], v[152:153], off offset:1536 nt
	global_load_dwordx4 v[30:33], v[152:153], off offset:2560 nt
	s_nop 1
	v_add_f32_dpp v148, v148, v148 quad_perm:[1,0,3,2] row_mask:0xf bank_mask:0xf
	s_nop 1
	v_add_f32_dpp v148, v148, v148 quad_perm:[2,3,0,1] row_mask:0xf bank_mask:0xf
	s_nop 1
	v_add_f32_dpp v148, v148, v148 row_half_mirror row_mask:0xf bank_mask:0xf
	s_nop 1
	v_add_f32_dpp v148, v148, v148 row_mirror row_mask:0xf bank_mask:0xf
	s_nop 1
	v_add_f32_dpp v148, v148, v148 row_bcast:15 row_mask:0xa bank_mask:0xf
	s_nop 1
	v_add_f32_dpp v148, v148, v148 row_bcast:31 row_mask:0xc bank_mask:0xf
	s_nop 0
	v_readlane_b32 s0, v148, 63
	s_nop 1
	v_mov_b32_e32 v148, s0
	v_fmamk_f32 v148, v148, 0x3b000000, v162
	v_mul_f32_e32 v150, 0x4b800000, v148
	v_cmp_gt_f32_e32 vcc, s31, v148
	s_nop 1
	v_cndmask_b32_e32 v148, v148, v150, vcc
	v_rsq_f32_e32 v148, v148
	s_nop 0
	v_mul_f32_e32 v150, 0x45800000, v148
	v_cndmask_b32_e32 v149, v148, v150, vcc
	v_mul_f32_e32 v140, v149, v140
	v_mul_f32_e32 v141, v149, v141
	v_mul_f32_e32 v142, v149, v142
	v_mul_f32_e32 v143, v149, v143
	v_mul_f32_e32 v144, v149, v144
	v_mul_f32_e32 v145, v149, v145
	v_mul_f32_e32 v146, v149, v146
	v_mul_f32_e32 v147, v149, v147
	v_cvt_pk_bf16_f32 v140, v140, v141
	v_cvt_pk_bf16_f32 v141, v142, v143
	v_cvt_pk_bf16_f32 v142, v144, v145
	v_cvt_pk_bf16_f32 v143, v146, v147
	global_store_dwordx4 v[156:157], v[140:143], off offset:2048 sc1
	v_lshl_add_u64 v[156:157], v[156:157], 0, s[20:21]
	s_waitcnt vmcnt(10)
	v_lshlrev_b32_e32 v204, 16, v18
	v_and_b32_e32 v205, 0xffff0000, v18
	v_lshlrev_b32_e32 v206, 16, v19
	v_and_b32_e32 v207, 0xffff0000, v19
	v_lshlrev_b32_e32 v208, 16, v20
	v_and_b32_e32 v209, 0xffff0000, v20
	v_lshlrev_b32_e32 v210, 16, v21
	v_and_b32_e32 v211, 0xffff0000, v21
	v_mul_f32_e32 v140, v164, v204
	v_mul_f32_e32 v141, v165, v205
	v_mul_f32_e32 v142, v166, v206
	v_mul_f32_e32 v143, v167, v207
	v_mul_f32_e32 v144, v168, v208
	v_mul_f32_e32 v145, v169, v209
	v_mul_f32_e32 v146, v170, v210
	v_mul_f32_e32 v147, v171, v211
	v_fmac_f32_e32 v140, v172, v196
	v_fmac_f32_e32 v141, v173, v197
	v_fmac_f32_e32 v142, v174, v198
	v_fmac_f32_e32 v143, v175, v199
	v_fmac_f32_e32 v144, v176, v200
	v_fmac_f32_e32 v145, v177, v201
	v_fmac_f32_e32 v146, v178, v202
	v_fmac_f32_e32 v147, v179, v203
	v_fmac_f32_e32 v140, v180, v188
	v_fmac_f32_e32 v141, v181, v189
	v_fmac_f32_e32 v142, v182, v190
	v_fmac_f32_e32 v143, v183, v191
	v_fmac_f32_e32 v144, v184, v192
	v_fmac_f32_e32 v145, v185, v193
	v_fmac_f32_e32 v146, v186, v194
	v_fmac_f32_e32 v147, v187, v195
	v_lshlrev_b32_e32 v150, 16, v2
	v_and_b32_e32 v151, 0xffff0000, v2
	v_mul_f32_e32 v140, v150, v140
	v_mul_f32_e32 v141, v151, v141
	v_lshlrev_b32_e32 v150, 16, v3
	v_and_b32_e32 v151, 0xffff0000, v3
	v_mul_f32_e32 v142, v150, v142
	v_mul_f32_e32 v143, v151, v143
	v_lshlrev_b32_e32 v150, 16, v4
	v_and_b32_e32 v151, 0xffff0000, v4
	v_mul_f32_e32 v144, v150, v144
	v_mul_f32_e32 v145, v151, v145
	v_lshlrev_b32_e32 v150, 16, v5
	v_and_b32_e32 v151, 0xffff0000, v5
	v_mul_f32_e32 v146, v150, v146
	v_mul_f32_e32 v147, v151, v147
	v_mul_f32_e32 v148, v140, v140
	v_fmac_f32_e32 v148, v141, v141
	v_fmac_f32_e32 v148, v142, v142
	v_fmac_f32_e32 v148, v143, v143
	v_fmac_f32_e32 v148, v144, v144
	v_fmac_f32_e32 v148, v145, v145
	v_fmac_f32_e32 v148, v146, v146
	v_fmac_f32_e32 v148, v147, v147
	v_mad_i64_i32 v[152:153], vcc, s41, v221, v[58:59]
	s_add_u32 s41, s41, 1
	global_load_dwordx4 v[2:5], v[152:153], off offset:1536 nt
	global_load_dwordx4 v[18:21], v[152:153], off offset:2560 nt
	s_nop 1
	v_add_f32_dpp v148, v148, v148 quad_perm:[1,0,3,2] row_mask:0xf bank_mask:0xf
	s_nop 1
	v_add_f32_dpp v148, v148, v148 quad_perm:[2,3,0,1] row_mask:0xf bank_mask:0xf
	s_nop 1
	v_add_f32_dpp v148, v148, v148 row_half_mirror row_mask:0xf bank_mask:0xf
	s_nop 1
	v_add_f32_dpp v148, v148, v148 row_mirror row_mask:0xf bank_mask:0xf
	s_nop 1
	v_add_f32_dpp v148, v148, v148 row_bcast:15 row_mask:0xa bank_mask:0xf
	s_nop 1
	v_add_f32_dpp v148, v148, v148 row_bcast:31 row_mask:0xc bank_mask:0xf
	s_nop 0
	v_readlane_b32 s0, v148, 63
	s_nop 1
	v_mov_b32_e32 v148, s0
	v_fmamk_f32 v148, v148, 0x3b000000, v162
	v_mul_f32_e32 v150, 0x4b800000, v148
	v_cmp_gt_f32_e32 vcc, s31, v148
	s_nop 1
	v_cndmask_b32_e32 v148, v148, v150, vcc
	v_rsq_f32_e32 v148, v148
	s_nop 0
	v_mul_f32_e32 v150, 0x45800000, v148
	v_cndmask_b32_e32 v149, v148, v150, vcc
	v_mul_f32_e32 v140, v149, v140
	v_mul_f32_e32 v141, v149, v141
	v_mul_f32_e32 v142, v149, v142
	v_mul_f32_e32 v143, v149, v143
	v_mul_f32_e32 v144, v149, v144
	v_mul_f32_e32 v145, v149, v145
	v_mul_f32_e32 v146, v149, v146
	v_mul_f32_e32 v147, v149, v147
	v_cvt_pk_bf16_f32 v140, v140, v141
	v_cvt_pk_bf16_f32 v141, v142, v143
	v_cvt_pk_bf16_f32 v142, v144, v145
	v_cvt_pk_bf16_f32 v143, v146, v147
	global_store_dwordx4 v[156:157], v[140:143], off sc1
	s_waitcnt vmcnt(10)
; __device__ __forceinline__ unsigned cvt_pk_bf16(float lo, float hi) { unsigned r; asm volatile("v_cvt_pk_bf16_f32 %0, %1, %2" : "=v"(r) : "v"(lo), "v"(hi)); return r; }
; __device__ __forceinline__ float bf_lo(unsigned w) { return __uint_as_float(w << 16); }
; __device__ __forceinline__ float bf_hi(unsigned w) { return __uint_as_float(w & 0xffff0000u); }
; __global__ void __launch_bounds__(512, 2) trunk_fwd(Args args) {
;     ...
;                 for (int rr = 0; rr < 16; ++rr) {
;                     const int r = r0 + rr;
;                     const u32x4 gb = gb_n, gu = gu_n; const f32x4 pv4 = pv_n;
;                     if (rr < 15) { gb_n = *(const u32x4*)(Z + (size_t)(r + 1) * INP + 768 + c0); gu_n = *(const u32x4*)(Z + (size_t)(r + 1) * INP + 1280 + c0);
;                                    pv_n = *(const f32x4*)(pl + (size_t)(r + 1) * PLE + lane * 4); }
;                     float cv[8], uu[8]; float ss = 0.f;
; #pragma unroll
;                     for (int i = 0; i < 4; ++i) {
;                         uu[2 * i] = bf_lo(gu[i]); uu[2 * i + 1] = bf_hi(gu[i]);
;                         cv[2 * i] = bf_lo(gb[i]) * (w0[2 * i] * uu[2 * i] + w1[2 * i] * u1[2 * i] + w2[2 * i] * u2[2 * i]);
;                         cv[2 * i + 1] = bf_hi(gb[i]) * (w0[2 * i + 1] * uu[2 * i + 1] + w1[2 * i + 1] * u1[2 * i + 1] + w2[2 * i + 1] * u2[2 * i + 1]);
;                     }
; #pragma unroll
;                     for (int i = 0; i < 8; ++i) { ss += cv[i] * cv[i]; u2[i] = u1[i]; u1[i] = uu[i]; }
;                     ss = wave_sum(ss);
;                     const float rc = rsqrtf(ss * (1.0f / 512.0f) + EPS);
;                     u32x4 oc;
; #pragma unroll
;                     for (int i = 0; i < 4; ++i) oc[i] = cvt_pk_bf16(cv[2 * i] * rc, cv[2 * i + 1] * rc);
;                     *(u32x4*)(MIX + (size_t)r * 1024 + 512 + c0) = oc;
;                     u32x2 pw; pw.x = cvt_pk_bf16(pv4[0], pv4[1]); pw.y = cvt_pk_bf16(pv4[2], pv4[3]);
;                     *(u32x2*)(PB + (size_t)r * PLE + lane * 4) = pw;
	v_lshlrev_b32_e32 v188, 16, v22
	v_and_b32_e32 v189, 0xffff0000, v22
	v_lshlrev_b32_e32 v190, 16, v23
	v_and_b32_e32 v191, 0xffff0000, v23
	v_lshlrev_b32_e32 v192, 16, v24
	v_and_b32_e32 v193, 0xffff0000, v24
	v_lshlrev_b32_e32 v194, 16, v25
	v_and_b32_e32 v195, 0xffff0000, v25
	v_mul_f32_e32 v140, v164, v188
	v_mul_f32_e32 v141, v165, v189
	v_mul_f32_e32 v142, v166, v190
	v_mul_f32_e32 v143, v167, v191
	v_mul_f32_e32 v144, v168, v192
	v_mul_f32_e32 v145, v169, v193
	v_mul_f32_e32 v146, v170, v194
	v_mul_f32_e32 v147, v171, v195
	v_fmac_f32_e32 v140, v172, v204
	v_fmac_f32_e32 v141, v173, v205
	v_fmac_f32_e32 v142, v174, v206
	v_fmac_f32_e32 v143, v175, v207
	v_fmac_f32_e32 v144, v176, v208
	v_fmac_f32_e32 v145, v177, v209
	v_fmac_f32_e32 v146, v178, v210
	v_fmac_f32_e32 v147, v179, v211
	v_fmac_f32_e32 v140, v180, v196
	v_fmac_f32_e32 v141, v181, v197
	v_fmac_f32_e32 v142, v182, v198
	v_fmac_f32_e32 v143, v183, v199
	v_fmac_f32_e32 v144, v184, v200
	v_fmac_f32_e32 v145, v185, v201
	v_fmac_f32_e32 v146, v186, v202
	v_fmac_f32_e32 v147, v187, v203
	v_lshlrev_b32_e32 v150, 16, v6
	v_and_b32_e32 v151, 0xffff0000, v6
	v_mul_f32_e32 v140, v150, v140
	v_mul_f32_e32 v141, v151, v141
	v_lshlrev_b32_e32 v150, 16, v7
	v_and_b32_e32 v151, 0xffff0000, v7
	v_mul_f32_e32 v142, v150, v142
	v_mul_f32_e32 v143, v151, v143
	v_lshlrev_b32_e32 v150, 16, v8
	v_and_b32_e32 v151, 0xffff0000, v8
	v_mul_f32_e32 v144, v150, v144
	v_mul_f32_e32 v145, v151, v145
	v_lshlrev_b32_e32 v150, 16, v9
	v_and_b32_e32 v151, 0xffff0000, v9
	v_mul_f32_e32 v146, v150, v146
	v_mul_f32_e32 v147, v151, v147
	v_mul_f32_e32 v148, v140, v140
	v_fmac_f32_e32 v148, v141, v141
	v_fmac_f32_e32 v148, v142, v142
	v_fmac_f32_e32 v148, v143, v143
	v_fmac_f32_e32 v148, v144, v144
	v_fmac_f32_e32 v148, v145, v145
	v_fmac_f32_e32 v148, v146, v146
	v_fmac_f32_e32 v148, v147, v147
	v_mad_i64_i32 v[152:153], vcc, s41, v221, v[58:59]
	s_add_u32 s41, s41, 1
	global_load_dwordx4 v[6:9], v[152:153], off offset:1536 nt
	global_load_dwordx4 v[22:25], v[152:153], off offset:2560 nt
	s_nop 1
	v_add_f32_dpp v148, v148, v148 quad_perm:[1,0,3,2] row_mask:0xf bank_mask:0xf
	s_nop 1
	v_add_f32_dpp v148, v148, v148 quad_perm:[2,3,0,1] row_mask:0xf bank_mask:0xf
	s_nop 1
	v_add_f32_dpp v148, v148, v148 row_half_mirror row_mask:0xf bank_mask:0xf
	s_nop 1
	v_add_f32_dpp v148, v148, v148 row_mirror row_mask:0xf bank_mask:0xf
	s_nop 1
	v_add_f32_dpp v148, v148, v148 row_bcast:15 row_mask:0xa bank_mask:0xf
	s_nop 1
	v_add_f32_dpp v148, v148, v148 row_bcast:31 row_mask:0xc bank_mask:0xf
	s_nop 0
	v_readlane_b32 s0, v148, 63
	s_nop 1
	v_mov_b32_e32 v148, s0
	v_fmamk_f32 v148, v148, 0x3b000000, v162
	v_mul_f32_e32 v150, 0x4b800000, v148
	v_cmp_gt_f32_e32 vcc, s31, v148
	s_nop 1
	v_cndmask_b32_e32 v148, v148, v150, vcc
	v_rsq_f32_e32 v148, v148
	s_nop 0
	v_mul_f32_e32 v150, 0x45800000, v148
	v_cndmask_b32_e32 v149, v148, v150, vcc
	v_mul_f32_e32 v140, v149, v140
	v_mul_f32_e32 v141, v149, v141
	v_mul_f32_e32 v142, v149, v142
	v_mul_f32_e32 v143, v149, v143
	v_mul_f32_e32 v144, v149, v144
	v_mul_f32_e32 v145, v149, v145
	v_mul_f32_e32 v146, v149, v146
	v_mul_f32_e32 v147, v149, v147
	v_cvt_pk_bf16_f32 v140, v140, v141
	v_cvt_pk_bf16_f32 v141, v142, v143
	v_cvt_pk_bf16_f32 v142, v144, v145
	v_cvt_pk_bf16_f32 v143, v146, v147
	global_store_dwordx4 v[156:157], v[140:143], off offset:2048 sc1
	v_lshl_add_u64 v[156:157], v[156:157], 0, s[20:21]
	s_waitcnt vmcnt(10)
	v_lshlrev_b32_e32 v196, 16, v26
	v_and_b32_e32 v197, 0xffff0000, v26
	v_lshlrev_b32_e32 v198, 16, v27
	v_and_b32_e32 v199, 0xffff0000, v27
	v_lshlrev_b32_e32 v200, 16, v28
	v_and_b32_e32 v201, 0xffff0000, v28
	v_lshlrev_b32_e32 v202, 16, v29
	v_and_b32_e32 v203, 0xffff0000, v29
	v_mul_f32_e32 v140, v164, v196
	v_mul_f32_e32 v141, v165, v197
	v_mul_f32_e32 v142, v166, v198
	v_mul_f32_e32 v143, v167, v199
	v_mul_f32_e32 v144, v168, v200
	v_mul_f32_e32 v145, v169, v201
	v_mul_f32_e32 v146, v170, v202
	v_mul_f32_e32 v147, v171, v203
	v_fmac_f32_e32 v140, v172, v188
	v_fmac_f32_e32 v141, v173, v189
	v_fmac_f32_e32 v142, v174, v190
	v_fmac_f32_e32 v143, v175, v191
	v_fmac_f32_e32 v144, v176, v192
	v_fmac_f32_e32 v145, v177, v193
	v_fmac_f32_e32 v146, v178, v194
	v_fmac_f32_e32 v147, v179, v195
	v_fmac_f32_e32 v140, v180, v204
	v_fmac_f32_e32 v141, v181, v205
	v_fmac_f32_e32 v142, v182, v206
	v_fmac_f32_e32 v143, v183, v207
	v_fmac_f32_e32 v144, v184, v208
	v_fmac_f32_e32 v145, v185, v209
	v_fmac_f32_e32 v146, v186, v210
	v_fmac_f32_e32 v147, v187, v211
	v_lshlrev_b32_e32 v150, 16, v10
	v_and_b32_e32 v151, 0xffff0000, v10
	v_mul_f32_e32 v140, v150, v140
	v_mul_f32_e32 v141, v151, v141
	v_lshlrev_b32_e32 v150, 16, v11
	v_and_b32_e32 v151, 0xffff0000, v11
	v_mul_f32_e32 v142, v150, v142
	v_mul_f32_e32 v143, v151, v143
	v_lshlrev_b32_e32 v150, 16, v12
	v_and_b32_e32 v151, 0xffff0000, v12
	v_mul_f32_e32 v144, v150, v144
	v_mul_f32_e32 v145, v151, v145
	v_lshlrev_b32_e32 v150, 16, v13
	v_and_b32_e32 v151, 0xffff0000, v13
	v_mul_f32_e32 v146, v150, v146
	v_mul_f32_e32 v147, v151, v147
	v_mul_f32_e32 v148, v140, v140
	v_fmac_f32_e32 v148, v141, v141
	v_fmac_f32_e32 v148, v142, v142
	v_fmac_f32_e32 v148, v143, v143
	v_fmac_f32_e32 v148, v144, v144
	v_fmac_f32_e32 v148, v145, v145
	v_fmac_f32_e32 v148, v146, v146
	v_fmac_f32_e32 v148, v147, v147
	v_mad_i64_i32 v[152:153], vcc, s41, v221, v[58:59]
	s_add_u32 s41, s41, 1
	global_load_dwordx4 v[10:13], v[152:153], off offset:1536 nt
	global_load_dwordx4 v[26:29], v[152:153], off offset:2560 nt
	s_nop 1
	v_add_f32_dpp v148, v148, v148 quad_perm:[1,0,3,2] row_mask:0xf bank_mask:0xf
	s_nop 1
	v_add_f32_dpp v148, v148, v148 quad_perm:[2,3,0,1] row_mask:0xf bank_mask:0xf
	s_nop 1
	v_add_f32_dpp v148, v148, v148 row_half_mirror row_mask:0xf bank_mask:0xf
	s_nop 1
	v_add_f32_dpp v148, v148, v148 row_mirror row_mask:0xf bank_mask:0xf
	s_nop 1
	v_add_f32_dpp v148, v148, v148 row_bcast:15 row_mask:0xa bank_mask:0xf
	s_nop 1
	v_add_f32_dpp v148, v148, v148 row_bcast:31 row_mask:0xc bank_mask:0xf
	s_nop 0
	v_readlane_b32 s0, v148, 63
	s_nop 1
	v_mov_b32_e32 v148, s0
	v_fmamk_f32 v148, v148, 0x3b000000, v162
	v_mul_f32_e32 v150, 0x4b800000, v148
	v_cmp_gt_f32_e32 vcc, s31, v148
	s_nop 1
	v_cndmask_b32_e32 v148, v148, v150, vcc
	v_rsq_f32_e32 v148, v148
	s_nop 0
	v_mul_f32_e32 v150, 0x45800000, v148
	v_cndmask_b32_e32 v149, v148, v150, vcc
	v_mul_f32_e32 v140, v149, v140
	v_mul_f32_e32 v141, v149, v141
	v_mul_f32_e32 v142, v149, v142
	v_mul_f32_e32 v143, v149, v143
	v_mul_f32_e32 v144, v149, v144
	v_mul_f32_e32 v145, v149, v145
	v_mul_f32_e32 v146, v149, v146
	v_mul_f32_e32 v147, v149, v147
	v_cvt_pk_bf16_f32 v140, v140, v141
	v_cvt_pk_bf16_f32 v141, v142, v143
	v_cvt_pk_bf16_f32 v142, v144, v145
	v_cvt_pk_bf16_f32 v143, v146, v147
	global_store_dwordx4 v[156:157], v[140:143], off sc1
	s_waitcnt vmcnt(10)
; __device__ __forceinline__ unsigned cvt_pk_bf16(float lo, float hi) { unsigned r; asm volatile("v_cvt_pk_bf16_f32 %0, %1, %2" : "=v"(r) : "v"(lo), "v"(hi)); return r; }
; __device__ __forceinline__ float bf_lo(unsigned w) { return __uint_as_float(w << 16); }
; __device__ __forceinline__ float bf_hi(unsigned w) { return __uint_as_float(w & 0xffff0000u); }
; __global__ void __launch_bounds__(512, 2) trunk_fwd(Args args) {
;     ...
;                 for (int rr = 0; rr < 16; ++rr) {
;                     const int r = r0 + rr;
;                     const u32x4 gb = gb_n, gu = gu_n; const f32x4 pv4 = pv_n;
;                     if (rr < 15) { gb_n = *(const u32x4*)(Z + (size_t)(r + 1) * INP + 768 + c0); gu_n = *(const u32x4*)(Z + (size_t)(r + 1) * INP + 1280 + c0);
;                                    pv_n = *(const f32x4*)(pl + (size_t)(r + 1) * PLE + lane * 4); }
;                     float cv[8], uu[8]; float ss = 0.f;
; #pragma unroll
;                     for (int i = 0; i < 4; ++i) {
;                         uu[2 * i] = bf_lo(gu[i]); uu[2 * i + 1] = bf_hi(gu[i]);
;                         cv[2 * i] = bf_lo(gb[i]) * (w0[2 * i] * uu[2 * i] + w1[2 * i] * u1[2 * i] + w2[2 * i] * u2[2 * i]);
;                         cv[2 * i + 1] = bf_hi(gb[i]) * (w0[2 * i + 1] * uu[2 * i + 1] + w1[2 * i + 1] * u1[2 * i + 1] + w2[2 * i + 1] * u2[2 * i + 1]);
;                     }
; #pragma unroll
;                     for (int i = 0; i < 8; ++i) { ss += cv[i] * cv[i]; u2[i] = u1[i]; u1[i] = uu[i]; }
;                     ss = wave_sum(ss);
;                     const float rc = rsqrtf(ss * (1.0f / 512.0f) + EPS);
;                     u32x4 oc;
; #pragma unroll
;                     for (int i = 0; i < 4; ++i) oc[i] = cvt_pk_bf16(cv[2 * i] * rc, cv[2 * i + 1] * rc);
;                     *(u32x4*)(MIX + (size_t)r * 1024 + 512 + c0) = oc;
;                     u32x2 pw; pw.x = cvt_pk_bf16(pv4[0], pv4[1]); pw.y = cvt_pk_bf16(pv4[2], pv4[3]);
;                     *(u32x2*)(PB + (size_t)r * PLE + lane * 4) = pw;
	v_lshlrev_b32_e32 v204, 16, v30
	v_and_b32_e32 v205, 0xffff0000, v30
	v_lshlrev_b32_e32 v206, 16, v31
	v_and_b32_e32 v207, 0xffff0000, v31
	v_lshlrev_b32_e32 v208, 16, v32
	v_and_b32_e32 v209, 0xffff0000, v32
	v_lshlrev_b32_e32 v210, 16, v33
	v_and_b32_e32 v211, 0xffff0000, v33
	v_mul_f32_e32 v140, v164, v204
	v_mul_f32_e32 v141, v165, v205
	v_mul_f32_e32 v142, v166, v206
	v_mul_f32_e32 v143, v167, v207
	v_mul_f32_e32 v144, v168, v208
	v_mul_f32_e32 v145, v169, v209
	v_mul_f32_e32 v146, v170, v210
	v_mul_f32_e32 v147, v171, v211
	v_fmac_f32_e32 v140, v172, v196
	v_fmac_f32_e32 v141, v173, v197
	v_fmac_f32_e32 v142, v174, v198
	v_fmac_f32_e32 v143, v175, v199
	v_fmac_f32_e32 v144, v176, v200
	v_fmac_f32_e32 v145, v177, v201
	v_fmac_f32_e32 v146, v178, v202
	v_fmac_f32_e32 v147, v179, v203
	v_fmac_f32_e32 v140, v180, v188
	v_fmac_f32_e32 v141, v181, v189
	v_fmac_f32_e32 v142, v182, v190
	v_fmac_f32_e32 v143, v183, v191
	v_fmac_f32_e32 v144, v184, v192
	v_fmac_f32_e32 v145, v185, v193
	v_fmac_f32_e32 v146, v186, v194
	v_fmac_f32_e32 v147, v187, v195
	v_lshlrev_b32_e32 v150, 16, v14
	v_and_b32_e32 v151, 0xffff0000, v14
	v_mul_f32_e32 v140, v150, v140
	v_mul_f32_e32 v141, v151, v141
	v_lshlrev_b32_e32 v150, 16, v15
	v_and_b32_e32 v151, 0xffff0000, v15
	v_mul_f32_e32 v142, v150, v142
	v_mul_f32_e32 v143, v151, v143
	v_lshlrev_b32_e32 v150, 16, v16
	v_and_b32_e32 v151, 0xffff0000, v16
	v_mul_f32_e32 v144, v150, v144
	v_mul_f32_e32 v145, v151, v145
	v_lshlrev_b32_e32 v150, 16, v17
	v_and_b32_e32 v151, 0xffff0000, v17
	v_mul_f32_e32 v146, v150, v146
	v_mul_f32_e32 v147, v151, v147
	v_mul_f32_e32 v148, v140, v140
	v_fmac_f32_e32 v148, v141, v141
	v_fmac_f32_e32 v148, v142, v142
	v_fmac_f32_e32 v148, v143, v143
	v_fmac_f32_e32 v148, v144, v144
	v_fmac_f32_e32 v148, v145, v145
	v_fmac_f32_e32 v148, v146, v146
	v_fmac_f32_e32 v148, v147, v147
	v_mad_i64_i32 v[152:153], vcc, s41, v221, v[58:59]
	s_add_u32 s41, s41, 1
	global_load_dwordx4 v[14:17], v[152:153], off offset:1536 nt
	global_load_dwordx4 v[30:33], v[152:153], off offset:2560 nt
	s_nop 1
	v_add_f32_dpp v148, v148, v148 quad_perm:[1,0,3,2] row_mask:0xf bank_mask:0xf
	s_nop 1
	v_add_f32_dpp v148, v148, v148 quad_perm:[2,3,0,1] row_mask:0xf bank_mask:0xf
	s_nop 1
	v_add_f32_dpp v148, v148, v148 row_half_mirror row_mask:0xf bank_mask:0xf
	s_nop 1
	v_add_f32_dpp v148, v148, v148 row_mirror row_mask:0xf bank_mask:0xf
	s_nop 1
	v_add_f32_dpp v148, v148, v148 row_bcast:15 row_mask:0xa bank_mask:0xf
	s_nop 1
	v_add_f32_dpp v148, v148, v148 row_bcast:31 row_mask:0xc bank_mask:0xf
	s_nop 0
	v_readlane_b32 s0, v148, 63
	s_nop 1
	v_mov_b32_e32 v148, s0
	v_fmamk_f32 v148, v148, 0x3b000000, v162
	v_mul_f32_e32 v150, 0x4b800000, v148
	v_cmp_gt_f32_e32 vcc, s31, v148
	s_nop 1
	v_cndmask_b32_e32 v148, v148, v150, vcc
	v_rsq_f32_e32 v148, v148
	s_nop 0
	v_mul_f32_e32 v150, 0x45800000, v148
	v_cndmask_b32_e32 v149, v148, v150, vcc
	v_mul_f32_e32 v140, v149, v140
	v_mul_f32_e32 v141, v149, v141
	v_mul_f32_e32 v142, v149, v142
	v_mul_f32_e32 v143, v149, v143
	v_mul_f32_e32 v144, v149, v144
	v_mul_f32_e32 v145, v149, v145
	v_mul_f32_e32 v146, v149, v146
	v_mul_f32_e32 v147, v149, v147
	v_cvt_pk_bf16_f32 v140, v140, v141
	v_cvt_pk_bf16_f32 v141, v142, v143
	v_cvt_pk_bf16_f32 v142, v144, v145
	v_cvt_pk_bf16_f32 v143, v146, v147
	global_store_dwordx4 v[156:157], v[140:143], off offset:2048 sc1
	v_lshl_add_u64 v[156:157], v[156:157], 0, s[20:21]
	s_waitcnt vmcnt(10)
	v_lshlrev_b32_e32 v188, 16, v18
	v_and_b32_e32 v189, 0xffff0000, v18
	v_lshlrev_b32_e32 v190, 16, v19
	v_and_b32_e32 v191, 0xffff0000, v19
	v_lshlrev_b32_e32 v192, 16, v20
	v_and_b32_e32 v193, 0xffff0000, v20
	v_lshlrev_b32_e32 v194, 16, v21
	v_and_b32_e32 v195, 0xffff0000, v21
	v_mul_f32_e32 v140, v164, v188
	v_mul_f32_e32 v141, v165, v189
	v_mul_f32_e32 v142, v166, v190
	v_mul_f32_e32 v143, v167, v191
	v_mul_f32_e32 v144, v168, v192
	v_mul_f32_e32 v145, v169, v193
	v_mul_f32_e32 v146, v170, v194
	v_mul_f32_e32 v147, v171, v195
	v_fmac_f32_e32 v140, v172, v204
	v_fmac_f32_e32 v141, v173, v205
	v_fmac_f32_e32 v142, v174, v206
	v_fmac_f32_e32 v143, v175, v207
	v_fmac_f32_e32 v144, v176, v208
	v_fmac_f32_e32 v145, v177, v209
	v_fmac_f32_e32 v146, v178, v210
	v_fmac_f32_e32 v147, v179, v211
	v_fmac_f32_e32 v140, v180, v196
	v_fmac_f32_e32 v141, v181, v197
	v_fmac_f32_e32 v142, v182, v198
	v_fmac_f32_e32 v143, v183, v199
	v_fmac_f32_e32 v144, v184, v200
	v_fmac_f32_e32 v145, v185, v201
	v_fmac_f32_e32 v146, v186, v202
	v_fmac_f32_e32 v147, v187, v203
	v_lshlrev_b32_e32 v150, 16, v2
	v_and_b32_e32 v151, 0xffff0000, v2
	v_mul_f32_e32 v140, v150, v140
	v_mul_f32_e32 v141, v151, v141
	v_lshlrev_b32_e32 v150, 16, v3
	v_and_b32_e32 v151, 0xffff0000, v3
	v_mul_f32_e32 v142, v150, v142
	v_mul_f32_e32 v143, v151, v143
	v_lshlrev_b32_e32 v150, 16, v4
	v_and_b32_e32 v151, 0xffff0000, v4
	v_mul_f32_e32 v144, v150, v144
	v_mul_f32_e32 v145, v151, v145
	v_lshlrev_b32_e32 v150, 16, v5
	v_and_b32_e32 v151, 0xffff0000, v5
	v_mul_f32_e32 v146, v150, v146
	v_mul_f32_e32 v147, v151, v147
	v_mul_f32_e32 v148, v140, v140
	v_fmac_f32_e32 v148, v141, v141
	v_fmac_f32_e32 v148, v142, v142
	v_fmac_f32_e32 v148, v143, v143
	v_fmac_f32_e32 v148, v144, v144
	v_fmac_f32_e32 v148, v145, v145
	v_fmac_f32_e32 v148, v146, v146
	v_fmac_f32_e32 v148, v147, v147
	s_nop 1
	v_add_f32_dpp v148, v148, v148 quad_perm:[1,0,3,2] row_mask:0xf bank_mask:0xf
	s_nop 1
	v_add_f32_dpp v148, v148, v148 quad_perm:[2,3,0,1] row_mask:0xf bank_mask:0xf
	s_nop 1
	v_add_f32_dpp v148, v148, v148 row_half_mirror row_mask:0xf bank_mask:0xf
	s_nop 1
	v_add_f32_dpp v148, v148, v148 row_mirror row_mask:0xf bank_mask:0xf
	s_nop 1
	v_add_f32_dpp v148, v148, v148 row_bcast:15 row_mask:0xa bank_mask:0xf
	s_nop 1
	v_add_f32_dpp v148, v148, v148 row_bcast:31 row_mask:0xc bank_mask:0xf
	s_nop 0
	v_readlane_b32 s0, v148, 63
	s_nop 1
	v_mov_b32_e32 v148, s0
	v_fmamk_f32 v148, v148, 0x3b000000, v162
	v_mul_f32_e32 v150, 0x4b800000, v148
	v_cmp_gt_f32_e32 vcc, s31, v148
	s_nop 1
	v_cndmask_b32_e32 v148, v148, v150, vcc
	v_rsq_f32_e32 v148, v148
	s_nop 0
	v_mul_f32_e32 v150, 0x45800000, v148
	v_cndmask_b32_e32 v149, v148, v150, vcc
	v_mul_f32_e32 v140, v149, v140
	v_mul_f32_e32 v141, v149, v141
	v_mul_f32_e32 v142, v149, v142
	v_mul_f32_e32 v143, v149, v143
	v_mul_f32_e32 v144, v149, v144
	v_mul_f32_e32 v145, v149, v145
	v_mul_f32_e32 v146, v149, v146
	v_mul_f32_e32 v147, v149, v147
	v_cvt_pk_bf16_f32 v140, v140, v141
	v_cvt_pk_bf16_f32 v141, v142, v143
	v_cvt_pk_bf16_f32 v142, v144, v145
	v_cvt_pk_bf16_f32 v143, v146, v147
	global_store_dwordx4 v[156:157], v[140:143], off sc1
	s_waitcnt vmcnt(8)
; __device__ __forceinline__ unsigned cvt_pk_bf16(float lo, float hi) { unsigned r; asm volatile("v_cvt_pk_bf16_f32 %0, %1, %2" : "=v"(r) : "v"(lo), "v"(hi)); return r; }
; __device__ __forceinline__ float bf_lo(unsigned w) { return __uint_as_float(w << 16); }
; __device__ __forceinline__ float bf_hi(unsigned w) { return __uint_as_float(w & 0xffff0000u); }
; __global__ void __launch_bounds__(512, 2) trunk_fwd(Args args) {
;     ...
;                 for (int rr = 0; rr < 16; ++rr) {
;                     const int r = r0 + rr;
;                     const u32x4 gb = gb_n, gu = gu_n; const f32x4 pv4 = pv_n;
;                     if (rr < 15) { gb_n = *(const u32x4*)(Z + (size_t)(r + 1) * INP + 768 + c0); gu_n = *(const u32x4*)(Z + (size_t)(r + 1) * INP + 1280 + c0);
;                                    pv_n = *(const f32x4*)(pl + (size_t)(r + 1) * PLE + lane * 4); }
;                     float cv[8], uu[8]; float ss = 0.f;
; #pragma unroll
;                     for (int i = 0; i < 4; ++i) {
;                         uu[2 * i] = bf_lo(gu[i]); uu[2 * i + 1] = bf_hi(gu[i]);
;                         cv[2 * i] = bf_lo(gb[i]) * (w0[2 * i] * uu[2 * i] + w1[2 * i] * u1[2 * i] + w2[2 * i] * u2[2 * i]);
;                         cv[2 * i + 1] = bf_hi(gb[i]) * (w0[2 * i + 1] * uu[2 * i + 1] + w1[2 * i + 1] * u1[2 * i + 1] + w2[2 * i + 1] * u2[2 * i + 1]);
;                     }
; #pragma unroll
;                     for (int i = 0; i < 8; ++i) { ss += cv[i] * cv[i]; u2[i] = u1[i]; u1[i] = uu[i]; }
;                     ss = wave_sum(ss);
;                     const float rc = rsqrtf(ss * (1.0f / 512.0f) + EPS);
;                     u32x4 oc;
; #pragma unroll
;                     for (int i = 0; i < 4; ++i) oc[i] = cvt_pk_bf16(cv[2 * i] * rc, cv[2 * i + 1] * rc);
;                     *(u32x4*)(MIX + (size_t)r * 1024 + 512 + c0) = oc;
;                     u32x2 pw; pw.x = cvt_pk_bf16(pv4[0], pv4[1]); pw.y = cvt_pk_bf16(pv4[2], pv4[3]);
;                     *(u32x2*)(PB + (size_t)r * PLE + lane * 4) = pw;
	v_lshlrev_b32_e32 v196, 16, v22
	v_and_b32_e32 v197, 0xffff0000, v22
	v_lshlrev_b32_e32 v198, 16, v23
	v_and_b32_e32 v199, 0xffff0000, v23
	v_lshlrev_b32_e32 v200, 16, v24
	v_and_b32_e32 v201, 0xffff0000, v24
	v_lshlrev_b32_e32 v202, 16, v25
	v_and_b32_e32 v203, 0xffff0000, v25
	v_mul_f32_e32 v140, v164, v196
	v_mul_f32_e32 v141, v165, v197
	v_mul_f32_e32 v142, v166, v198
	v_mul_f32_e32 v143, v167, v199
	v_mul_f32_e32 v144, v168, v200
	v_mul_f32_e32 v145, v169, v201
	v_mul_f32_e32 v146, v170, v202
	v_mul_f32_e32 v147, v171, v203
	v_fmac_f32_e32 v140, v172, v188
	v_fmac_f32_e32 v141, v173, v189
	v_fmac_f32_e32 v142, v174, v190
	v_fmac_f32_e32 v143, v175, v191
	v_fmac_f32_e32 v144, v176, v192
	v_fmac_f32_e32 v145, v177, v193
	v_fmac_f32_e32 v146, v178, v194
	v_fmac_f32_e32 v147, v179, v195
	v_fmac_f32_e32 v140, v180, v204
	v_fmac_f32_e32 v141, v181, v205
	v_fmac_f32_e32 v142, v182, v206
	v_fmac_f32_e32 v143, v183, v207
	v_fmac_f32_e32 v144, v184, v208
	v_fmac_f32_e32 v145, v185, v209
	v_fmac_f32_e32 v146, v186, v210
	v_fmac_f32_e32 v147, v187, v211
	v_lshlrev_b32_e32 v150, 16, v6
	v_and_b32_e32 v151, 0xffff0000, v6
	v_mul_f32_e32 v140, v150, v140
	v_mul_f32_e32 v141, v151, v141
	v_lshlrev_b32_e32 v150, 16, v7
	v_and_b32_e32 v151, 0xffff0000, v7
	v_mul_f32_e32 v142, v150, v142
	v_mul_f32_e32 v143, v151, v143
	v_lshlrev_b32_e32 v150, 16, v8
	v_and_b32_e32 v151, 0xffff0000, v8
	v_mul_f32_e32 v144, v150, v144
	v_mul_f32_e32 v145, v151, v145
	v_lshlrev_b32_e32 v150, 16, v9
	v_and_b32_e32 v151, 0xffff0000, v9
	v_mul_f32_e32 v146, v150, v146
	v_mul_f32_e32 v147, v151, v147
	v_mul_f32_e32 v148, v140, v140
	v_fmac_f32_e32 v148, v141, v141
	v_fmac_f32_e32 v148, v142, v142
	v_fmac_f32_e32 v148, v143, v143
	v_fmac_f32_e32 v148, v144, v144
	v_fmac_f32_e32 v148, v145, v145
	v_fmac_f32_e32 v148, v146, v146
	v_fmac_f32_e32 v148, v147, v147
	s_nop 1
	v_add_f32_dpp v148, v148, v148 quad_perm:[1,0,3,2] row_mask:0xf bank_mask:0xf
	s_nop 1
	v_add_f32_dpp v148, v148, v148 quad_perm:[2,3,0,1] row_mask:0xf bank_mask:0xf
	s_nop 1
	v_add_f32_dpp v148, v148, v148 row_half_mirror row_mask:0xf bank_mask:0xf
	s_nop 1
	v_add_f32_dpp v148, v148, v148 row_mirror row_mask:0xf bank_mask:0xf
	s_nop 1
	v_add_f32_dpp v148, v148, v148 row_bcast:15 row_mask:0xa bank_mask:0xf
	s_nop 1
	v_add_f32_dpp v148, v148, v148 row_bcast:31 row_mask:0xc bank_mask:0xf
	s_nop 0
	v_readlane_b32 s0, v148, 63
	s_nop 1
	v_mov_b32_e32 v148, s0
	v_fmamk_f32 v148, v148, 0x3b000000, v162
	v_mul_f32_e32 v150, 0x4b800000, v148
	v_cmp_gt_f32_e32 vcc, s31, v148
	s_nop 1
	v_cndmask_b32_e32 v148, v148, v150, vcc
	v_rsq_f32_e32 v148, v148
	s_nop 0
	v_mul_f32_e32 v150, 0x45800000, v148
	v_cndmask_b32_e32 v149, v148, v150, vcc
	v_mul_f32_e32 v140, v149, v140
	v_mul_f32_e32 v141, v149, v141
	v_mul_f32_e32 v142, v149, v142
	v_mul_f32_e32 v143, v149, v143
	v_mul_f32_e32 v144, v149, v144
	v_mul_f32_e32 v145, v149, v145
	v_mul_f32_e32 v146, v149, v146
	v_mul_f32_e32 v147, v149, v147
	v_cvt_pk_bf16_f32 v140, v140, v141
	v_cvt_pk_bf16_f32 v141, v142, v143
	v_cvt_pk_bf16_f32 v142, v144, v145
	v_cvt_pk_bf16_f32 v143, v146, v147
	global_store_dwordx4 v[156:157], v[140:143], off offset:2048 sc1
	v_lshl_add_u64 v[156:157], v[156:157], 0, s[20:21]
	s_waitcnt vmcnt(6)
	v_lshlrev_b32_e32 v204, 16, v26
	v_and_b32_e32 v205, 0xffff0000, v26
	v_lshlrev_b32_e32 v206, 16, v27
	v_and_b32_e32 v207, 0xffff0000, v27
	v_lshlrev_b32_e32 v208, 16, v28
	v_and_b32_e32 v209, 0xffff0000, v28
	v_lshlrev_b32_e32 v210, 16, v29
	v_and_b32_e32 v211, 0xffff0000, v29
	v_mul_f32_e32 v140, v164, v204
	v_mul_f32_e32 v141, v165, v205
	v_mul_f32_e32 v142, v166, v206
	v_mul_f32_e32 v143, v167, v207
	v_mul_f32_e32 v144, v168, v208
	v_mul_f32_e32 v145, v169, v209
	v_mul_f32_e32 v146, v170, v210
	v_mul_f32_e32 v147, v171, v211
	v_fmac_f32_e32 v140, v172, v196
	v_fmac_f32_e32 v141, v173, v197
	v_fmac_f32_e32 v142, v174, v198
	v_fmac_f32_e32 v143, v175, v199
	v_fmac_f32_e32 v144, v176, v200
	v_fmac_f32_e32 v145, v177, v201
	v_fmac_f32_e32 v146, v178, v202
	v_fmac_f32_e32 v147, v179, v203
	v_fmac_f32_e32 v140, v180, v188
	v_fmac_f32_e32 v141, v181, v189
	v_fmac_f32_e32 v142, v182, v190
	v_fmac_f32_e32 v143, v183, v191
	v_fmac_f32_e32 v144, v184, v192
	v_fmac_f32_e32 v145, v185, v193
	v_fmac_f32_e32 v146, v186, v194
	v_fmac_f32_e32 v147, v187, v195
	v_lshlrev_b32_e32 v150, 16, v10
	v_and_b32_e32 v151, 0xffff0000, v10
	v_mul_f32_e32 v140, v150, v140
	v_mul_f32_e32 v141, v151, v141
	v_lshlrev_b32_e32 v150, 16, v11
	v_and_b32_e32 v151, 0xffff0000, v11
	v_mul_f32_e32 v142, v150, v142
	v_mul_f32_e32 v143, v151, v143
	v_lshlrev_b32_e32 v150, 16, v12
	v_and_b32_e32 v151, 0xffff0000, v12
	v_mul_f32_e32 v144, v150, v144
	v_mul_f32_e32 v145, v151, v145
	v_lshlrev_b32_e32 v150, 16, v13
	v_and_b32_e32 v151, 0xffff0000, v13
	v_mul_f32_e32 v146, v150, v146
	v_mul_f32_e32 v147, v151, v147
	v_mul_f32_e32 v148, v140, v140
	v_fmac_f32_e32 v148, v141, v141
	v_fmac_f32_e32 v148, v142, v142
	v_fmac_f32_e32 v148, v143, v143
	v_fmac_f32_e32 v148, v144, v144
	v_fmac_f32_e32 v148, v145, v145
	v_fmac_f32_e32 v148, v146, v146
	v_fmac_f32_e32 v148, v147, v147
	s_nop 1
	v_add_f32_dpp v148, v148, v148 quad_perm:[1,0,3,2] row_mask:0xf bank_mask:0xf
	s_nop 1
	v_add_f32_dpp v148, v148, v148 quad_perm:[2,3,0,1] row_mask:0xf bank_mask:0xf
	s_nop 1
	v_add_f32_dpp v148, v148, v148 row_half_mirror row_mask:0xf bank_mask:0xf
	s_nop 1
	v_add_f32_dpp v148, v148, v148 row_mirror row_mask:0xf bank_mask:0xf
	s_nop 1
	v_add_f32_dpp v148, v148, v148 row_bcast:15 row_mask:0xa bank_mask:0xf
	s_nop 1
	v_add_f32_dpp v148, v148, v148 row_bcast:31 row_mask:0xc bank_mask:0xf
	s_nop 0
	v_readlane_b32 s0, v148, 63
	s_nop 1
	v_mov_b32_e32 v148, s0
	v_fmamk_f32 v148, v148, 0x3b000000, v162
	v_mul_f32_e32 v150, 0x4b800000, v148
	v_cmp_gt_f32_e32 vcc, s31, v148
	s_nop 1
	v_cndmask_b32_e32 v148, v148, v150, vcc
	v_rsq_f32_e32 v148, v148
	s_nop 0
	v_mul_f32_e32 v150, 0x45800000, v148
	v_cndmask_b32_e32 v149, v148, v150, vcc
	v_mul_f32_e32 v140, v149, v140
	v_mul_f32_e32 v141, v149, v141
	v_mul_f32_e32 v142, v149, v142
	v_mul_f32_e32 v143, v149, v143
	v_mul_f32_e32 v144, v149, v144
	v_mul_f32_e32 v145, v149, v145
	v_mul_f32_e32 v146, v149, v146
	v_mul_f32_e32 v147, v149, v147
	v_cvt_pk_bf16_f32 v140, v140, v141
	v_cvt_pk_bf16_f32 v141, v142, v143
	v_cvt_pk_bf16_f32 v142, v144, v145
	v_cvt_pk_bf16_f32 v143, v146, v147
	global_store_dwordx4 v[156:157], v[140:143], off sc1
	s_waitcnt vmcnt(4)
; __device__ __forceinline__ unsigned cvt_pk_bf16(float lo, float hi) { unsigned r; asm volatile("v_cvt_pk_bf16_f32 %0, %1, %2" : "=v"(r) : "v"(lo), "v"(hi)); return r; }
; __device__ __forceinline__ float bf_lo(unsigned w) { return __uint_as_float(w << 16); }
; __device__ __forceinline__ float bf_hi(unsigned w) { return __uint_as_float(w & 0xffff0000u); }
; __global__ void __launch_bounds__(512, 2) trunk_fwd(Args args) {
;     ...
;                 for (int rr = 0; rr < 16; ++rr) {
;                     const int r = r0 + rr;
;                     const u32x4 gb = gb_n, gu = gu_n; const f32x4 pv4 = pv_n;
;                     if (rr < 15) { gb_n = *(const u32x4*)(Z + (size_t)(r + 1) * INP + 768 + c0); gu_n = *(const u32x4*)(Z + (size_t)(r + 1) * INP + 1280 + c0);
;                                    pv_n = *(const f32x4*)(pl + (size_t)(r + 1) * PLE + lane * 4); }
;                     float cv[8], uu[8]; float ss = 0.f;
; #pragma unroll
;                     for (int i = 0; i < 4; ++i) {
;                         uu[2 * i] = bf_lo(gu[i]); uu[2 * i + 1] = bf_hi(gu[i]);
;                         cv[2 * i] = bf_lo(gb[i]) * (w0[2 * i] * uu[2 * i] + w1[2 * i] * u1[2 * i] + w2[2 * i] * u2[2 * i]);
;                         cv[2 * i + 1] = bf_hi(gb[i]) * (w0[2 * i + 1] * uu[2 * i + 1] + w1[2 * i + 1] * u1[2 * i + 1] + w2[2 * i + 1] * u2[2 * i + 1]);
;                     }
; #pragma unroll
;                     for (int i = 0; i < 8; ++i) { ss += cv[i] * cv[i]; u2[i] = u1[i]; u1[i] = uu[i]; }
;                     ss = wave_sum(ss);
;                     const float rc = rsqrtf(ss * (1.0f / 512.0f) + EPS);
;                     u32x4 oc;
; #pragma unroll
;                     for (int i = 0; i < 4; ++i) oc[i] = cvt_pk_bf16(cv[2 * i] * rc, cv[2 * i + 1] * rc);
;                     *(u32x4*)(MIX + (size_t)r * 1024 + 512 + c0) = oc;
;                     u32x2 pw; pw.x = cvt_pk_bf16(pv4[0], pv4[1]); pw.y = cvt_pk_bf16(pv4[2], pv4[3]);
;                     *(u32x2*)(PB + (size_t)r * PLE + lane * 4) = pw;
	v_lshlrev_b32_e32 v188, 16, v30
	v_and_b32_e32 v189, 0xffff0000, v30
	v_lshlrev_b32_e32 v190, 16, v31
	v_and_b32_e32 v191, 0xffff0000, v31
	v_lshlrev_b32_e32 v192, 16, v32
	v_and_b32_e32 v193, 0xffff0000, v32
	v_lshlrev_b32_e32 v194, 16, v33
	v_and_b32_e32 v195, 0xffff0000, v33
	v_mul_f32_e32 v140, v164, v188
	v_mul_f32_e32 v141, v165, v189
	v_mul_f32_e32 v142, v166, v190
	v_mul_f32_e32 v143, v167, v191
	v_mul_f32_e32 v144, v168, v192
	v_mul_f32_e32 v145, v169, v193
	v_mul_f32_e32 v146, v170, v194
	v_mul_f32_e32 v147, v171, v195
	v_fmac_f32_e32 v140, v172, v204
	v_fmac_f32_e32 v141, v173, v205
	v_fmac_f32_e32 v142, v174, v206
	v_fmac_f32_e32 v143, v175, v207
	v_fmac_f32_e32 v144, v176, v208
	v_fmac_f32_e32 v145, v177, v209
	v_fmac_f32_e32 v146, v178, v210
	v_fmac_f32_e32 v147, v179, v211
	v_fmac_f32_e32 v140, v180, v196
	v_fmac_f32_e32 v141, v181, v197
	v_fmac_f32_e32 v142, v182, v198
	v_fmac_f32_e32 v143, v183, v199
	v_fmac_f32_e32 v144, v184, v200
	v_fmac_f32_e32 v145, v185, v201
	v_fmac_f32_e32 v146, v186, v202
	v_fmac_f32_e32 v147, v187, v203
	v_lshlrev_b32_e32 v150, 16, v14
	v_and_b32_e32 v151, 0xffff0000, v14
	v_mul_f32_e32 v140, v150, v140
	v_mul_f32_e32 v141, v151, v141
	v_lshlrev_b32_e32 v150, 16, v15
	v_and_b32_e32 v151, 0xffff0000, v15
	v_mul_f32_e32 v142, v150, v142
	v_mul_f32_e32 v143, v151, v143
	v_lshlrev_b32_e32 v150, 16, v16
	v_and_b32_e32 v151, 0xffff0000, v16
	v_mul_f32_e32 v144, v150, v144
	v_mul_f32_e32 v145, v151, v145
	v_lshlrev_b32_e32 v150, 16, v17
	v_and_b32_e32 v151, 0xffff0000, v17
	v_mul_f32_e32 v146, v150, v146
	v_mul_f32_e32 v147, v151, v147
	v_mul_f32_e32 v148, v140, v140
	v_fmac_f32_e32 v148, v141, v141
	v_fmac_f32_e32 v148, v142, v142
	v_fmac_f32_e32 v148, v143, v143
	v_fmac_f32_e32 v148, v144, v144
	v_fmac_f32_e32 v148, v145, v145
	v_fmac_f32_e32 v148, v146, v146
	v_fmac_f32_e32 v148, v147, v147
	s_nop 1
	v_add_f32_dpp v148, v148, v148 quad_perm:[1,0,3,2] row_mask:0xf bank_mask:0xf
	s_nop 1
	v_add_f32_dpp v148, v148, v148 quad_perm:[2,3,0,1] row_mask:0xf bank_mask:0xf
	s_nop 1
	v_add_f32_dpp v148, v148, v148 row_half_mirror row_mask:0xf bank_mask:0xf
	s_nop 1
	v_add_f32_dpp v148, v148, v148 row_mirror row_mask:0xf bank_mask:0xf
	s_nop 1
	v_add_f32_dpp v148, v148, v148 row_bcast:15 row_mask:0xa bank_mask:0xf
	s_nop 1
	v_add_f32_dpp v148, v148, v148 row_bcast:31 row_mask:0xc bank_mask:0xf
	s_nop 0
	v_readlane_b32 s0, v148, 63
	s_nop 1
	v_mov_b32_e32 v148, s0
	v_fmamk_f32 v148, v148, 0x3b000000, v162
	v_mul_f32_e32 v150, 0x4b800000, v148
	v_cmp_gt_f32_e32 vcc, s31, v148
	s_nop 1
	v_cndmask_b32_e32 v148, v148, v150, vcc
	v_rsq_f32_e32 v148, v148
	s_nop 0
	v_mul_f32_e32 v150, 0x45800000, v148
	v_cndmask_b32_e32 v149, v148, v150, vcc
	v_mul_f32_e32 v140, v149, v140
	v_mul_f32_e32 v141, v149, v141
	v_mul_f32_e32 v142, v149, v142
	v_mul_f32_e32 v143, v149, v143
	v_mul_f32_e32 v144, v149, v144
	v_mul_f32_e32 v145, v149, v145
	v_mul_f32_e32 v146, v149, v146
	v_mul_f32_e32 v147, v149, v147
	v_cvt_pk_bf16_f32 v140, v140, v141
	v_cvt_pk_bf16_f32 v141, v142, v143
	v_cvt_pk_bf16_f32 v142, v144, v145
	v_cvt_pk_bf16_f32 v143, v146, v147
	global_store_dwordx4 v[156:157], v[140:143], off offset:2048 sc1
	v_lshl_add_u64 v[156:157], v[156:157], 0, s[20:21]
	s_branch .LBB0_1053

; __device__ __forceinline__ void wconv_item(const float* W, int K, int Norig, int Nphys, bf16_t* WT, const float* gA, const float* gB, int split, int mapid, LAS float* scr, int item, int lane) {
;     const int nblk = Nphys / 32, kb = item / nblk, nb = item % nblk, k0 = 64 * kb, n0 = 32 * nb;
;     const int norig = colmap(mapid, n0 + (lane & 31));
;     float wv[32];
; #pragma unroll
;     for (int i = 0; i < 32; ++i) { const int k = k0 + 2 * i + (lane >> 5); wv[i] = (norig >= 0) ? W[(size_t)k * Norig + norig] : 0.f; }
; #pragma unroll
; template <class AP> __device__ __forceinline__ void convert_weights(AP a, int L, bf16_t* wb, LAS float* scr, int gw, int NGW, int lane) {
;     ...
;     for (int it = gw; it < NIT; it += NGW) {
;         int r = it;
;         if (r < I0) { wconv_item(w_in, 1024, INC, INP, wb + WO_IN, g_mix, g_mix, 1024, 0, scr, r, lane); continue; } r -= I0;
;         if (r < I1) { wconv_item(w_uq, QL, 768, 768, wb + WO_UQ, g_ql, g_ql, QL, 1, scr, r, lane); continue; } r -= I1;
;         if (r < I2) { wconv_item(w_ukv, KVL, 1024, 1024, wb + WO_UKV, g_kvl, g_kvl, KVL, 2, scr, r, lane); continue; } r -= I2;
;         if (r < I3) { wconv_item(w_o, 1024, 1024, 1024, wb + WO_O, g_oa, g_oc, 512, 3, scr, r, lane); continue; } r -= I3;
;         if (r < I4) { wconv_item(w_up, 1024, FF, FF, wb + WO_UP, g_mlp, g_mlp, 1024, 3, scr, r, lane); continue; } r -= I4;
;         if (r < I5) { wconv_item(w_dn, FF, 1024, 1024, wb + WO_DN, nullptr, nullptr, 0, 3, scr, r, lane); continue; } r -= I5;
;         if (r < I6) { wconv_item(w_g, 1024, 1024, 1024, wb + WO_G, g_ple, g_ple, 1024, 3, scr, r, lane); continue; } r -= I6;
;         wconv_item(w_ple, PLE, 1024, 1024, wb + WO_PLE, nullptr, nullptr, 0, 3, scr, r, lane);
.LBB0_1066:
	s_cmpk_gt_i32 s75, 0x47f
	s_mov_b64 s[38:39], -1
	s_cbranch_scc0 .LBB0_1160
	s_cmpk_gt_u32 s75, 0x50f
	s_cbranch_scc0 .LBB0_1141
	s_cmpk_gt_u32 s75, 0x58f
	s_cbranch_scc0 .LBB0_1122
	s_cmpk_gt_u32 s75, 0x78f
	s_cbranch_scc0 .LBB0_1107
	s_cmpk_gt_u32 s75, 0xf8f
	s_cbranch_scc0 .LBB0_1092
	s_cmpk_gt_u32 s75, 0x178f
	s_cbranch_scc0 .LBB0_1089
	s_cmpk_gt_u32 s75, 0x198f
	s_cbranch_scc0 .LBB0_1074
	s_add_i32 s4, s82, 0xfffcce00
	s_and_b32 s38, s4, 0x3e0
	s_and_b32 s39, s84, 0x1c0
	v_or_b32_e32 v0, s38, v42
	v_or_b32_e32 v22, s39, v2
	v_lshlrev_b32_e32 v0, 2, v0
	v_lshl_add_u64 v[20:21], s[66:67], 0, v[0:1]
	v_lshlrev_b32_e32 v0, 12, v22
	v_lshl_add_u64 v[20:21], v[20:21], 0, v[0:1]
	v_add_co_u32_e32 v22, vcc, 0x2000, v20
	global_load_dword v0, v[20:21], off nt
	s_nop 0
	v_addc_co_u32_e32 v23, vcc, 0, v21, vcc
	global_load_dword v24, v[22:23], off nt
	v_add_co_u32_e32 v22, vcc, 0x4000, v20
	s_mov_b32 s4, 0x10000
	s_nop 0
	v_addc_co_u32_e32 v23, vcc, 0, v21, vcc
	global_load_dword v25, v[22:23], off nt
	v_add_co_u32_e32 v22, vcc, 0x6000, v20
	s_lshl_b32 s48, s39, 1
	s_nop 0
	v_addc_co_u32_e32 v23, vcc, 0, v21, vcc
	global_load_dword v26, v[22:23], off nt
	v_add_co_u32_e32 v22, vcc, 0x8000, v20
	s_nop 1
	v_addc_co_u32_e32 v23, vcc, 0, v21, vcc
	global_load_dword v27, v[22:23], off nt
	v_add_co_u32_e32 v22, vcc, 0xa000, v20
	s_nop 1
	v_addc_co_u32_e32 v23, vcc, 0, v21, vcc
	global_load_dword v28, v[22:23], off nt
	v_add_co_u32_e32 v22, vcc, 0xc000, v20
	s_nop 1
	v_addc_co_u32_e32 v23, vcc, 0, v21, vcc
	global_load_dword v29, v[22:23], off nt
	v_add_co_u32_e32 v22, vcc, 0xe000, v20
	s_nop 1
	v_addc_co_u32_e32 v23, vcc, 0, v21, vcc
	global_load_dword v30, v[22:23], off nt
	v_add_co_u32_e32 v22, vcc, s4, v20
	s_mov_b32 s4, 0x12000
	s_nop 0
	v_addc_co_u32_e32 v23, vcc, 0, v21, vcc
	global_load_dword v31, v[22:23], off nt
	v_add_co_u32_e32 v22, vcc, s4, v20
	s_mov_b32 s4, 0x14000
	s_nop 0
	v_addc_co_u32_e32 v23, vcc, 0, v21, vcc
	global_load_dword v32, v[22:23], off nt
	v_add_co_u32_e32 v22, vcc, s4, v20
	s_mov_b32 s4, 0x16000
	s_nop 0
	v_addc_co_u32_e32 v23, vcc, 0, v21, vcc
	global_load_dword v33, v[22:23], off nt
	v_add_co_u32_e32 v22, vcc, s4, v20
	s_mov_b32 s4, 0x18000
	s_nop 0
	v_addc_co_u32_e32 v23, vcc, 0, v21, vcc
	global_load_dword v34, v[22:23], off nt
	v_add_co_u32_e32 v22, vcc, s4, v20
	s_mov_b32 s4, 0x1a000
	s_nop 0
	v_addc_co_u32_e32 v23, vcc, 0, v21, vcc
	global_load_dword v35, v[22:23], off nt
	v_add_co_u32_e32 v22, vcc, s4, v20
	s_mov_b32 s4, 0x1c000
	s_nop 0
	v_addc_co_u32_e32 v23, vcc, 0, v21, vcc
	global_load_dword v36, v[22:23], off nt
	v_add_co_u32_e32 v22, vcc, s4, v20
	s_mov_b32 s4, 0x1e000
	s_nop 0
	v_addc_co_u32_e32 v23, vcc, 0, v21, vcc
	global_load_dword v37, v[22:23], off nt
	v_add_co_u32_e32 v22, vcc, s4, v20
	s_mov_b32 s4, 0x20000
	s_nop 0
	v_addc_co_u32_e32 v23, vcc, 0, v21, vcc
	global_load_dword v38, v[22:23], off nt
	v_add_co_u32_e32 v22, vcc, s4, v20
	s_mov_b32 s4, 0x22000
	s_nop 0
	v_addc_co_u32_e32 v23, vcc, 0, v21, vcc
	global_load_dword v39, v[22:23], off nt
	v_add_co_u32_e32 v22, vcc, s4, v20
	s_mov_b32 s4, 0x24000
	s_nop 0
	v_addc_co_u32_e32 v23, vcc, 0, v21, vcc
	global_load_dword v40, v[22:23], off nt
	v_add_co_u32_e32 v22, vcc, s4, v20
	s_mov_b32 s4, 0x26000
	s_nop 0
	v_addc_co_u32_e32 v23, vcc, 0, v21, vcc
	global_load_dword v41, v[22:23], off nt
	v_add_co_u32_e32 v22, vcc, s4, v20
	s_mov_b32 s4, 0x28000
	s_nop 0
	v_addc_co_u32_e32 v23, vcc, 0, v21, vcc
	global_load_dword v91, v[22:23], off nt
	v_add_co_u32_e32 v22, vcc, s4, v20
	s_mov_b32 s4, 0x2a000
	s_nop 0
	v_addc_co_u32_e32 v23, vcc, 0, v21, vcc
	global_load_dword v92, v[22:23], off nt
	v_add_co_u32_e32 v22, vcc, s4, v20
	s_mov_b32 s4, 0x2c000
	s_nop 0
	v_addc_co_u32_e32 v23, vcc, 0, v21, vcc
	global_load_dword v93, v[22:23], off nt
	v_add_co_u32_e32 v22, vcc, s4, v20
	s_mov_b32 s4, 0x2e000
	s_nop 0
	v_addc_co_u32_e32 v23, vcc, 0, v21, vcc
	global_load_dword v94, v[22:23], off nt
	v_add_co_u32_e32 v22, vcc, s4, v20
	s_mov_b32 s4, 0x30000
	s_nop 0
	v_addc_co_u32_e32 v23, vcc, 0, v21, vcc
	global_load_dword v95, v[22:23], off nt
	v_add_co_u32_e32 v22, vcc, s4, v20
	s_mov_b32 s4, 0x32000
	s_nop 0
	v_addc_co_u32_e32 v23, vcc, 0, v21, vcc
	global_load_dword v96, v[22:23], off nt
	v_add_co_u32_e32 v22, vcc, s4, v20
	s_mov_b32 s4, 0x34000
	s_nop 0
	v_addc_co_u32_e32 v23, vcc, 0, v21, vcc
	global_load_dword v97, v[22:23], off nt
	v_add_co_u32_e32 v22, vcc, s4, v20
	s_mov_b32 s4, 0x36000
	s_nop 0
	v_addc_co_u32_e32 v23, vcc, 0, v21, vcc
	global_load_dword v98, v[22:23], off nt
	v_add_co_u32_e32 v22, vcc, s4, v20
	s_mov_b32 s4, 0x38000
	s_nop 0
	v_addc_co_u32_e32 v23, vcc, 0, v21, vcc
	global_load_dword v99, v[22:23], off nt
	v_add_co_u32_e32 v22, vcc, s4, v20
	s_mov_b32 s4, 0x3a000
	s_nop 0
	v_addc_co_u32_e32 v23, vcc, 0, v21, vcc
	global_load_dword v100, v[22:23], off nt
	v_add_co_u32_e32 v22, vcc, s4, v20
	s_mov_b32 s4, 0x3c000
	s_nop 0
	v_addc_co_u32_e32 v23, vcc, 0, v21, vcc
	global_load_dword v101, v[22:23], off nt
	v_add_co_u32_e32 v22, vcc, s4, v20
	s_mov_b32 s4, 0x3e000
	s_nop 0
	v_addc_co_u32_e32 v23, vcc, 0, v21, vcc
	v_add_co_u32_e32 v20, vcc, s4, v20
	global_load_dword v22, v[22:23], off nt
	s_nop 0
	v_addc_co_u32_e32 v21, vcc, 0, v21, vcc
	global_load_dword v20, v[20:21], off nt
	s_waitcnt vmcnt(0)
; #define LAS __attribute__((address_space(3)))
; __device__ __forceinline__ unsigned cvt_pk_bf16(float lo, float hi) { unsigned r; asm volatile("v_cvt_pk_bf16_f32 %0, %1, %2" : "=v"(r) : "v"(lo), "v"(hi)); return r; }
; __device__ __forceinline__ void wconv_item(const float* W, int K, int Norig, int Nphys, bf16_t* WT, const float* gA, const float* gB, int split, int mapid, LAS float* scr, int item, int lane) {
;     ...
;     for (int i = 0; i < 32; ++i) { const int kk = 2 * i + (lane >> 5), k = k0 + kk;
;         float v = wv[i];
;         if (gA) v *= (k < split ? gA[k] : gB[k - split]);
;         scr[kk * 33 + (lane & 31)] = v; }
;     asm volatile("s_waitcnt lgkmcnt(0)" ::: "memory");
;     const int c = lane & 7;
; #pragma unroll
;     for (int j = 0; j < 4; ++j) { const int n = (lane >> 3) + 8 * j; const LAS float* s = scr + (8 * c) * 33 + n;
;         u32x4 o; o.x = cvt_pk_bf16(s[0 * 33], s[1 * 33]); o.y = cvt_pk_bf16(s[2 * 33], s[3 * 33]); o.z = cvt_pk_bf16(s[4 * 33], s[5 * 33]); o.w = cvt_pk_bf16(s[6 * 33], s[7 * 33]);
;         *(u32x4*)(WT + (size_t)(n0 + n) * K + k0 + 8 * c) = o; }
;     asm volatile("s_waitcnt lgkmcnt(0)" ::: "memory");
	ds_write2_b32 v44, v0, v24 offset1:66
	ds_write2_b32 v44, v25, v26 offset0:132 offset1:198
	v_add_u32_e32 v0, 0x400, v44
	ds_write2_b32 v0, v27, v28 offset0:8 offset1:74
	ds_write2_b32 v0, v29, v30 offset0:140 offset1:206
	v_add_u32_e32 v0, 0x800, v44
	ds_write2_b32 v0, v31, v32 offset0:16 offset1:82
	ds_write2_b32 v0, v33, v34 offset0:148 offset1:214
	v_add_u32_e32 v0, 0xc00, v44
	ds_write2_b32 v0, v35, v36 offset0:24 offset1:90
	ds_write2_b32 v0, v37, v38 offset0:156 offset1:222
	v_add_u32_e32 v0, 0x1000, v44
	ds_write2_b32 v0, v39, v40 offset0:32 offset1:98
	ds_write2_b32 v0, v41, v91 offset0:164 offset1:230
	v_add_u32_e32 v0, 0x1400, v44
	ds_write2_b32 v0, v92, v93 offset0:40 offset1:106
	ds_write2_b32 v0, v94, v95 offset0:172 offset1:238
	v_add_u32_e32 v0, 0x1800, v44
	ds_write2_b32 v0, v96, v97 offset0:48 offset1:114
	ds_write2_b32 v0, v98, v99 offset0:180 offset1:246
	v_add_u32_e32 v0, 0x1c00, v44
	ds_write2_b32 v0, v100, v101 offset0:56 offset1:122
	ds_write2_b32 v0, v22, v20 offset0:188 offset1:254
	s_waitcnt lgkmcnt(0)
	ds_read2_b32 v[20:21], v46 offset1:33
	s_waitcnt lgkmcnt(0)
	v_cvt_pk_bf16_f32 v20, v20, v21
	ds_read2_b32 v[22:23], v46 offset0:66 offset1:99
	s_waitcnt lgkmcnt(0)
	v_cvt_pk_bf16_f32 v21, v22, v23
	ds_read2_b32 v[22:23], v46 offset0:132 offset1:165
	v_or_b32_e32 v0, s38, v45
	v_lshl_add_u64 v[24:25], v[4:5], 0, s[48:49]
	s_waitcnt lgkmcnt(0)
	v_cvt_pk_bf16_f32 v22, v22, v23
	ds_read2_b32 v[26:27], v46 offset0:198 offset1:231
	v_lshlrev_b32_e32 v0, 9, v0
	s_waitcnt lgkmcnt(0)
	v_cvt_pk_bf16_f32 v23, v26, v27
	v_lshl_add_u64 v[26:27], v[24:25], 0, v[0:1]
	global_store_dwordx4 v[26:27], v[20:23], off sc1
	ds_read2_b32 v[20:21], v46 offset0:8 offset1:41
	v_or_b32_e32 v0, s38, v47
	s_waitcnt lgkmcnt(0)
	v_cvt_pk_bf16_f32 v20, v20, v21
	ds_read2_b32 v[22:23], v46 offset0:74 offset1:107
	s_waitcnt lgkmcnt(0)
	v_cvt_pk_bf16_f32 v21, v22, v23
	ds_read2_b32 v[22:23], v46 offset0:140 offset1:173
	s_waitcnt lgkmcnt(0)
	v_cvt_pk_bf16_f32 v22, v22, v23
	ds_read2_b32 v[26:27], v46 offset0:206 offset1:239
	v_lshlrev_b32_e32 v0, 9, v0
	s_waitcnt lgkmcnt(0)
	v_cvt_pk_bf16_f32 v23, v26, v27
	v_lshl_add_u64 v[26:27], v[24:25], 0, v[0:1]
	global_store_dwordx4 v[26:27], v[20:23], off sc1
	ds_read2_b32 v[20:21], v46 offset0:16 offset1:49
	v_or_b32_e32 v0, s38, v48
	s_waitcnt lgkmcnt(0)
	v_cvt_pk_bf16_f32 v20, v20, v21
	ds_read2_b32 v[22:23], v46 offset0:82 offset1:115
	s_waitcnt lgkmcnt(0)
	v_cvt_pk_bf16_f32 v21, v22, v23
	ds_read2_b32 v[22:23], v46 offset0:148 offset1:181
	s_waitcnt lgkmcnt(0)
	v_cvt_pk_bf16_f32 v22, v22, v23
	ds_read2_b32 v[26:27], v46 offset0:214 offset1:247
	v_lshlrev_b32_e32 v0, 9, v0
	s_waitcnt lgkmcnt(0)
	v_cvt_pk_bf16_f32 v23, v26, v27
	v_lshl_add_u64 v[26:27], v[24:25], 0, v[0:1]
	global_store_dwordx4 v[26:27], v[20:23], off sc1
	ds_read2_b32 v[20:21], v46 offset0:24 offset1:57
	v_or_b32_e32 v0, s38, v49
	s_waitcnt lgkmcnt(0)
	v_cvt_pk_bf16_f32 v20, v20, v21
	ds_read2_b32 v[22:23], v46 offset0:90 offset1:123
	v_lshlrev_b32_e32 v0, 9, v0
	s_waitcnt lgkmcnt(0)
	v_cvt_pk_bf16_f32 v21, v22, v23
	ds_read2_b32 v[22:23], v46 offset0:156 offset1:189
	v_lshl_add_u64 v[24:25], v[24:25], 0, v[0:1]
	s_waitcnt lgkmcnt(0)
	v_cvt_pk_bf16_f32 v22, v22, v23
	ds_read2_b32 v[26:27], v46 offset0:222 offset1:255
	s_waitcnt lgkmcnt(0)
	v_cvt_pk_bf16_f32 v23, v26, v27
	global_store_dwordx4 v[24:25], v[20:23], off sc1
	s_waitcnt lgkmcnt(0)
	s_mov_b64 s[38:39], 0
; __device__ __forceinline__ void wconv_item(const float* W, int K, int Norig, int Nphys, bf16_t* WT, const float* gA, const float* gB, int split, int mapid, LAS float* scr, int item, int lane) {
;     const int nblk = Nphys / 32, kb = item / nblk, nb = item % nblk, k0 = 64 * kb, n0 = 32 * nb;
;     const int norig = colmap(mapid, n0 + (lane & 31));
;     float wv[32];
; #pragma unroll
;     for (int i = 0; i < 32; ++i) { const int k = k0 + 2 * i + (lane >> 5); wv[i] = (norig >= 0) ? W[(size_t)k * Norig + norig] : 0.f; }
; #pragma unroll
;     for (int i = 0; i < 32; ++i) { const int kk = 2 * i + (lane >> 5), k = k0 + kk;
;         float v = wv[i];
;         if (gA) v *= (k < split ? gA[k] : gB[k - split]);
;         scr[kk * 33 + (lane & 31)] = v; }
.LBB0_1074:
	s_andn2_b64 vcc, exec, s[38:39]
	s_cbranch_vccnz .LBB0_1088
	s_add_i32 s4, s84, 0x400
	s_and_b32 s48, s4, 0x1ffc0
	s_add_i32 s4, s82, 0xfffd0e00
	s_and_b32 s72, s4, 0x3e0
	v_or_b32_e32 v0, s72, v42
	v_readlane_b32 s4, v255, 29
	v_or_b32_e32 v38, s48, v2
	v_lshlrev_b32_e32 v0, 2, v0
	v_readlane_b32 s5, v255, 30
	v_add_lshl_u32 v104, s48, v2, 2
	s_nop 0
	v_lshl_add_u64 v[20:21], s[4:5], 0, v[0:1]
	v_lshlrev_b32_e32 v0, 12, v38
	v_lshl_add_u64 v[36:37], v[20:21], 0, v[0:1]
	v_add_co_u32_e32 v20, vcc, 0x2000, v36
	global_load_dword v100, v[36:37], off nt
	s_nop 0
	v_addc_co_u32_e32 v21, vcc, 0, v37, vcc
	global_load_dword v101, v[20:21], off nt
	v_add_co_u32_e32 v20, vcc, 0x4000, v36
	s_mov_b32 s4, 0x10000
	s_nop 0
	v_addc_co_u32_e32 v21, vcc, 0, v37, vcc
	global_load_dword v102, v[20:21], off nt
	v_add_co_u32_e32 v20, vcc, 0x6000, v36
	s_nop 1
	v_addc_co_u32_e32 v21, vcc, 0, v37, vcc
	global_load_dword v103, v[20:21], off nt
	v_add_co_u32_e32 v20, vcc, 0x8000, v36
	s_nop 1
	v_addc_co_u32_e32 v21, vcc, 0, v37, vcc
	global_load_dword v32, v[20:21], off nt
	v_add_co_u32_e32 v20, vcc, 0xa000, v36
	s_nop 1
	v_addc_co_u32_e32 v21, vcc, 0, v37, vcc
	global_load_dword v33, v[20:21], off nt
	v_add_co_u32_e32 v20, vcc, 0xc000, v36
	s_nop 1
	v_addc_co_u32_e32 v21, vcc, 0, v37, vcc
	global_load_dword v34, v[20:21], off nt
	v_add_co_u32_e32 v20, vcc, 0xe000, v36
	s_nop 1
	v_addc_co_u32_e32 v21, vcc, 0, v37, vcc
	global_load_dword v35, v[20:21], off nt
	v_add_co_u32_e32 v20, vcc, s4, v36
	s_mov_b32 s4, 0x12000
	s_nop 0
	v_addc_co_u32_e32 v21, vcc, 0, v37, vcc
	global_load_dword v96, v[20:21], off nt
	v_add_co_u32_e32 v20, vcc, s4, v36
	s_mov_b32 s4, 0x14000
	s_nop 0
	v_addc_co_u32_e32 v21, vcc, 0, v37, vcc
	global_load_dword v97, v[20:21], off nt
	v_add_co_u32_e32 v20, vcc, s4, v36
	s_mov_b32 s4, 0x16000
	s_nop 0
	v_addc_co_u32_e32 v21, vcc, 0, v37, vcc
	global_load_dword v98, v[20:21], off nt
	v_add_co_u32_e32 v20, vcc, s4, v36
	s_mov_b32 s4, 0x18000
	s_nop 0
	v_addc_co_u32_e32 v21, vcc, 0, v37, vcc
	global_load_dword v99, v[20:21], off nt
	v_add_co_u32_e32 v20, vcc, s4, v36
	s_mov_b32 s4, 0x1a000
	s_nop 0
	v_addc_co_u32_e32 v21, vcc, 0, v37, vcc
	global_load_dword v28, v[20:21], off nt
	v_add_co_u32_e32 v20, vcc, s4, v36
	s_mov_b32 s4, 0x1c000
	s_nop 0
	v_addc_co_u32_e32 v21, vcc, 0, v37, vcc
	global_load_dword v29, v[20:21], off nt
	v_add_co_u32_e32 v20, vcc, s4, v36
	s_mov_b32 s4, 0x1e000
	s_nop 0
	v_addc_co_u32_e32 v21, vcc, 0, v37, vcc
	global_load_dword v30, v[20:21], off nt
	v_add_co_u32_e32 v20, vcc, s4, v36
	s_mov_b32 s4, 0x20000
	s_nop 0
	v_addc_co_u32_e32 v21, vcc, 0, v37, vcc
	global_load_dword v31, v[20:21], off nt
	v_add_co_u32_e32 v20, vcc, s4, v36
	s_mov_b32 s4, 0x22000
	s_nop 0
	v_addc_co_u32_e32 v21, vcc, 0, v37, vcc
	global_load_dword v92, v[20:21], off nt
	v_add_co_u32_e32 v20, vcc, s4, v36
	s_mov_b32 s4, 0x24000
	s_nop 0
	v_addc_co_u32_e32 v21, vcc, 0, v37, vcc
	global_load_dword v93, v[20:21], off nt
	v_add_co_u32_e32 v20, vcc, s4, v36
	s_mov_b32 s4, 0x26000
	s_nop 0
	v_addc_co_u32_e32 v21, vcc, 0, v37, vcc
	global_load_dword v94, v[20:21], off nt
	v_add_co_u32_e32 v20, vcc, s4, v36
	s_mov_b32 s4, 0x28000
	s_nop 0
	v_addc_co_u32_e32 v21, vcc, 0, v37, vcc
	global_load_dword v95, v[20:21], off nt
	v_add_co_u32_e32 v20, vcc, s4, v36
	s_mov_b32 s4, 0x2a000
	s_nop 0
	v_addc_co_u32_e32 v21, vcc, 0, v37, vcc
	global_load_dword v24, v[20:21], off nt
	v_add_co_u32_e32 v20, vcc, s4, v36
	s_mov_b32 s4, 0x2c000
	s_nop 0
	v_addc_co_u32_e32 v21, vcc, 0, v37, vcc
	global_load_dword v25, v[20:21], off nt
	v_add_co_u32_e32 v20, vcc, s4, v36
	s_mov_b32 s4, 0x2e000
	s_nop 0
	v_addc_co_u32_e32 v21, vcc, 0, v37, vcc
	global_load_dword v26, v[20:21], off nt
	v_add_co_u32_e32 v20, vcc, s4, v36
	s_mov_b32 s4, 0x30000
	s_nop 0
	v_addc_co_u32_e32 v21, vcc, 0, v37, vcc
	global_load_dword v27, v[20:21], off nt
	v_add_co_u32_e32 v20, vcc, s4, v36
	s_mov_b32 s4, 0x32000
	s_nop 0
	v_addc_co_u32_e32 v21, vcc, 0, v37, vcc
	global_load_dword v0, v[20:21], off nt
	v_add_co_u32_e32 v20, vcc, s4, v36
	s_mov_b32 s4, 0x34000
	s_nop 0
	v_addc_co_u32_e32 v21, vcc, 0, v37, vcc
	global_load_dword v40, v[20:21], off nt
	v_add_co_u32_e32 v20, vcc, s4, v36
	s_mov_b32 s4, 0x36000
	s_nop 0
	v_addc_co_u32_e32 v21, vcc, 0, v37, vcc
	global_load_dword v41, v[20:21], off nt
	v_add_co_u32_e32 v20, vcc, s4, v36
	s_mov_b32 s4, 0x38000
	s_nop 0
	v_addc_co_u32_e32 v21, vcc, 0, v37, vcc
	global_load_dword v91, v[20:21], off nt
	v_add_co_u32_e32 v20, vcc, s4, v36
	v_readlane_b32 s4, v255, 31
	s_nop 0
	v_addc_co_u32_e32 v21, vcc, 0, v37, vcc
	v_add_co_u32_e32 v22, vcc, 0x3a000, v36
	global_load_dword v20, v[20:21], off nt
	s_nop 0
	v_addc_co_u32_e32 v23, vcc, 0, v37, vcc
	global_load_dword v21, v[22:23], off nt
	v_add_co_u32_e32 v22, vcc, 0x3c000, v36
	v_readlane_b32 s5, v255, 32
	s_nop 0
	v_addc_co_u32_e32 v23, vcc, 0, v37, vcc
	v_add_co_u32_e32 v36, vcc, 0x3e000, v36
	global_load_dword v22, v[22:23], off nt
	s_nop 0
	v_addc_co_u32_e32 v37, vcc, 0, v37, vcc
	global_load_dword v23, v[36:37], off nt
	v_cndmask_b32_e64 v36, 0, 1, s[4:5]
	v_cmp_ne_u32_e64 s[38:39], 1, v36
	s_andn2_b64 vcc, exec, s[4:5]
	s_cbranch_vccnz .LBB0_1264
	v_lshlrev_b32_e32 v36, 2, v38
	global_load_dword v36, v36, s[62:63]
	s_nop 0
	global_load_dword v37, v104, s[62:63] offset:8
	global_load_dword v38, v104, s[62:63] offset:16
	global_load_dword v39, v104, s[62:63] offset:24
	s_waitcnt vmcnt(0)
	v_mul_f32_e32 v36, v100, v36
	ds_write_b32 v44, v36
	v_mul_f32_e32 v37, v101, v37
	v_mul_f32_e32 v38, v102, v38
	v_add_u32_e32 v36, v43, v51
	v_mul_f32_e32 v39, v103, v39
	ds_write2_b32 v36, v37, v38 offset1:66
	ds_write_b32 v36, v39 offset:528
	global_load_dword v36, v104, s[62:63] offset:32
	global_load_dword v37, v104, s[62:63] offset:40
	global_load_dword v38, v104, s[62:63] offset:48
	global_load_dword v39, v104, s[62:63] offset:56
	s_waitcnt vmcnt(2)
	v_pk_mul_f32 v[36:37], v[32:33], v[36:37]
	s_waitcnt vmcnt(0)
	v_pk_mul_f32 v[38:39], v[34:35], v[38:39]
	s_cbranch_execnz .LBB0_1078

; __device__ __forceinline__ void wconv_item(const float* W, int K, int Norig, int Nphys, bf16_t* WT, const float* gA, const float* gB, int split, int mapid, LAS float* scr, int item, int lane) {
;     const int nblk = Nphys / 32, kb = item / nblk, nb = item % nblk, k0 = 64 * kb, n0 = 32 * nb;
;     const int norig = colmap(mapid, n0 + (lane & 31));
;     float wv[32];
; #pragma unroll
;     for (int i = 0; i < 32; ++i) { const int k = k0 + 2 * i + (lane >> 5); wv[i] = (norig >= 0) ? W[(size_t)k * Norig + norig] : 0.f; }
; #pragma unroll
.LBB0_1089:
	s_andn2_b64 vcc, exec, s[38:39]
	s_cbranch_vccnz .LBB0_1091
	s_add_i32 s4, s84, 0x1400
	s_and_b32 s39, s4, 0x1ffc0
	s_add_i32 s4, s82, 0xfffe0e00
	s_and_b32 s38, s4, 0x3e0
	v_or_b32_e32 v0, s38, v42
	v_or_b32_e32 v22, s39, v2
	v_lshlrev_b32_e32 v0, 2, v0
	v_lshl_add_u64 v[20:21], s[88:89], 0, v[0:1]
	v_lshlrev_b32_e32 v0, 12, v22
	v_lshl_add_u64 v[20:21], v[20:21], 0, v[0:1]
	v_add_co_u32_e32 v22, vcc, 0x2000, v20
	global_load_dword v0, v[20:21], off nt
	s_nop 0
	v_addc_co_u32_e32 v23, vcc, 0, v21, vcc
	global_load_dword v24, v[22:23], off nt
	v_add_co_u32_e32 v22, vcc, 0x4000, v20
	s_mov_b32 s4, 0x10000
	s_nop 0
	v_addc_co_u32_e32 v23, vcc, 0, v21, vcc
	global_load_dword v25, v[22:23], off nt
	v_add_co_u32_e32 v22, vcc, 0x6000, v20
	s_lshl_b32 s48, s39, 1
	s_nop 0
	v_addc_co_u32_e32 v23, vcc, 0, v21, vcc
	global_load_dword v26, v[22:23], off nt
	v_add_co_u32_e32 v22, vcc, 0x8000, v20
	s_nop 1
	v_addc_co_u32_e32 v23, vcc, 0, v21, vcc
	global_load_dword v27, v[22:23], off nt
	v_add_co_u32_e32 v22, vcc, 0xa000, v20
	s_nop 1
	v_addc_co_u32_e32 v23, vcc, 0, v21, vcc
	global_load_dword v28, v[22:23], off nt
	v_add_co_u32_e32 v22, vcc, 0xc000, v20
	s_nop 1
	v_addc_co_u32_e32 v23, vcc, 0, v21, vcc
	global_load_dword v29, v[22:23], off nt
	v_add_co_u32_e32 v22, vcc, 0xe000, v20
	s_nop 1
	v_addc_co_u32_e32 v23, vcc, 0, v21, vcc
	global_load_dword v30, v[22:23], off nt
	v_add_co_u32_e32 v22, vcc, s4, v20
	s_mov_b32 s4, 0x12000
	s_nop 0
	v_addc_co_u32_e32 v23, vcc, 0, v21, vcc
	global_load_dword v31, v[22:23], off nt
	v_add_co_u32_e32 v22, vcc, s4, v20
	s_mov_b32 s4, 0x14000
	s_nop 0
	v_addc_co_u32_e32 v23, vcc, 0, v21, vcc
	global_load_dword v32, v[22:23], off nt
	v_add_co_u32_e32 v22, vcc, s4, v20
	s_mov_b32 s4, 0x16000
	s_nop 0
	v_addc_co_u32_e32 v23, vcc, 0, v21, vcc
	global_load_dword v33, v[22:23], off nt
	v_add_co_u32_e32 v22, vcc, s4, v20
	s_mov_b32 s4, 0x18000
	s_nop 0
	v_addc_co_u32_e32 v23, vcc, 0, v21, vcc
	global_load_dword v34, v[22:23], off nt
	v_add_co_u32_e32 v22, vcc, s4, v20
	s_mov_b32 s4, 0x1a000
	s_nop 0
	v_addc_co_u32_e32 v23, vcc, 0, v21, vcc
	global_load_dword v35, v[22:23], off nt
	v_add_co_u32_e32 v22, vcc, s4, v20
	s_mov_b32 s4, 0x1c000
	s_nop 0
	v_addc_co_u32_e32 v23, vcc, 0, v21, vcc
	global_load_dword v36, v[22:23], off nt
	v_add_co_u32_e32 v22, vcc, s4, v20
	s_mov_b32 s4, 0x1e000
	s_nop 0
	v_addc_co_u32_e32 v23, vcc, 0, v21, vcc
	global_load_dword v37, v[22:23], off nt
	v_add_co_u32_e32 v22, vcc, s4, v20
	s_mov_b32 s4, 0x20000
	s_nop 0
	v_addc_co_u32_e32 v23, vcc, 0, v21, vcc
	global_load_dword v38, v[22:23], off nt
	v_add_co_u32_e32 v22, vcc, s4, v20
	s_mov_b32 s4, 0x22000
	s_nop 0
	v_addc_co_u32_e32 v23, vcc, 0, v21, vcc
	global_load_dword v39, v[22:23], off nt
	v_add_co_u32_e32 v22, vcc, s4, v20
	s_mov_b32 s4, 0x24000
	s_nop 0
	v_addc_co_u32_e32 v23, vcc, 0, v21, vcc
	global_load_dword v40, v[22:23], off nt
	v_add_co_u32_e32 v22, vcc, s4, v20
	s_mov_b32 s4, 0x26000
	s_nop 0
	v_addc_co_u32_e32 v23, vcc, 0, v21, vcc
	global_load_dword v41, v[22:23], off nt
	v_add_co_u32_e32 v22, vcc, s4, v20
	s_mov_b32 s4, 0x28000
	s_nop 0
	v_addc_co_u32_e32 v23, vcc, 0, v21, vcc
	global_load_dword v91, v[22:23], off nt
	v_add_co_u32_e32 v22, vcc, s4, v20
	s_mov_b32 s4, 0x2a000
	s_nop 0
	v_addc_co_u32_e32 v23, vcc, 0, v21, vcc
	global_load_dword v92, v[22:23], off nt
	v_add_co_u32_e32 v22, vcc, s4, v20
	s_mov_b32 s4, 0x2c000
	s_nop 0
	v_addc_co_u32_e32 v23, vcc, 0, v21, vcc
	global_load_dword v93, v[22:23], off nt
	v_add_co_u32_e32 v22, vcc, s4, v20
	s_mov_b32 s4, 0x2e000
	s_nop 0
	v_addc_co_u32_e32 v23, vcc, 0, v21, vcc
	global_load_dword v94, v[22:23], off nt
	v_add_co_u32_e32 v22, vcc, s4, v20
	s_mov_b32 s4, 0x30000
	s_nop 0
	v_addc_co_u32_e32 v23, vcc, 0, v21, vcc
	global_load_dword v95, v[22:23], off nt
	v_add_co_u32_e32 v22, vcc, s4, v20
	s_mov_b32 s4, 0x32000
	s_nop 0
	v_addc_co_u32_e32 v23, vcc, 0, v21, vcc
	global_load_dword v96, v[22:23], off nt
	v_add_co_u32_e32 v22, vcc, s4, v20
	s_mov_b32 s4, 0x34000
	s_nop 0
	v_addc_co_u32_e32 v23, vcc, 0, v21, vcc
	global_load_dword v97, v[22:23], off nt
	v_add_co_u32_e32 v22, vcc, s4, v20
	s_mov_b32 s4, 0x36000
	s_nop 0
	v_addc_co_u32_e32 v23, vcc, 0, v21, vcc
	global_load_dword v98, v[22:23], off nt
	v_add_co_u32_e32 v22, vcc, s4, v20
	s_mov_b32 s4, 0x38000
	s_nop 0
	v_addc_co_u32_e32 v23, vcc, 0, v21, vcc
	global_load_dword v99, v[22:23], off nt
	v_add_co_u32_e32 v22, vcc, s4, v20
	s_mov_b32 s4, 0x3a000
	s_nop 0
	v_addc_co_u32_e32 v23, vcc, 0, v21, vcc
	global_load_dword v100, v[22:23], off nt
	v_add_co_u32_e32 v22, vcc, s4, v20
	s_mov_b32 s4, 0x3c000
	s_nop 0
	v_addc_co_u32_e32 v23, vcc, 0, v21, vcc
	global_load_dword v101, v[22:23], off nt
	v_add_co_u32_e32 v22, vcc, s4, v20
	s_mov_b32 s4, 0x3e000
	s_nop 0
	v_addc_co_u32_e32 v23, vcc, 0, v21, vcc
	v_add_co_u32_e32 v20, vcc, s4, v20
	global_load_dword v22, v[22:23], off nt
	s_nop 0
	v_addc_co_u32_e32 v21, vcc, 0, v21, vcc
	global_load_dword v20, v[20:21], off nt
	s_waitcnt vmcnt(0)
; #define LAS __attribute__((address_space(3)))
; __device__ __forceinline__ unsigned cvt_pk_bf16(float lo, float hi) { unsigned r; asm volatile("v_cvt_pk_bf16_f32 %0, %1, %2" : "=v"(r) : "v"(lo), "v"(hi)); return r; }
; __device__ __forceinline__ void wconv_item(const float* W, int K, int Norig, int Nphys, bf16_t* WT, const float* gA, const float* gB, int split, int mapid, LAS float* scr, int item, int lane) {
;     ...
;     for (int i = 0; i < 32; ++i) { const int kk = 2 * i + (lane >> 5), k = k0 + kk;
;         float v = wv[i];
;         if (gA) v *= (k < split ? gA[k] : gB[k - split]);
;         scr[kk * 33 + (lane & 31)] = v; }
;     asm volatile("s_waitcnt lgkmcnt(0)" ::: "memory");
;     const int c = lane & 7;
; #pragma unroll
;     for (int j = 0; j < 4; ++j) { const int n = (lane >> 3) + 8 * j; const LAS float* s = scr + (8 * c) * 33 + n;
;         u32x4 o; o.x = cvt_pk_bf16(s[0 * 33], s[1 * 33]); o.y = cvt_pk_bf16(s[2 * 33], s[3 * 33]); o.z = cvt_pk_bf16(s[4 * 33], s[5 * 33]); o.w = cvt_pk_bf16(s[6 * 33], s[7 * 33]);
;         *(u32x4*)(WT + (size_t)(n0 + n) * K + k0 + 8 * c) = o; }
;     asm volatile("s_waitcnt lgkmcnt(0)" ::: "memory");
	ds_write2_b32 v44, v0, v24 offset1:66
	ds_write2_b32 v44, v25, v26 offset0:132 offset1:198
	v_add_u32_e32 v0, 0x400, v44
	ds_write2_b32 v0, v27, v28 offset0:8 offset1:74
	ds_write2_b32 v0, v29, v30 offset0:140 offset1:206
	v_add_u32_e32 v0, 0x800, v44
	ds_write2_b32 v0, v31, v32 offset0:16 offset1:82
	ds_write2_b32 v0, v33, v34 offset0:148 offset1:214
	v_add_u32_e32 v0, 0xc00, v44
	ds_write2_b32 v0, v35, v36 offset0:24 offset1:90
	ds_write2_b32 v0, v37, v38 offset0:156 offset1:222
	v_add_u32_e32 v0, 0x1000, v44
	ds_write2_b32 v0, v39, v40 offset0:32 offset1:98
	ds_write2_b32 v0, v41, v91 offset0:164 offset1:230
	v_add_u32_e32 v0, 0x1400, v44
	ds_write2_b32 v0, v92, v93 offset0:40 offset1:106
	ds_write2_b32 v0, v94, v95 offset0:172 offset1:238
	v_add_u32_e32 v0, 0x1800, v44
	ds_write2_b32 v0, v96, v97 offset0:48 offset1:114
	ds_write2_b32 v0, v98, v99 offset0:180 offset1:246
	v_add_u32_e32 v0, 0x1c00, v44
	ds_write2_b32 v0, v100, v101 offset0:56 offset1:122
	ds_write2_b32 v0, v22, v20 offset0:188 offset1:254
	s_waitcnt lgkmcnt(0)
	ds_read2_b32 v[20:21], v46 offset1:33
	s_waitcnt lgkmcnt(0)
	v_cvt_pk_bf16_f32 v20, v20, v21
	ds_read2_b32 v[22:23], v46 offset0:66 offset1:99
	s_waitcnt lgkmcnt(0)
	v_cvt_pk_bf16_f32 v21, v22, v23
	ds_read2_b32 v[22:23], v46 offset0:132 offset1:165
	v_or_b32_e32 v0, s38, v45
	v_lshl_add_u64 v[24:25], v[8:9], 0, s[48:49]
	s_waitcnt lgkmcnt(0)
	v_cvt_pk_bf16_f32 v22, v22, v23
	ds_read2_b32 v[26:27], v46 offset0:198 offset1:231
	v_lshlrev_b32_e32 v0, 13, v0
	s_waitcnt lgkmcnt(0)
	v_cvt_pk_bf16_f32 v23, v26, v27
	v_lshl_add_u64 v[26:27], v[24:25], 0, v[0:1]
	global_store_dwordx4 v[26:27], v[20:23], off sc1
	ds_read2_b32 v[20:21], v46 offset0:8 offset1:41
	v_or_b32_e32 v0, s38, v47
	s_waitcnt lgkmcnt(0)
	v_cvt_pk_bf16_f32 v20, v20, v21
	ds_read2_b32 v[22:23], v46 offset0:74 offset1:107
	s_waitcnt lgkmcnt(0)
	v_cvt_pk_bf16_f32 v21, v22, v23
	ds_read2_b32 v[22:23], v46 offset0:140 offset1:173
	s_waitcnt lgkmcnt(0)
	v_cvt_pk_bf16_f32 v22, v22, v23
	ds_read2_b32 v[26:27], v46 offset0:206 offset1:239
	v_lshlrev_b32_e32 v0, 13, v0
	s_waitcnt lgkmcnt(0)
	v_cvt_pk_bf16_f32 v23, v26, v27
	v_lshl_add_u64 v[26:27], v[24:25], 0, v[0:1]
	global_store_dwordx4 v[26:27], v[20:23], off sc1
	ds_read2_b32 v[20:21], v46 offset0:16 offset1:49
	v_or_b32_e32 v0, s38, v48
	s_waitcnt lgkmcnt(0)
	v_cvt_pk_bf16_f32 v20, v20, v21
	ds_read2_b32 v[22:23], v46 offset0:82 offset1:115
	s_waitcnt lgkmcnt(0)
	v_cvt_pk_bf16_f32 v21, v22, v23
	ds_read2_b32 v[22:23], v46 offset0:148 offset1:181
	s_waitcnt lgkmcnt(0)
	v_cvt_pk_bf16_f32 v22, v22, v23
	ds_read2_b32 v[26:27], v46 offset0:214 offset1:247
	v_lshlrev_b32_e32 v0, 13, v0
	s_waitcnt lgkmcnt(0)
	v_cvt_pk_bf16_f32 v23, v26, v27
	v_lshl_add_u64 v[26:27], v[24:25], 0, v[0:1]
	global_store_dwordx4 v[26:27], v[20:23], off sc1
	ds_read2_b32 v[20:21], v46 offset0:24 offset1:57
	v_or_b32_e32 v0, s38, v49
	s_waitcnt lgkmcnt(0)
	v_cvt_pk_bf16_f32 v20, v20, v21
	ds_read2_b32 v[22:23], v46 offset0:90 offset1:123
	v_lshlrev_b32_e32 v0, 13, v0
	s_waitcnt lgkmcnt(0)
	v_cvt_pk_bf16_f32 v21, v22, v23
	ds_read2_b32 v[22:23], v46 offset0:156 offset1:189
	v_lshl_add_u64 v[24:25], v[24:25], 0, v[0:1]
	s_waitcnt lgkmcnt(0)
	v_cvt_pk_bf16_f32 v22, v22, v23
	ds_read2_b32 v[26:27], v46 offset0:222 offset1:255
	s_waitcnt lgkmcnt(0)
	v_cvt_pk_bf16_f32 v23, v26, v27
	global_store_dwordx4 v[24:25], v[20:23], off sc1
	s_waitcnt lgkmcnt(0)

; __device__ __forceinline__ void wconv_item(const float* W, int K, int Norig, int Nphys, bf16_t* WT, const float* gA, const float* gB, int split, int mapid, LAS float* scr, int item, int lane) {
;     const int nblk = Nphys / 32, kb = item / nblk, nb = item % nblk, k0 = 64 * kb, n0 = 32 * nb;
;     const int norig = colmap(mapid, n0 + (lane & 31));
;     float wv[32];
; #pragma unroll
;     for (int i = 0; i < 32; ++i) { const int k = k0 + 2 * i + (lane >> 5); wv[i] = (norig >= 0) ? W[(size_t)k * Norig + norig] : 0.f; }
; #pragma unroll
;     for (int i = 0; i < 32; ++i) { const int kk = 2 * i + (lane >> 5), k = k0 + kk;
;         float v = wv[i];
;         if (gA) v *= (k < split ? gA[k] : gB[k - split]);
;         scr[kk * 33 + (lane & 31)] = v; }
.LBB0_1092:
	s_andn2_b64 vcc, exec, s[38:39]
	s_cbranch_vccnz .LBB0_1106
	s_add_i32 s4, s75, 0xfffff870
	s_lshr_b32 s4, s4, 1
	s_and_b32 s48, s4, 0x7fc0
	s_add_i32 s4, s82, 0xffff0e00
	s_and_b32 s72, s4, 0xfe0
	v_or_b32_e32 v0, s72, v42
	v_or_b32_e32 v38, s48, v2
	v_lshlrev_b32_e32 v0, 2, v0
	v_lshl_add_u64 v[20:21], s[60:61], 0, v[0:1]
	v_lshlrev_b32_e32 v0, 14, v38
	v_lshl_add_u64 v[36:37], v[20:21], 0, v[0:1]
	v_add_co_u32_e32 v20, vcc, 0x8000, v36
	s_mov_b32 s4, 0x10000
	s_nop 0
	v_addc_co_u32_e32 v21, vcc, 0, v37, vcc
	global_load_dword v100, v[36:37], off nt
	global_load_dword v101, v[20:21], off nt
	v_add_co_u32_e32 v20, vcc, s4, v36
	s_mov_b32 s4, 0x18000
	s_nop 0
	v_addc_co_u32_e32 v21, vcc, 0, v37, vcc
	global_load_dword v102, v[20:21], off nt
	v_add_co_u32_e32 v20, vcc, s4, v36
	s_mov_b32 s4, 0x30000
	s_nop 0
	v_addc_co_u32_e32 v21, vcc, 0, v37, vcc
	global_load_dword v103, v[20:21], off nt
	v_add_co_u32_e32 v20, vcc, 0x20000, v36
	v_add_lshl_u32 v104, s48, v2, 2
	s_nop 0
	v_addc_co_u32_e32 v21, vcc, 0, v37, vcc
	global_load_dword v32, v[20:21], off nt
	v_add_co_u32_e32 v20, vcc, 0x28000, v36
	s_nop 1
	v_addc_co_u32_e32 v21, vcc, 0, v37, vcc
	global_load_dword v33, v[20:21], off nt
	v_add_co_u32_e32 v20, vcc, s4, v36
	s_nop 1
	v_addc_co_u32_e32 v21, vcc, 0, v37, vcc
	global_load_dword v34, v[20:21], off nt
	v_add_co_u32_e32 v20, vcc, 0x38000, v36
	s_nop 1
	v_addc_co_u32_e32 v21, vcc, 0, v37, vcc
	global_load_dword v35, v[20:21], off nt
	v_add_co_u32_e32 v20, vcc, 0x40000, v36
	s_nop 1
	v_addc_co_u32_e32 v21, vcc, 0, v37, vcc
	global_load_dword v96, v[20:21], off nt
	v_add_co_u32_e32 v20, vcc, 0x48000, v36
	s_nop 1
	v_addc_co_u32_e32 v21, vcc, 0, v37, vcc
	global_load_dword v97, v[20:21], off nt
	v_add_co_u32_e32 v20, vcc, 0x50000, v36
	s_nop 1
	v_addc_co_u32_e32 v21, vcc, 0, v37, vcc
	global_load_dword v98, v[20:21], off nt
	v_add_co_u32_e32 v20, vcc, 0x58000, v36
	s_nop 1
	v_addc_co_u32_e32 v21, vcc, 0, v37, vcc
	global_load_dword v99, v[20:21], off nt
	v_add_co_u32_e32 v20, vcc, 0x60000, v36
	s_nop 1
	v_addc_co_u32_e32 v21, vcc, 0, v37, vcc
	global_load_dword v28, v[20:21], off nt
	v_add_co_u32_e32 v20, vcc, 0x68000, v36
	s_nop 1
	v_addc_co_u32_e32 v21, vcc, 0, v37, vcc
	global_load_dword v29, v[20:21], off nt
	v_add_co_u32_e32 v20, vcc, 0x70000, v36
	s_nop 1
	v_addc_co_u32_e32 v21, vcc, 0, v37, vcc
	global_load_dword v30, v[20:21], off nt
	v_add_co_u32_e32 v20, vcc, 0x78000, v36
	s_nop 1
	v_addc_co_u32_e32 v21, vcc, 0, v37, vcc
	global_load_dword v31, v[20:21], off nt
	v_add_co_u32_e32 v20, vcc, 0x80000, v36
	s_nop 1
	v_addc_co_u32_e32 v21, vcc, 0, v37, vcc
	global_load_dword v92, v[20:21], off nt
	v_add_co_u32_e32 v20, vcc, 0x88000, v36
	s_nop 1
	v_addc_co_u32_e32 v21, vcc, 0, v37, vcc
	global_load_dword v93, v[20:21], off nt
	v_add_co_u32_e32 v20, vcc, 0x90000, v36
	s_nop 1
	v_addc_co_u32_e32 v21, vcc, 0, v37, vcc
	global_load_dword v94, v[20:21], off nt
	v_add_co_u32_e32 v20, vcc, 0x98000, v36
	s_nop 1
	v_addc_co_u32_e32 v21, vcc, 0, v37, vcc
	global_load_dword v95, v[20:21], off nt
	v_add_co_u32_e32 v20, vcc, 0xa0000, v36
	s_nop 1
	v_addc_co_u32_e32 v21, vcc, 0, v37, vcc
	global_load_dword v24, v[20:21], off nt
	v_add_co_u32_e32 v20, vcc, 0xa8000, v36
	s_nop 1
	v_addc_co_u32_e32 v21, vcc, 0, v37, vcc
	global_load_dword v25, v[20:21], off nt
	v_add_co_u32_e32 v20, vcc, 0xb0000, v36
	s_nop 1
	v_addc_co_u32_e32 v21, vcc, 0, v37, vcc
	global_load_dword v26, v[20:21], off nt
	v_add_co_u32_e32 v20, vcc, 0xb8000, v36
	s_nop 1
	v_addc_co_u32_e32 v21, vcc, 0, v37, vcc
	global_load_dword v27, v[20:21], off nt
	v_add_co_u32_e32 v20, vcc, 0xc0000, v36
	s_nop 1
	v_addc_co_u32_e32 v21, vcc, 0, v37, vcc
	global_load_dword v0, v[20:21], off nt
	v_add_co_u32_e32 v20, vcc, 0xc8000, v36
	s_nop 1
	v_addc_co_u32_e32 v21, vcc, 0, v37, vcc
	global_load_dword v40, v[20:21], off nt
	v_add_co_u32_e32 v20, vcc, 0xd0000, v36
	s_nop 1
	v_addc_co_u32_e32 v21, vcc, 0, v37, vcc
	global_load_dword v41, v[20:21], off nt
	v_add_co_u32_e32 v20, vcc, 0xd8000, v36
	s_nop 1
	v_addc_co_u32_e32 v21, vcc, 0, v37, vcc
	global_load_dword v91, v[20:21], off nt
	v_add_co_u32_e32 v20, vcc, 0xe0000, v36
	s_nop 1
	v_addc_co_u32_e32 v21, vcc, 0, v37, vcc
	v_add_co_u32_e32 v22, vcc, 0xe8000, v36
	global_load_dword v20, v[20:21], off nt
	s_nop 0
	v_addc_co_u32_e32 v23, vcc, 0, v37, vcc
	global_load_dword v21, v[22:23], off nt
	v_add_co_u32_e32 v22, vcc, 0xf0000, v36
	s_nop 1
	v_addc_co_u32_e32 v23, vcc, 0, v37, vcc
	v_add_co_u32_e32 v36, vcc, 0xf8000, v36
	global_load_dword v22, v[22:23], off nt
	s_nop 0
	v_addc_co_u32_e32 v37, vcc, 0, v37, vcc
	global_load_dword v23, v[36:37], off nt
	v_cndmask_b32_e64 v36, 0, 1, s[58:59]
	v_cmp_ne_u32_e64 s[38:39], 1, v36
	s_andn2_b64 vcc, exec, s[58:59]
	s_cbranch_vccnz .LBB0_1260
	v_lshlrev_b32_e32 v36, 2, v38
	global_load_dword v36, v36, s[56:57]
	s_nop 0
	global_load_dword v37, v104, s[56:57] offset:8
	global_load_dword v38, v104, s[56:57] offset:16
	global_load_dword v39, v104, s[56:57] offset:24
	s_waitcnt vmcnt(0)
	v_mul_f32_e32 v36, v100, v36
	ds_write_b32 v44, v36
	v_mul_f32_e32 v37, v101, v37
	v_mul_f32_e32 v38, v102, v38
	v_add_u32_e32 v36, v43, v51
	v_mul_f32_e32 v39, v103, v39
	ds_write2_b32 v36, v37, v38 offset1:66
	ds_write_b32 v36, v39 offset:528
	global_load_dword v36, v104, s[56:57] offset:32
	global_load_dword v37, v104, s[56:57] offset:40
	global_load_dword v38, v104, s[56:57] offset:48
	global_load_dword v39, v104, s[56:57] offset:56
	s_waitcnt vmcnt(2)
	v_pk_mul_f32 v[36:37], v[32:33], v[36:37]
	s_waitcnt vmcnt(0)
	v_pk_mul_f32 v[38:39], v[34:35], v[38:39]
	s_cbranch_execnz .LBB0_1096

; __device__ __forceinline__ void wconv_item(const float* W, int K, int Norig, int Nphys, bf16_t* WT, const float* gA, const float* gB, int split, int mapid, LAS float* scr, int item, int lane) {
;     const int nblk = Nphys / 32, kb = item / nblk, nb = item % nblk, k0 = 64 * kb, n0 = 32 * nb;
;     const int norig = colmap(mapid, n0 + (lane & 31));
;     float wv[32];
; #pragma unroll
;     for (int i = 0; i < 32; ++i) { const int k = k0 + 2 * i + (lane >> 5); wv[i] = (norig >= 0) ? W[(size_t)k * Norig + norig] : 0.f; }
; #pragma unroll
.LBB0_1107:
	s_andn2_b64 vcc, exec, s[38:39]
	s_cbranch_vccnz .LBB0_1121
	s_add_i32 s4, s84, 0x2800
	s_and_b32 s48, s4, 0x1ffc0
	s_add_i32 s4, s82, 0xffff4e00
	s_and_b32 s72, s4, 0x3e0
	v_or_b32_e32 v0, s72, v42
	v_or_b32_e32 v38, s48, v2
	v_lshlrev_b32_e32 v0, 2, v0
	v_lshl_add_u64 v[20:21], s[86:87], 0, v[0:1]
	v_lshlrev_b32_e32 v0, 12, v38
	v_lshl_add_u64 v[32:33], v[20:21], 0, v[0:1]
	v_add_co_u32_e32 v20, vcc, 0x2000, v32
	global_load_dword v103, v[32:33], off nt
	s_nop 0
	v_addc_co_u32_e32 v21, vcc, 0, v33, vcc
	global_load_dword v104, v[20:21], off nt
	v_add_co_u32_e32 v20, vcc, 0x4000, v32
	s_mov_b32 s4, 0x10000
	s_nop 0
	v_addc_co_u32_e32 v21, vcc, 0, v33, vcc
	global_load_dword v105, v[20:21], off nt
	v_add_co_u32_e32 v20, vcc, 0x6000, v32
	v_cndmask_b32_e64 v0, 0, 1, s[52:53]
	s_nop 0
	v_addc_co_u32_e32 v21, vcc, 0, v33, vcc
	global_load_dword v106, v[20:21], off nt
	v_add_co_u32_e32 v20, vcc, 0x8000, v32
	v_cmp_ne_u32_e64 s[38:39], 1, v0
	s_nop 0
	v_addc_co_u32_e32 v21, vcc, 0, v33, vcc
	global_load_dword v34, v[20:21], off nt
	v_add_co_u32_e32 v20, vcc, 0xa000, v32
	s_nop 1
	v_addc_co_u32_e32 v21, vcc, 0, v33, vcc
	global_load_dword v35, v[20:21], off nt
	v_add_co_u32_e32 v20, vcc, 0xc000, v32
	s_nop 1
	v_addc_co_u32_e32 v21, vcc, 0, v33, vcc
	global_load_dword v36, v[20:21], off nt
	v_add_co_u32_e32 v20, vcc, 0xe000, v32
	s_nop 1
	v_addc_co_u32_e32 v21, vcc, 0, v33, vcc
	global_load_dword v37, v[20:21], off nt
	v_add_co_u32_e32 v20, vcc, s4, v32
	s_mov_b32 s4, 0x12000
	s_nop 0
	v_addc_co_u32_e32 v21, vcc, 0, v33, vcc
	global_load_dword v99, v[20:21], off nt
	v_add_co_u32_e32 v20, vcc, s4, v32
	s_mov_b32 s4, 0x14000
	s_nop 0
	v_addc_co_u32_e32 v21, vcc, 0, v33, vcc
	global_load_dword v100, v[20:21], off nt
	v_add_co_u32_e32 v20, vcc, s4, v32
	s_mov_b32 s4, 0x16000
	s_nop 0
	v_addc_co_u32_e32 v21, vcc, 0, v33, vcc
	global_load_dword v101, v[20:21], off nt
	v_add_co_u32_e32 v20, vcc, s4, v32
	s_mov_b32 s4, 0x18000
	s_nop 0
	v_addc_co_u32_e32 v21, vcc, 0, v33, vcc
	global_load_dword v102, v[20:21], off nt
	v_add_co_u32_e32 v20, vcc, s4, v32
	s_mov_b32 s4, 0x1a000
	s_nop 0
	v_addc_co_u32_e32 v21, vcc, 0, v33, vcc
	global_load_dword v28, v[20:21], off nt
	v_add_co_u32_e32 v20, vcc, s4, v32
	s_mov_b32 s4, 0x1c000
	s_nop 0
	v_addc_co_u32_e32 v21, vcc, 0, v33, vcc
	global_load_dword v29, v[20:21], off nt
	v_add_co_u32_e32 v20, vcc, s4, v32
	s_mov_b32 s4, 0x1e000
	s_nop 0
	v_addc_co_u32_e32 v21, vcc, 0, v33, vcc
	global_load_dword v30, v[20:21], off nt
	v_add_co_u32_e32 v20, vcc, s4, v32
	s_mov_b32 s4, 0x20000
	s_nop 0
	v_addc_co_u32_e32 v21, vcc, 0, v33, vcc
	global_load_dword v31, v[20:21], off nt
	v_add_co_u32_e32 v20, vcc, s4, v32
	s_mov_b32 s4, 0x22000
	s_nop 0
	v_addc_co_u32_e32 v21, vcc, 0, v33, vcc
	global_load_dword v95, v[20:21], off nt
	v_add_co_u32_e32 v20, vcc, s4, v32
	s_mov_b32 s4, 0x24000
	s_nop 0
	v_addc_co_u32_e32 v21, vcc, 0, v33, vcc
	global_load_dword v96, v[20:21], off nt
	v_add_co_u32_e32 v20, vcc, s4, v32
	s_mov_b32 s4, 0x26000
	s_nop 0
	v_addc_co_u32_e32 v21, vcc, 0, v33, vcc
	global_load_dword v97, v[20:21], off nt
	v_add_co_u32_e32 v20, vcc, s4, v32
	s_mov_b32 s4, 0x28000
	s_nop 0
	v_addc_co_u32_e32 v21, vcc, 0, v33, vcc
	global_load_dword v98, v[20:21], off nt
	v_add_co_u32_e32 v20, vcc, s4, v32
	s_mov_b32 s4, 0x2a000
	s_nop 0
	v_addc_co_u32_e32 v21, vcc, 0, v33, vcc
	global_load_dword v24, v[20:21], off nt
	v_add_co_u32_e32 v20, vcc, s4, v32
	s_mov_b32 s4, 0x2c000
	s_nop 0
	v_addc_co_u32_e32 v21, vcc, 0, v33, vcc
	global_load_dword v25, v[20:21], off nt
	v_add_co_u32_e32 v20, vcc, s4, v32
	s_mov_b32 s4, 0x2e000
	s_nop 0
	v_addc_co_u32_e32 v21, vcc, 0, v33, vcc
	global_load_dword v26, v[20:21], off nt
	v_add_co_u32_e32 v20, vcc, s4, v32
	s_mov_b32 s4, 0x30000
	s_nop 0
	v_addc_co_u32_e32 v21, vcc, 0, v33, vcc
	global_load_dword v27, v[20:21], off nt
	v_add_co_u32_e32 v20, vcc, s4, v32
	s_mov_b32 s4, 0x32000
	s_nop 0
	v_addc_co_u32_e32 v21, vcc, 0, v33, vcc
	global_load_dword v91, v[20:21], off nt
	v_add_co_u32_e32 v20, vcc, s4, v32
	s_mov_b32 s4, 0x34000
	s_nop 0
	v_addc_co_u32_e32 v21, vcc, 0, v33, vcc
	global_load_dword v92, v[20:21], off nt
	v_add_co_u32_e32 v20, vcc, s4, v32
	s_mov_b32 s4, 0x36000
	s_nop 0
	v_addc_co_u32_e32 v21, vcc, 0, v33, vcc
	global_load_dword v93, v[20:21], off nt
	v_add_co_u32_e32 v20, vcc, s4, v32
	s_mov_b32 s4, 0x38000
	s_nop 0
	v_addc_co_u32_e32 v21, vcc, 0, v33, vcc
	global_load_dword v94, v[20:21], off nt
	v_add_co_u32_e32 v20, vcc, s4, v32
	s_nop 1
	v_addc_co_u32_e32 v21, vcc, 0, v33, vcc
	v_add_co_u32_e32 v22, vcc, 0x3a000, v32
	global_load_dword v20, v[20:21], off nt
	s_nop 0
	v_addc_co_u32_e32 v23, vcc, 0, v33, vcc
	global_load_dword v21, v[22:23], off nt
	v_add_co_u32_e32 v22, vcc, 0x3c000, v32
	s_nop 1
	v_addc_co_u32_e32 v23, vcc, 0, v33, vcc
	v_add_co_u32_e32 v32, vcc, 0x3e000, v32
	global_load_dword v22, v[22:23], off nt
	s_nop 0
	v_addc_co_u32_e32 v33, vcc, 0, v33, vcc
	global_load_dword v23, v[32:33], off nt
	s_andn2_b64 vcc, exec, s[52:53]
	v_add_lshl_u32 v32, s48, v2, 2
	s_cbranch_vccnz .LBB0_1256
; __device__ __forceinline__ void wconv_item(const float* W, int K, int Norig, int Nphys, bf16_t* WT, const float* gA, const float* gB, int split, int mapid, LAS float* scr, int item, int lane) {
;     ...
;     for (int i = 0; i < 32; ++i) { const int kk = 2 * i + (lane >> 5), k = k0 + kk;
;         float v = wv[i];
;         if (gA) v *= (k < split ? gA[k] : gB[k - split]);
;         scr[kk * 33 + (lane & 31)] = v; }
	v_lshlrev_b32_e32 v0, 2, v38
	s_movk_i32 s64, 0xf800
	s_cmpk_lt_u32 s48, 0x200
	v_lshl_add_u64 v[40:41], s[54:55], 0, v[0:1]
	s_mov_b32 s65, -1
	s_cselect_b64 vcc, -1, 0
	v_lshl_add_u64 v[38:39], s[70:71], 0, v[0:1]
	v_lshl_add_u64 v[40:41], v[40:41], 0, s[64:65]
	v_mov_b32_e32 v33, v1
	s_movk_i32 s64, 0xf808
	v_cndmask_b32_e32 v39, v41, v39, vcc
	v_cndmask_b32_e32 v38, v40, v38, vcc
	v_lshl_add_u64 v[40:41], s[70:71], 0, v[32:33]
	v_lshl_add_u64 v[108:109], s[54:55], 0, v[32:33]
	s_mov_b32 s65, -1
	global_load_dword v0, v[38:39], off nt
	v_lshl_add_u64 v[38:39], v[40:41], 0, 8
	v_lshl_add_u64 v[110:111], v[108:109], 0, s[64:65]
	s_movk_i32 s64, 0xf810
	v_cndmask_b32_e32 v39, v111, v39, vcc
	v_cndmask_b32_e32 v38, v110, v38, vcc
	s_mov_b32 s65, -1
	global_load_dword v33, v[38:39], off nt
	v_lshl_add_u64 v[38:39], v[40:41], 0, 16
	v_lshl_add_u64 v[110:111], v[108:109], 0, s[64:65]
	v_cndmask_b32_e32 v39, v111, v39, vcc
	v_cndmask_b32_e32 v38, v110, v38, vcc
	global_load_dword v38, v[38:39], off nt
	s_movk_i32 s64, 0xf818
	s_mov_b32 s65, -1
	v_lshl_add_u64 v[110:111], v[108:109], 0, s[64:65]
	s_movk_i32 s64, 0xf820
	s_mov_b32 s65, -1
	s_waitcnt vmcnt(0)
	v_mul_f32_e32 v0, v103, v0
	ds_write_b32 v44, v0
	v_add_u32_e32 v0, v43, v51
	v_mul_f32_e32 v33, v104, v33
	v_mul_f32_e32 v107, v105, v38
	v_lshl_add_u64 v[38:39], v[40:41], 0, 24
	v_cndmask_b32_e32 v39, v111, v39, vcc
	v_cndmask_b32_e32 v38, v110, v38, vcc
	global_load_dword v38, v[38:39], off nt
	v_lshl_add_u64 v[110:111], v[108:109], 0, s[64:65]
	s_movk_i32 s64, 0xf828
	s_mov_b32 s65, -1
	v_lshl_add_u64 v[112:113], v[108:109], 0, s[64:65]
	s_movk_i32 s64, 0xf830
	s_mov_b32 s65, -1
	s_waitcnt vmcnt(0)
	v_mul_f32_e32 v38, v106, v38
	ds_write2_b32 v0, v33, v107 offset1:66
	ds_write_b32 v0, v38 offset:528
	v_lshl_add_u64 v[38:39], v[40:41], 0, 32
	v_cndmask_b32_e32 v39, v111, v39, vcc
	v_cndmask_b32_e32 v38, v110, v38, vcc
	v_lshl_add_u64 v[110:111], v[40:41], 0, 40
	v_cndmask_b32_e32 v111, v113, v111, vcc
	v_cndmask_b32_e32 v110, v112, v110, vcc
	v_lshl_add_u64 v[112:113], v[108:109], 0, s[64:65]
	s_movk_i32 s64, 0xf838
	s_mov_b32 s65, -1
	global_load_dword v38, v[38:39], off nt
	v_lshl_add_u64 v[108:109], v[108:109], 0, s[64:65]
	global_load_dword v39, v[110:111], off nt
	v_lshl_add_u64 v[110:111], v[40:41], 0, 48
	v_lshl_add_u64 v[40:41], v[40:41], 0, 56
	v_cndmask_b32_e32 v111, v113, v111, vcc
	v_cndmask_b32_e32 v110, v112, v110, vcc
	v_cndmask_b32_e32 v41, v109, v41, vcc
	v_cndmask_b32_e32 v40, v108, v40, vcc
	global_load_dword v110, v[110:111], off nt
	s_nop 0
	global_load_dword v111, v[40:41], off nt
	s_waitcnt vmcnt(2)
	v_pk_mul_f32 v[38:39], v[34:35], v[38:39]
	s_waitcnt vmcnt(0)
	v_pk_mul_f32 v[40:41], v[36:37], v[110:111]
	s_cbranch_execnz .LBB0_1111

; __device__ __forceinline__ void wconv_item(const float* W, int K, int Norig, int Nphys, bf16_t* WT, const float* gA, const float* gB, int split, int mapid, LAS float* scr, int item, int lane) {
;     ...
;     for (int i = 0; i < 32; ++i) { const int kk = 2 * i + (lane >> 5), k = k0 + kk;
;         float v = wv[i];
;         if (gA) v *= (k < split ? gA[k] : gB[k - split]);
;         scr[kk * 33 + (lane & 31)] = v; }
.LBB0_1111:
	v_add_u32_e32 v0, v43, v55
	s_and_b64 vcc, exec, s[38:39]
	ds_write2_b32 v0, v38, v39 offset1:66
	ds_write2_b32 v0, v40, v41 offset0:132 offset1:198
	s_cbranch_vccnz .LBB0_1257
	v_mov_b32_e32 v33, v1
	s_movk_i32 s64, 0xf840
	s_cmpk_lt_u32 s48, 0x200
	s_waitcnt vmcnt(0)
	v_lshl_add_u64 v[36:37], s[70:71], 0, v[32:33]
	v_lshl_add_u64 v[38:39], s[54:55], 0, v[32:33]
	s_mov_b32 s65, -1
	s_cselect_b64 vcc, -1, 0
	v_lshl_add_u64 v[34:35], v[36:37], 0, 64
	v_lshl_add_u64 v[40:41], v[38:39], 0, s[64:65]
	v_cndmask_b32_e32 v35, v41, v35, vcc
	v_cndmask_b32_e32 v34, v40, v34, vcc
	s_mov_b64 s[64:65], 0x48
	global_load_dword v0, v[34:35], off nt
	v_lshl_add_u64 v[34:35], v[36:37], 0, s[64:65]
	s_movk_i32 s64, 0xf848
	s_mov_b32 s65, -1
	v_lshl_add_u64 v[40:41], v[38:39], 0, s[64:65]
	v_cndmask_b32_e32 v35, v41, v35, vcc
	v_cndmask_b32_e32 v34, v40, v34, vcc
	s_mov_b64 s[64:65], 0x50
	global_load_dword v33, v[34:35], off nt
	v_lshl_add_u64 v[34:35], v[36:37], 0, s[64:65]
	s_movk_i32 s64, 0xf850
	s_mov_b32 s65, -1
	v_lshl_add_u64 v[40:41], v[38:39], 0, s[64:65]
	v_cndmask_b32_e32 v35, v41, v35, vcc
	v_cndmask_b32_e32 v34, v40, v34, vcc
	global_load_dword v34, v[34:35], off nt
	s_mov_b64 s[64:65], 0x58
	s_waitcnt vmcnt(2)
	v_mul_f32_e32 v0, v99, v0
	s_waitcnt vmcnt(1)
	v_mul_f32_e32 v33, v100, v33
	s_waitcnt vmcnt(0)
	v_mul_f32_e32 v103, v101, v34
	v_lshl_add_u64 v[34:35], v[36:37], 0, s[64:65]
	s_movk_i32 s64, 0xf858
	s_mov_b32 s65, -1
	v_lshl_add_u64 v[40:41], v[38:39], 0, s[64:65]
	v_cndmask_b32_e32 v35, v41, v35, vcc
	v_cndmask_b32_e32 v34, v40, v34, vcc
	global_load_dword v34, v[34:35], off nt
	v_add_u32_e32 v35, v43, v60
	s_mov_b64 s[64:65], 0x60
	s_waitcnt vmcnt(0)
	v_mul_f32_e32 v34, v102, v34
	ds_write2_b32 v35, v0, v33 offset1:66
	ds_write2_b32 v35, v103, v34 offset0:132 offset1:198
	v_lshl_add_u64 v[34:35], v[36:37], 0, s[64:65]
	s_movk_i32 s64, 0xf860
	s_mov_b32 s65, -1
	v_lshl_add_u64 v[40:41], v[38:39], 0, s[64:65]
	s_mov_b64 s[64:65], 0x68
	v_cndmask_b32_e32 v35, v41, v35, vcc
	v_cndmask_b32_e32 v34, v40, v34, vcc
	v_lshl_add_u64 v[40:41], v[36:37], 0, s[64:65]
	s_movk_i32 s64, 0xf868
	s_mov_b32 s65, -1
	v_lshl_add_u64 v[104:105], v[38:39], 0, s[64:65]
	v_cndmask_b32_e32 v41, v105, v41, vcc
	v_cndmask_b32_e32 v40, v104, v40, vcc
	s_mov_b64 s[64:65], 0x70
	global_load_dword v34, v[34:35], off nt
	s_nop 0
	global_load_dword v35, v[40:41], off nt
	v_lshl_add_u64 v[40:41], v[36:37], 0, s[64:65]
	s_movk_i32 s64, 0xf870
	s_mov_b32 s65, -1
	v_lshl_add_u64 v[104:105], v[38:39], 0, s[64:65]
	s_mov_b64 s[64:65], 0x78
	v_lshl_add_u64 v[36:37], v[36:37], 0, s[64:65]
	s_movk_i32 s64, 0xf878
	s_mov_b32 s65, -1
	v_lshl_add_u64 v[38:39], v[38:39], 0, s[64:65]
	v_cndmask_b32_e32 v41, v105, v41, vcc
	v_cndmask_b32_e32 v40, v104, v40, vcc
	v_cndmask_b32_e32 v37, v39, v37, vcc
	v_cndmask_b32_e32 v36, v38, v36, vcc
	global_load_dword v40, v[40:41], off nt
	s_nop 0
	global_load_dword v41, v[36:37], off nt
	s_waitcnt vmcnt(2)
	v_pk_mul_f32 v[34:35], v[28:29], v[34:35]
	s_waitcnt vmcnt(0)
	v_pk_mul_f32 v[36:37], v[30:31], v[40:41]
	s_cbranch_execnz .LBB0_1114

; __device__ __forceinline__ void wconv_item(const float* W, int K, int Norig, int Nphys, bf16_t* WT, const float* gA, const float* gB, int split, int mapid, LAS float* scr, int item, int lane) {
;     ...
;     for (int i = 0; i < 32; ++i) { const int kk = 2 * i + (lane >> 5), k = k0 + kk;
;         float v = wv[i];
;         if (gA) v *= (k < split ? gA[k] : gB[k - split]);
;         scr[kk * 33 + (lane & 31)] = v; }
.LBB0_1114:
	v_add_u32_e32 v0, v43, v65
	s_and_b64 vcc, exec, s[38:39]
	s_waitcnt vmcnt(0)
	ds_write2_b32 v0, v34, v35 offset1:66
	ds_write2_b32 v0, v36, v37 offset0:132 offset1:198
	s_cbranch_vccnz .LBB0_1258
	v_mov_b32_e32 v33, v1
	s_movk_i32 s64, 0xf880
	s_cmpk_lt_u32 s48, 0x200
	v_lshl_add_u64 v[30:31], s[70:71], 0, v[32:33]
	v_lshl_add_u64 v[34:35], s[54:55], 0, v[32:33]
	s_mov_b32 s65, -1
	s_cselect_b64 vcc, -1, 0
	v_lshl_add_u64 v[28:29], v[30:31], 0, s[24:25]
	v_lshl_add_u64 v[36:37], v[34:35], 0, s[64:65]
	v_cndmask_b32_e32 v29, v37, v29, vcc
	v_cndmask_b32_e32 v28, v36, v28, vcc
	s_mov_b64 s[64:65], 0x88
	global_load_dword v0, v[28:29], off nt
	v_lshl_add_u64 v[28:29], v[30:31], 0, s[64:65]
	s_movk_i32 s64, 0xf888
	s_mov_b32 s65, -1
	v_lshl_add_u64 v[36:37], v[34:35], 0, s[64:65]
	v_cndmask_b32_e32 v29, v37, v29, vcc
	v_cndmask_b32_e32 v28, v36, v28, vcc
	global_load_dword v28, v[28:29], off nt
	s_mov_b64 s[64:65], 0x90
	s_waitcnt vmcnt(1)
	v_mul_f32_e32 v0, v95, v0
	s_waitcnt vmcnt(0)
	v_mul_f32_e32 v33, v96, v28
	v_lshl_add_u64 v[28:29], v[30:31], 0, s[64:65]
	s_movk_i32 s64, 0xf890
	s_mov_b32 s65, -1
	v_lshl_add_u64 v[36:37], v[34:35], 0, s[64:65]
	v_cndmask_b32_e32 v29, v37, v29, vcc
	v_cndmask_b32_e32 v28, v36, v28, vcc
	global_load_dword v28, v[28:29], off nt
	s_mov_b64 s[64:65], 0x98
	s_waitcnt vmcnt(0)
	v_mul_f32_e32 v38, v97, v28
	v_lshl_add_u64 v[28:29], v[30:31], 0, s[64:65]
	s_movk_i32 s64, 0xf898
	s_mov_b32 s65, -1
	v_lshl_add_u64 v[36:37], v[34:35], 0, s[64:65]
	v_cndmask_b32_e32 v29, v37, v29, vcc
	v_cndmask_b32_e32 v28, v36, v28, vcc
	global_load_dword v28, v[28:29], off nt
	v_add_u32_e32 v29, v43, v70
	s_mov_b64 s[64:65], 0xa0
	s_waitcnt vmcnt(0)
	v_mul_f32_e32 v28, v98, v28
	ds_write2_b32 v29, v0, v33 offset1:66
	ds_write2_b32 v29, v38, v28 offset0:132 offset1:198
	v_lshl_add_u64 v[28:29], v[30:31], 0, s[64:65]
	s_movk_i32 s64, 0xf8a0
	s_mov_b32 s65, -1
	v_lshl_add_u64 v[36:37], v[34:35], 0, s[64:65]
	s_mov_b64 s[64:65], 0xa8
	v_cndmask_b32_e32 v29, v37, v29, vcc
	v_cndmask_b32_e32 v28, v36, v28, vcc
	v_lshl_add_u64 v[36:37], v[30:31], 0, s[64:65]
	s_movk_i32 s64, 0xf8a8
	s_mov_b32 s65, -1
	v_lshl_add_u64 v[38:39], v[34:35], 0, s[64:65]
	v_cndmask_b32_e32 v37, v39, v37, vcc
	v_cndmask_b32_e32 v36, v38, v36, vcc
	s_mov_b64 s[64:65], 0xb0
	global_load_dword v28, v[28:29], off nt
	s_nop 0
	global_load_dword v29, v[36:37], off nt
	v_lshl_add_u64 v[36:37], v[30:31], 0, s[64:65]
	s_movk_i32 s64, 0xf8b0
	s_mov_b32 s65, -1
	v_lshl_add_u64 v[38:39], v[34:35], 0, s[64:65]
	s_mov_b64 s[64:65], 0xb8
	v_lshl_add_u64 v[30:31], v[30:31], 0, s[64:65]
	s_movk_i32 s64, 0xf8b8
	s_mov_b32 s65, -1
	v_lshl_add_u64 v[34:35], v[34:35], 0, s[64:65]
	v_cndmask_b32_e32 v37, v39, v37, vcc
	v_cndmask_b32_e32 v36, v38, v36, vcc
	v_cndmask_b32_e32 v31, v35, v31, vcc
	v_cndmask_b32_e32 v30, v34, v30, vcc
	global_load_dword v36, v[36:37], off nt
	s_nop 0
	global_load_dword v37, v[30:31], off nt
	s_waitcnt vmcnt(2)
	v_pk_mul_f32 v[28:29], v[24:25], v[28:29]
	s_waitcnt vmcnt(0)
	v_pk_mul_f32 v[30:31], v[26:27], v[36:37]
	s_cbranch_execnz .LBB0_1117

; __device__ __forceinline__ void wconv_item(const float* W, int K, int Norig, int Nphys, bf16_t* WT, const float* gA, const float* gB, int split, int mapid, LAS float* scr, int item, int lane) {
;     ...
;     for (int i = 0; i < 32; ++i) { const int kk = 2 * i + (lane >> 5), k = k0 + kk;
;         float v = wv[i];
;         if (gA) v *= (k < split ? gA[k] : gB[k - split]);
;         scr[kk * 33 + (lane & 31)] = v; }
.LBB0_1117:
	v_add_u32_e32 v0, v43, v75
	s_and_b64 vcc, exec, s[38:39]
	ds_write2_b32 v0, v28, v29 offset1:66
	ds_write2_b32 v0, v30, v31 offset0:132 offset1:198
	s_cbranch_vccnz .LBB0_1259
	v_mov_b32_e32 v33, v1
	v_lshl_add_u64 v[26:27], s[70:71], 0, v[32:33]
	s_mov_b64 s[38:39], 0xc0
	v_lshl_add_u64 v[24:25], v[26:27], 0, s[38:39]
	s_movk_i32 s38, 0xf8c0
	s_cmpk_lt_u32 s48, 0x200
	v_lshl_add_u64 v[28:29], s[54:55], 0, v[32:33]
	s_mov_b32 s39, -1
	s_cselect_b64 vcc, -1, 0
	v_lshl_add_u64 v[30:31], v[28:29], 0, s[38:39]
	v_cndmask_b32_e32 v25, v31, v25, vcc
	v_cndmask_b32_e32 v24, v30, v24, vcc
	s_mov_b64 s[38:39], 0xc8
	global_load_dword v0, v[24:25], off nt
	v_lshl_add_u64 v[24:25], v[26:27], 0, s[38:39]
	s_movk_i32 s38, 0xf8c8
	s_mov_b32 s39, -1
	v_lshl_add_u64 v[30:31], v[28:29], 0, s[38:39]
	v_cndmask_b32_e32 v25, v31, v25, vcc
	v_cndmask_b32_e32 v24, v30, v24, vcc
	global_load_dword v24, v[24:25], off nt
	s_mov_b64 s[38:39], 0xd0
	s_waitcnt vmcnt(1)
	v_mul_f32_e32 v0, v91, v0
	s_waitcnt vmcnt(0)
	v_mul_f32_e32 v32, v92, v24
	v_lshl_add_u64 v[24:25], v[26:27], 0, s[38:39]
	s_movk_i32 s38, 0xf8d0
	s_mov_b32 s39, -1
	v_lshl_add_u64 v[30:31], v[28:29], 0, s[38:39]
	v_cndmask_b32_e32 v25, v31, v25, vcc
	v_cndmask_b32_e32 v24, v30, v24, vcc
	global_load_dword v24, v[24:25], off nt
	s_mov_b64 s[38:39], 0xd8
	s_waitcnt vmcnt(0)
	v_mul_f32_e32 v33, v93, v24
	v_lshl_add_u64 v[24:25], v[26:27], 0, s[38:39]
	s_movk_i32 s38, 0xf8d8
	s_mov_b32 s39, -1
	v_lshl_add_u64 v[30:31], v[28:29], 0, s[38:39]
	v_cndmask_b32_e32 v25, v31, v25, vcc
	v_cndmask_b32_e32 v24, v30, v24, vcc
	global_load_dword v24, v[24:25], off nt
	v_add_u32_e32 v25, v43, v80
	s_mov_b64 s[38:39], 0xe0
	s_waitcnt vmcnt(0)
	v_mul_f32_e32 v24, v94, v24
	ds_write2_b32 v25, v0, v32 offset1:66
	ds_write2_b32 v25, v33, v24 offset0:132 offset1:198
	v_lshl_add_u64 v[24:25], v[26:27], 0, s[38:39]
	s_movk_i32 s38, 0xf8e0
	s_mov_b32 s39, -1
	v_lshl_add_u64 v[30:31], v[28:29], 0, s[38:39]
	s_mov_b64 s[38:39], 0xe8
	v_cndmask_b32_e32 v25, v31, v25, vcc
	v_cndmask_b32_e32 v24, v30, v24, vcc
	v_lshl_add_u64 v[30:31], v[26:27], 0, s[38:39]
	s_movk_i32 s38, 0xf8e8
	s_mov_b32 s39, -1
	v_lshl_add_u64 v[32:33], v[28:29], 0, s[38:39]
	v_cndmask_b32_e32 v31, v33, v31, vcc
	v_cndmask_b32_e32 v30, v32, v30, vcc
	s_mov_b64 s[38:39], 0xf0
	global_load_dword v24, v[24:25], off nt
	s_nop 0
	global_load_dword v25, v[30:31], off nt
	v_lshl_add_u64 v[30:31], v[26:27], 0, s[38:39]
	s_movk_i32 s38, 0xf8f0
	s_mov_b32 s39, -1
	v_lshl_add_u64 v[32:33], v[28:29], 0, s[38:39]
	s_mov_b64 s[38:39], 0xf8
	v_lshl_add_u64 v[26:27], v[26:27], 0, s[38:39]
	s_movk_i32 s38, 0xf8f8
	s_mov_b32 s39, -1
	v_lshl_add_u64 v[28:29], v[28:29], 0, s[38:39]
	v_cndmask_b32_e32 v31, v33, v31, vcc
	v_cndmask_b32_e32 v30, v32, v30, vcc
	v_cndmask_b32_e32 v27, v29, v27, vcc
	v_cndmask_b32_e32 v26, v28, v26, vcc
	global_load_dword v30, v[30:31], off nt
	s_nop 0
	global_load_dword v31, v[26:27], off nt
	s_waitcnt vmcnt(2)
	v_pk_mul_f32 v[24:25], v[20:21], v[24:25]
	s_waitcnt vmcnt(0)
	v_pk_mul_f32 v[26:27], v[22:23], v[30:31]
	s_cbranch_execnz .LBB0_1120

; __device__ __forceinline__ void wconv_item(const float* W, int K, int Norig, int Nphys, bf16_t* WT, const float* gA, const float* gB, int split, int mapid, LAS float* scr, int item, int lane) {
;     const int nblk = Nphys / 32, kb = item / nblk, nb = item % nblk, k0 = 64 * kb, n0 = 32 * nb;
;     const int norig = colmap(mapid, n0 + (lane & 31));
;     float wv[32];
; #pragma unroll
;     for (int i = 0; i < 32; ++i) { const int k = k0 + 2 * i + (lane >> 5); wv[i] = (norig >= 0) ? W[(size_t)k * Norig + norig] : 0.f; }
; #pragma unroll
;     for (int i = 0; i < 32; ++i) { const int kk = 2 * i + (lane >> 5), k = k0 + kk;
;         float v = wv[i];
;         if (gA) v *= (k < split ? gA[k] : gB[k - split]);
;         scr[kk * 33 + (lane & 31)] = v; }
.LBB0_1127:
	s_add_i32 s4, s84, 0x2900
	s_and_b32 s48, s4, 0x1c0
	v_or_b32_e32 v38, s48, v2
	v_lshl_add_u64 v[20:21], v[0:1], 2, s[6:7]
	v_lshlrev_b32_e32 v0, 12, v38
	v_lshl_add_u64 v[36:37], v[20:21], 0, v[0:1]
	v_add_co_u32_e32 v20, vcc, 0x2000, v36
	global_load_dword v100, v[36:37], off nt
	s_nop 0
	v_addc_co_u32_e32 v21, vcc, 0, v37, vcc
	global_load_dword v101, v[20:21], off nt
	v_add_co_u32_e32 v20, vcc, 0x4000, v36
	s_mov_b32 s4, 0x10000
	s_nop 0
	v_addc_co_u32_e32 v21, vcc, 0, v37, vcc
	global_load_dword v102, v[20:21], off nt
	v_add_co_u32_e32 v20, vcc, 0x6000, v36
	v_add_lshl_u32 v104, s48, v2, 2
	s_nop 0
	v_addc_co_u32_e32 v21, vcc, 0, v37, vcc
	global_load_dword v103, v[20:21], off nt
	v_add_co_u32_e32 v20, vcc, 0x8000, v36
	s_nop 1
	v_addc_co_u32_e32 v21, vcc, 0, v37, vcc
	global_load_dword v32, v[20:21], off nt
	v_add_co_u32_e32 v20, vcc, 0xa000, v36
	s_nop 1
	v_addc_co_u32_e32 v21, vcc, 0, v37, vcc
	global_load_dword v33, v[20:21], off nt
	v_add_co_u32_e32 v20, vcc, 0xc000, v36
	s_nop 1
	v_addc_co_u32_e32 v21, vcc, 0, v37, vcc
	global_load_dword v34, v[20:21], off nt
	v_add_co_u32_e32 v20, vcc, 0xe000, v36
	s_nop 1
	v_addc_co_u32_e32 v21, vcc, 0, v37, vcc
	global_load_dword v35, v[20:21], off nt
	v_add_co_u32_e32 v20, vcc, s4, v36
	s_mov_b32 s4, 0x12000
	s_nop 0
	v_addc_co_u32_e32 v21, vcc, 0, v37, vcc
	global_load_dword v96, v[20:21], off nt
	v_add_co_u32_e32 v20, vcc, s4, v36
	s_mov_b32 s4, 0x14000
	s_nop 0
	v_addc_co_u32_e32 v21, vcc, 0, v37, vcc
	global_load_dword v97, v[20:21], off nt
	v_add_co_u32_e32 v20, vcc, s4, v36
	s_mov_b32 s4, 0x16000
	s_nop 0
	v_addc_co_u32_e32 v21, vcc, 0, v37, vcc
	global_load_dword v98, v[20:21], off nt
	v_add_co_u32_e32 v20, vcc, s4, v36
	s_mov_b32 s4, 0x18000
	s_nop 0
	v_addc_co_u32_e32 v21, vcc, 0, v37, vcc
	global_load_dword v99, v[20:21], off nt
	v_add_co_u32_e32 v20, vcc, s4, v36
	s_mov_b32 s4, 0x1a000
	s_nop 0
	v_addc_co_u32_e32 v21, vcc, 0, v37, vcc
	global_load_dword v28, v[20:21], off nt
	v_add_co_u32_e32 v20, vcc, s4, v36
	s_mov_b32 s4, 0x1c000
	s_nop 0
	v_addc_co_u32_e32 v21, vcc, 0, v37, vcc
	global_load_dword v29, v[20:21], off nt
	v_add_co_u32_e32 v20, vcc, s4, v36
	s_mov_b32 s4, 0x1e000
	s_nop 0
	v_addc_co_u32_e32 v21, vcc, 0, v37, vcc
	global_load_dword v30, v[20:21], off nt
	v_add_co_u32_e32 v20, vcc, s4, v36
	s_mov_b32 s4, 0x20000
	s_nop 0
	v_addc_co_u32_e32 v21, vcc, 0, v37, vcc
	global_load_dword v31, v[20:21], off nt
	v_add_co_u32_e32 v20, vcc, s4, v36
	s_mov_b32 s4, 0x22000
	s_nop 0
	v_addc_co_u32_e32 v21, vcc, 0, v37, vcc
	global_load_dword v92, v[20:21], off nt
	v_add_co_u32_e32 v20, vcc, s4, v36
	s_mov_b32 s4, 0x24000
	s_nop 0
	v_addc_co_u32_e32 v21, vcc, 0, v37, vcc
	global_load_dword v93, v[20:21], off nt
	v_add_co_u32_e32 v20, vcc, s4, v36
	s_mov_b32 s4, 0x26000
	s_nop 0
	v_addc_co_u32_e32 v21, vcc, 0, v37, vcc
	global_load_dword v94, v[20:21], off nt
	v_add_co_u32_e32 v20, vcc, s4, v36
	s_mov_b32 s4, 0x28000
	s_nop 0
	v_addc_co_u32_e32 v21, vcc, 0, v37, vcc
	global_load_dword v95, v[20:21], off nt
	v_add_co_u32_e32 v20, vcc, s4, v36
	s_mov_b32 s4, 0x2a000
	s_nop 0
	v_addc_co_u32_e32 v21, vcc, 0, v37, vcc
	global_load_dword v24, v[20:21], off nt
	v_add_co_u32_e32 v20, vcc, s4, v36
	s_mov_b32 s4, 0x2c000
	s_nop 0
	v_addc_co_u32_e32 v21, vcc, 0, v37, vcc
	global_load_dword v25, v[20:21], off nt
	v_add_co_u32_e32 v20, vcc, s4, v36
	s_mov_b32 s4, 0x2e000
	s_nop 0
	v_addc_co_u32_e32 v21, vcc, 0, v37, vcc
	global_load_dword v26, v[20:21], off nt
	v_add_co_u32_e32 v20, vcc, s4, v36
	s_mov_b32 s4, 0x30000
	s_nop 0
	v_addc_co_u32_e32 v21, vcc, 0, v37, vcc
	global_load_dword v27, v[20:21], off nt
	v_add_co_u32_e32 v20, vcc, s4, v36
	s_mov_b32 s4, 0x32000
	s_nop 0
	v_addc_co_u32_e32 v21, vcc, 0, v37, vcc
	global_load_dword v0, v[20:21], off nt
	v_add_co_u32_e32 v20, vcc, s4, v36
	s_mov_b32 s4, 0x34000
	s_nop 0
	v_addc_co_u32_e32 v21, vcc, 0, v37, vcc
	global_load_dword v40, v[20:21], off nt
	v_add_co_u32_e32 v20, vcc, s4, v36
	s_mov_b32 s4, 0x36000
	s_nop 0
	v_addc_co_u32_e32 v21, vcc, 0, v37, vcc
	global_load_dword v41, v[20:21], off nt
	v_add_co_u32_e32 v20, vcc, s4, v36
	s_mov_b32 s4, 0x38000
	s_nop 0
	v_addc_co_u32_e32 v21, vcc, 0, v37, vcc
	global_load_dword v91, v[20:21], off nt
	v_add_co_u32_e32 v20, vcc, s4, v36
	s_nop 1
	v_addc_co_u32_e32 v21, vcc, 0, v37, vcc
	v_add_co_u32_e32 v22, vcc, 0x3a000, v36
	global_load_dword v20, v[20:21], off nt
	s_nop 0
	v_addc_co_u32_e32 v23, vcc, 0, v37, vcc
	global_load_dword v21, v[22:23], off nt
	v_add_co_u32_e32 v22, vcc, 0x3c000, v36
	s_nop 1
	v_addc_co_u32_e32 v23, vcc, 0, v37, vcc
	v_add_co_u32_e32 v36, vcc, 0x3e000, v36
	global_load_dword v22, v[22:23], off nt
	s_nop 0
	v_addc_co_u32_e32 v37, vcc, 0, v37, vcc
	global_load_dword v23, v[36:37], off nt
	v_cndmask_b32_e64 v36, 0, 1, s[68:69]
	v_cmp_ne_u32_e64 s[38:39], 1, v36
	s_andn2_b64 vcc, exec, s[68:69]
	s_cbranch_vccnz .LBB0_1252
	v_lshlrev_b32_e32 v36, 2, v38
	global_load_dword v36, v36, s[0:1]
	s_nop 0
	global_load_dword v37, v104, s[0:1] offset:8
	global_load_dword v38, v104, s[0:1] offset:16
	global_load_dword v39, v104, s[0:1] offset:24
	s_waitcnt vmcnt(0)
	v_mul_f32_e32 v36, v100, v36
	ds_write_b32 v44, v36
	v_mul_f32_e32 v37, v101, v37
	v_mul_f32_e32 v38, v102, v38
	v_add_u32_e32 v36, v43, v51
	v_mul_f32_e32 v39, v103, v39
	ds_write2_b32 v36, v37, v38 offset1:66
	ds_write_b32 v36, v39 offset:528
	global_load_dword v36, v104, s[0:1] offset:32
	global_load_dword v37, v104, s[0:1] offset:40
	global_load_dword v38, v104, s[0:1] offset:48
	global_load_dword v39, v104, s[0:1] offset:56
	s_waitcnt vmcnt(2)
	v_pk_mul_f32 v[36:37], v[32:33], v[36:37]
	s_waitcnt vmcnt(0)
	v_pk_mul_f32 v[38:39], v[34:35], v[38:39]
	s_cbranch_execnz .LBB0_1130

; __device__ __forceinline__ void wconv_item(const float* W, int K, int Norig, int Nphys, bf16_t* WT, const float* gA, const float* gB, int split, int mapid, LAS float* scr, int item, int lane) {
;     const int nblk = Nphys / 32, kb = item / nblk, nb = item % nblk, k0 = 64 * kb, n0 = 32 * nb;
;     const int norig = colmap(mapid, n0 + (lane & 31));
;     float wv[32];
; #pragma unroll
;     for (int i = 0; i < 32; ++i) { const int k = k0 + 2 * i + (lane >> 5); wv[i] = (norig >= 0) ? W[(size_t)k * Norig + norig] : 0.f; }
; #pragma unroll
;     for (int i = 0; i < 32; ++i) { const int kk = 2 * i + (lane >> 5), k = k0 + kk;
;         float v = wv[i];
;         if (gA) v *= (k < split ? gA[k] : gB[k - split]);
;         scr[kk * 33 + (lane & 31)] = v; }
.LBB0_1146:
	s_and_b32 s4, 0xffff, s64
	s_lshl_b32 s72, s4, 6
	v_or_b32_e32 v38, s72, v2
	v_lshl_add_u64 v[20:21], v[0:1], 2, s[46:47]
	v_mul_u32_u24_e32 v0, 0x300, v38
	v_lshlrev_b32_e32 v0, 2, v0
	v_lshl_add_u64 v[36:37], v[20:21], 0, v[0:1]
	v_add_co_u32_e32 v20, vcc, 0x1000, v36
	s_movk_i32 s4, 0x3000
	s_nop 0
	v_addc_co_u32_e32 v21, vcc, 0, v37, vcc
	global_load_dword v101, v[20:21], off offset:2048 nt
	v_add_co_u32_e32 v20, vcc, s4, v36
	s_movk_i32 s4, 0x4000
	s_nop 0
	v_addc_co_u32_e32 v21, vcc, 0, v37, vcc
	global_load_dword v100, v[36:37], off nt
	global_load_dword v102, v[20:21], off nt
	v_add_co_u32_e32 v20, vcc, s4, v36
	s_movk_i32 s4, 0x6000
	s_nop 0
	v_addc_co_u32_e32 v21, vcc, 0, v37, vcc
	global_load_dword v103, v[20:21], off offset:2048 nt
	v_add_co_u32_e32 v20, vcc, s4, v36
	s_movk_i32 s4, 0x7000
	s_nop 0
	v_addc_co_u32_e32 v21, vcc, 0, v37, vcc
	global_load_dword v32, v[20:21], off nt
	v_add_co_u32_e32 v20, vcc, s4, v36
	s_mov_b32 s4, 0x9000
	s_nop 0
	v_addc_co_u32_e32 v21, vcc, 0, v37, vcc
	global_load_dword v33, v[20:21], off offset:2048 nt
	v_add_co_u32_e32 v20, vcc, s4, v36
	s_mov_b32 s4, 0xa000
	s_nop 0
	v_addc_co_u32_e32 v21, vcc, 0, v37, vcc
	global_load_dword v34, v[20:21], off nt
	v_add_co_u32_e32 v20, vcc, s4, v36
	s_mov_b32 s4, 0xc000
	s_nop 0
	v_addc_co_u32_e32 v21, vcc, 0, v37, vcc
	global_load_dword v35, v[20:21], off offset:2048 nt
	v_add_co_u32_e32 v20, vcc, s4, v36
	s_mov_b32 s4, 0xd000
	s_nop 0
	v_addc_co_u32_e32 v21, vcc, 0, v37, vcc
	global_load_dword v96, v[20:21], off nt
	v_add_co_u32_e32 v20, vcc, s4, v36
	s_mov_b32 s4, 0xf000
	s_nop 0
	v_addc_co_u32_e32 v21, vcc, 0, v37, vcc
	global_load_dword v97, v[20:21], off offset:2048 nt
	v_add_co_u32_e32 v20, vcc, s4, v36
	s_mov_b32 s4, 0x10000
	s_nop 0
	v_addc_co_u32_e32 v21, vcc, 0, v37, vcc
	global_load_dword v98, v[20:21], off nt
	v_add_co_u32_e32 v20, vcc, s4, v36
	s_mov_b32 s4, 0x12000
	s_nop 0
	v_addc_co_u32_e32 v21, vcc, 0, v37, vcc
	global_load_dword v99, v[20:21], off offset:2048 nt
	v_add_co_u32_e32 v20, vcc, s4, v36
	s_mov_b32 s4, 0x13000
	s_nop 0
	v_addc_co_u32_e32 v21, vcc, 0, v37, vcc
	global_load_dword v28, v[20:21], off nt
	v_add_co_u32_e32 v20, vcc, s4, v36
	s_mov_b32 s4, 0x15000
	s_nop 0
	v_addc_co_u32_e32 v21, vcc, 0, v37, vcc
	global_load_dword v29, v[20:21], off offset:2048 nt
	v_add_co_u32_e32 v20, vcc, s4, v36
	s_mov_b32 s4, 0x16000
	s_nop 0
	v_addc_co_u32_e32 v21, vcc, 0, v37, vcc
	global_load_dword v30, v[20:21], off nt
	v_add_co_u32_e32 v20, vcc, s4, v36
	s_mov_b32 s4, 0x18000
	s_nop 0
	v_addc_co_u32_e32 v21, vcc, 0, v37, vcc
	global_load_dword v31, v[20:21], off offset:2048 nt
	v_add_co_u32_e32 v20, vcc, s4, v36
	s_mov_b32 s4, 0x19000
	s_nop 0
	v_addc_co_u32_e32 v21, vcc, 0, v37, vcc
	global_load_dword v92, v[20:21], off nt
	v_add_co_u32_e32 v20, vcc, s4, v36
	s_mov_b32 s4, 0x1b000
	s_nop 0
	v_addc_co_u32_e32 v21, vcc, 0, v37, vcc
	global_load_dword v93, v[20:21], off offset:2048 nt
	v_add_co_u32_e32 v20, vcc, s4, v36
	s_mov_b32 s4, 0x1c000
	s_nop 0
	v_addc_co_u32_e32 v21, vcc, 0, v37, vcc
	global_load_dword v94, v[20:21], off nt
	v_add_co_u32_e32 v20, vcc, s4, v36
	s_mov_b32 s4, 0x1e000
	s_nop 0
	v_addc_co_u32_e32 v21, vcc, 0, v37, vcc
	global_load_dword v95, v[20:21], off offset:2048 nt
	v_add_co_u32_e32 v20, vcc, s4, v36
	s_mov_b32 s4, 0x1f000
	s_nop 0
	v_addc_co_u32_e32 v21, vcc, 0, v37, vcc
	global_load_dword v24, v[20:21], off nt
	v_add_co_u32_e32 v20, vcc, s4, v36
	s_mov_b32 s4, 0x21000
	s_nop 0
	v_addc_co_u32_e32 v21, vcc, 0, v37, vcc
	global_load_dword v25, v[20:21], off offset:2048 nt
	v_add_co_u32_e32 v20, vcc, s4, v36
	s_mov_b32 s4, 0x22000
	s_nop 0
	v_addc_co_u32_e32 v21, vcc, 0, v37, vcc
	global_load_dword v26, v[20:21], off nt
	v_add_co_u32_e32 v20, vcc, s4, v36
	s_mov_b32 s4, 0x24000
	s_nop 0
	v_addc_co_u32_e32 v21, vcc, 0, v37, vcc
	global_load_dword v27, v[20:21], off offset:2048 nt
	v_add_co_u32_e32 v20, vcc, s4, v36
	s_mov_b32 s4, 0x25000
	s_nop 0
	v_addc_co_u32_e32 v21, vcc, 0, v37, vcc
	global_load_dword v0, v[20:21], off nt
	v_add_co_u32_e32 v20, vcc, s4, v36
	s_mov_b32 s4, 0x27000
	s_nop 0
	v_addc_co_u32_e32 v21, vcc, 0, v37, vcc
	global_load_dword v40, v[20:21], off offset:2048 nt
	v_add_co_u32_e32 v20, vcc, s4, v36
	s_mov_b32 s4, 0x28000
	s_nop 0
	v_addc_co_u32_e32 v21, vcc, 0, v37, vcc
	global_load_dword v41, v[20:21], off nt
	v_add_co_u32_e32 v20, vcc, s4, v36
	s_mov_b32 s4, 0x2a000
	s_nop 0
	v_addc_co_u32_e32 v21, vcc, 0, v37, vcc
	global_load_dword v91, v[20:21], off offset:2048 nt
	v_add_co_u32_e32 v20, vcc, s4, v36
	v_add_lshl_u32 v104, s72, v2, 2
	s_nop 0
	v_addc_co_u32_e32 v21, vcc, 0, v37, vcc
	v_add_co_u32_e32 v22, vcc, 0x2b000, v36
	global_load_dword v20, v[20:21], off nt
	s_nop 0
	v_addc_co_u32_e32 v23, vcc, 0, v37, vcc
	global_load_dword v21, v[22:23], off offset:2048 nt
	v_add_co_u32_e32 v22, vcc, 0x2d000, v36
	s_nop 1
	v_addc_co_u32_e32 v23, vcc, 0, v37, vcc
	v_add_co_u32_e32 v36, vcc, 0x2e000, v36
	global_load_dword v22, v[22:23], off nt
	s_nop 0
	v_addc_co_u32_e32 v37, vcc, 0, v37, vcc
	global_load_dword v23, v[36:37], off offset:2048 nt
	v_cndmask_b32_e64 v36, 0, 1, s[44:45]
	v_cmp_ne_u32_e64 s[38:39], 1, v36
	s_andn2_b64 vcc, exec, s[44:45]
	s_cbranch_vccnz .LBB0_1248
	v_lshlrev_b32_e32 v36, 2, v38
	global_load_dword v36, v36, s[18:19]
	s_nop 0
	global_load_dword v37, v104, s[18:19] offset:8
	global_load_dword v38, v104, s[18:19] offset:16
	global_load_dword v39, v104, s[18:19] offset:24
	s_waitcnt vmcnt(0)
	v_mul_f32_e32 v36, v100, v36
	ds_write_b32 v44, v36
	v_mul_f32_e32 v37, v101, v37
	v_mul_f32_e32 v38, v102, v38
	v_add_u32_e32 v36, v43, v51
	v_mul_f32_e32 v39, v103, v39
	ds_write2_b32 v36, v37, v38 offset1:66
	ds_write_b32 v36, v39 offset:528
	global_load_dword v36, v104, s[18:19] offset:32
	global_load_dword v37, v104, s[18:19] offset:40
	global_load_dword v38, v104, s[18:19] offset:48
	global_load_dword v39, v104, s[18:19] offset:56
	s_waitcnt vmcnt(2)
	v_pk_mul_f32 v[36:37], v[32:33], v[36:37]
	s_waitcnt vmcnt(0)
	v_pk_mul_f32 v[38:39], v[34:35], v[38:39]
	s_cbranch_execnz .LBB0_1149

; __device__ __forceinline__ void wconv_item(const float* W, int K, int Norig, int Nphys, bf16_t* WT, const float* gA, const float* gB, int split, int mapid, LAS float* scr, int item, int lane) {
;     ...
;     const int norig = colmap(mapid, n0 + (lane & 31));
;     float wv[32];
; #pragma unroll
;     for (int i = 0; i < 32; ++i) { const int k = k0 + 2 * i + (lane >> 5); wv[i] = (norig >= 0) ? W[(size_t)k * Norig + norig] : 0.f; }
.LBB0_1168:
	s_or_b64 exec, exec, s[38:39]
	s_lshl_b32 s64, s72, 6
	v_cmp_lt_i32_e32 vcc, -1, v0
	v_or_b32_e32 v36, s64, v2
	v_lshl_add_u64 v[38:39], v[0:1], 2, s[42:43]
	v_mov_b32_e32 v100, 0
	v_mov_b32_e32 v101, 0
	s_and_saveexec_b64 s[38:39], vcc
	s_cbranch_execz .LBB0_1170
	v_mad_i64_i32 v[20:21], s[72:73], v36, s29, v[38:39]
	global_load_dword v101, v[20:21], off nt
.LBB0_1170:
	s_or_b64 exec, exec, s[38:39]
	s_and_saveexec_b64 s[38:39], vcc
	s_cbranch_execz .LBB0_1172
	v_or_b32_e32 v0, 2, v36
	v_mad_i64_i32 v[20:21], s[72:73], v0, s29, v[38:39]
	global_load_dword v100, v[20:21], off nt
.LBB0_1172:
	s_or_b64 exec, exec, s[38:39]
	v_mov_b32_e32 v102, 0
	v_mov_b32_e32 v103, 0
	s_and_saveexec_b64 s[38:39], vcc
	s_cbranch_execz .LBB0_1174
	v_or_b32_e32 v0, 4, v36
	v_mad_i64_i32 v[20:21], s[72:73], v0, s29, v[38:39]
	global_load_dword v103, v[20:21], off nt
.LBB0_1174:
	s_or_b64 exec, exec, s[38:39]
	s_and_saveexec_b64 s[38:39], vcc
	s_cbranch_execz .LBB0_1176
	v_or_b32_e32 v0, 6, v36
	v_mad_i64_i32 v[20:21], s[72:73], v0, s29, v[38:39]
	global_load_dword v102, v[20:21], off nt
.LBB0_1176:
	s_or_b64 exec, exec, s[38:39]
	v_mov_b32_e32 v33, 0
	v_mov_b32_e32 v32, 0
	s_and_saveexec_b64 s[38:39], vcc
	s_cbranch_execz .LBB0_1178
	v_or_b32_e32 v0, 8, v36
	v_mad_i64_i32 v[20:21], s[72:73], v0, s29, v[38:39]
	global_load_dword v32, v[20:21], off nt
.LBB0_1178:
	s_or_b64 exec, exec, s[38:39]
	s_and_saveexec_b64 s[38:39], vcc
	s_cbranch_execz .LBB0_1180
	v_or_b32_e32 v0, 10, v36
	v_mad_i64_i32 v[20:21], s[72:73], v0, s29, v[38:39]
	global_load_dword v33, v[20:21], off nt
.LBB0_1180:
	s_or_b64 exec, exec, s[38:39]
	v_mov_b32_e32 v35, 0
	v_mov_b32_e32 v34, 0
	s_and_saveexec_b64 s[38:39], vcc
	s_cbranch_execz .LBB0_1182
	v_or_b32_e32 v0, 12, v36
	v_mad_i64_i32 v[20:21], s[72:73], v0, s29, v[38:39]
	global_load_dword v34, v[20:21], off nt
.LBB0_1182:
	s_or_b64 exec, exec, s[38:39]
	s_and_saveexec_b64 s[38:39], vcc
	s_cbranch_execz .LBB0_1184
	v_or_b32_e32 v0, 14, v36
	v_mad_i64_i32 v[20:21], s[72:73], v0, s29, v[38:39]
	global_load_dword v35, v[20:21], off nt
.LBB0_1184:
	s_or_b64 exec, exec, s[38:39]
	v_mov_b32_e32 v96, 0
	v_mov_b32_e32 v97, 0
	s_and_saveexec_b64 s[38:39], vcc
	s_cbranch_execz .LBB0_1186
	v_or_b32_e32 v0, 16, v36
	v_mad_i64_i32 v[20:21], s[72:73], v0, s29, v[38:39]
	global_load_dword v97, v[20:21], off nt
.LBB0_1186:
	s_or_b64 exec, exec, s[38:39]
	s_and_saveexec_b64 s[38:39], vcc
	s_cbranch_execz .LBB0_1188
	v_or_b32_e32 v0, 18, v36
	v_mad_i64_i32 v[20:21], s[72:73], v0, s29, v[38:39]
	global_load_dword v96, v[20:21], off nt
.LBB0_1188:
	s_or_b64 exec, exec, s[38:39]
	v_mov_b32_e32 v98, 0
	v_mov_b32_e32 v99, 0
	s_and_saveexec_b64 s[38:39], vcc
	s_cbranch_execz .LBB0_1190
	v_or_b32_e32 v0, 20, v36
	v_mad_i64_i32 v[20:21], s[72:73], v0, s29, v[38:39]
	global_load_dword v99, v[20:21], off nt
.LBB0_1190:
	s_or_b64 exec, exec, s[38:39]
	s_and_saveexec_b64 s[38:39], vcc
	s_cbranch_execz .LBB0_1192
	v_or_b32_e32 v0, 22, v36
	v_mad_i64_i32 v[20:21], s[72:73], v0, s29, v[38:39]
	global_load_dword v98, v[20:21], off nt
.LBB0_1192:
	s_or_b64 exec, exec, s[38:39]
	v_mov_b32_e32 v29, 0
	v_mov_b32_e32 v28, 0
	s_and_saveexec_b64 s[38:39], vcc
	s_cbranch_execz .LBB0_1194
	v_or_b32_e32 v0, 24, v36
	v_mad_i64_i32 v[20:21], s[72:73], v0, s29, v[38:39]
	global_load_dword v28, v[20:21], off nt
.LBB0_1194:
	s_or_b64 exec, exec, s[38:39]
	s_and_saveexec_b64 s[38:39], vcc
	s_cbranch_execz .LBB0_1196
	v_or_b32_e32 v0, 26, v36
	v_mad_i64_i32 v[20:21], s[72:73], v0, s29, v[38:39]
	global_load_dword v29, v[20:21], off nt
.LBB0_1196:
	s_or_b64 exec, exec, s[38:39]
	v_mov_b32_e32 v31, 0
	v_mov_b32_e32 v30, 0
	s_and_saveexec_b64 s[38:39], vcc
	s_cbranch_execz .LBB0_1198
	v_or_b32_e32 v0, 28, v36
	v_mad_i64_i32 v[20:21], s[72:73], v0, s29, v[38:39]
	global_load_dword v30, v[20:21], off nt
.LBB0_1198:
	s_or_b64 exec, exec, s[38:39]
	s_and_saveexec_b64 s[38:39], vcc
	s_cbranch_execz .LBB0_1200
	v_or_b32_e32 v0, 30, v36
	v_mad_i64_i32 v[20:21], s[72:73], v0, s29, v[38:39]
	global_load_dword v31, v[20:21], off nt
.LBB0_1200:
	s_or_b64 exec, exec, s[38:39]
	v_mov_b32_e32 v92, 0
	v_mov_b32_e32 v93, 0
	s_and_saveexec_b64 s[38:39], vcc
	s_cbranch_execz .LBB0_1202
	v_or_b32_e32 v0, 32, v36
	v_mad_i64_i32 v[20:21], s[72:73], v0, s29, v[38:39]
	global_load_dword v93, v[20:21], off nt
.LBB0_1202:
	s_or_b64 exec, exec, s[38:39]
	s_and_saveexec_b64 s[38:39], vcc
	s_cbranch_execz .LBB0_1204
	v_or_b32_e32 v0, 34, v36
	v_mad_i64_i32 v[20:21], s[72:73], v0, s29, v[38:39]
	global_load_dword v92, v[20:21], off nt
.LBB0_1204:
	s_or_b64 exec, exec, s[38:39]
	v_mov_b32_e32 v94, 0
	v_mov_b32_e32 v95, 0
	s_and_saveexec_b64 s[38:39], vcc
	s_cbranch_execz .LBB0_1206
	v_or_b32_e32 v0, 36, v36
	v_mad_i64_i32 v[20:21], s[72:73], v0, s29, v[38:39]
	global_load_dword v95, v[20:21], off nt
.LBB0_1206:
	s_or_b64 exec, exec, s[38:39]
	s_and_saveexec_b64 s[38:39], vcc
	s_cbranch_execz .LBB0_1208
	v_or_b32_e32 v0, 38, v36
	v_mad_i64_i32 v[20:21], s[72:73], v0, s29, v[38:39]
	global_load_dword v94, v[20:21], off nt
.LBB0_1208:
	s_or_b64 exec, exec, s[38:39]
	v_mov_b32_e32 v25, 0
	v_mov_b32_e32 v24, 0
	s_and_saveexec_b64 s[38:39], vcc
	s_cbranch_execz .LBB0_1210
	v_or_b32_e32 v0, 40, v36
	v_mad_i64_i32 v[20:21], s[72:73], v0, s29, v[38:39]
	global_load_dword v24, v[20:21], off nt
; __device__ __forceinline__ void wconv_item(const float* W, int K, int Norig, int Nphys, bf16_t* WT, const float* gA, const float* gB, int split, int mapid, LAS float* scr, int item, int lane) {
;     ...
;     for (int i = 0; i < 32; ++i) { const int k = k0 + 2 * i + (lane >> 5); wv[i] = (norig >= 0) ? W[(size_t)k * Norig + norig] : 0.f; }
; #pragma unroll
;     for (int i = 0; i < 32; ++i) { const int kk = 2 * i + (lane >> 5), k = k0 + kk;
;         float v = wv[i];
;         if (gA) v *= (k < split ? gA[k] : gB[k - split]);
;         scr[kk * 33 + (lane & 31)] = v; }
.LBB0_1210:
	s_or_b64 exec, exec, s[38:39]
	s_and_saveexec_b64 s[38:39], vcc
	s_cbranch_execz .LBB0_1212
	v_or_b32_e32 v0, 42, v36
	v_mad_i64_i32 v[20:21], s[72:73], v0, s29, v[38:39]
	global_load_dword v25, v[20:21], off nt
.LBB0_1212:
	s_or_b64 exec, exec, s[38:39]
	v_mov_b32_e32 v27, 0
	v_mov_b32_e32 v26, 0
	s_and_saveexec_b64 s[38:39], vcc
	s_cbranch_execz .LBB0_1214
	v_or_b32_e32 v0, 44, v36
	v_mad_i64_i32 v[20:21], s[72:73], v0, s29, v[38:39]
	global_load_dword v26, v[20:21], off nt
.LBB0_1214:
	s_or_b64 exec, exec, s[38:39]
	s_and_saveexec_b64 s[38:39], vcc
	s_cbranch_execz .LBB0_1216
	v_or_b32_e32 v0, 46, v36
	v_mad_i64_i32 v[20:21], s[72:73], v0, s29, v[38:39]
	global_load_dword v27, v[20:21], off nt
.LBB0_1216:
	s_or_b64 exec, exec, s[38:39]
	v_mov_b32_e32 v0, 0
	v_mov_b32_e32 v40, 0
	s_and_saveexec_b64 s[38:39], vcc
	s_cbranch_execz .LBB0_1218
	v_or_b32_e32 v20, 48, v36
	v_mad_i64_i32 v[20:21], s[72:73], v20, s29, v[38:39]
	global_load_dword v40, v[20:21], off nt
.LBB0_1218:
	s_or_b64 exec, exec, s[38:39]
	s_and_saveexec_b64 s[38:39], vcc
	s_cbranch_execz .LBB0_1220
	v_or_b32_e32 v0, 50, v36
	v_mad_i64_i32 v[20:21], s[72:73], v0, s29, v[38:39]
	global_load_dword v0, v[20:21], off nt
.LBB0_1220:
	s_or_b64 exec, exec, s[38:39]
	v_mov_b32_e32 v41, 0
	v_mov_b32_e32 v91, 0
	s_and_saveexec_b64 s[38:39], vcc
	s_cbranch_execz .LBB0_1222
	v_or_b32_e32 v20, 52, v36
	v_mad_i64_i32 v[20:21], s[72:73], v20, s29, v[38:39]
	global_load_dword v91, v[20:21], off nt
.LBB0_1222:
	s_or_b64 exec, exec, s[38:39]
	s_and_saveexec_b64 s[38:39], vcc
	s_cbranch_execz .LBB0_1224
	v_or_b32_e32 v20, 54, v36
	v_mad_i64_i32 v[20:21], s[72:73], v20, s29, v[38:39]
	global_load_dword v41, v[20:21], off nt
.LBB0_1224:
	s_or_b64 exec, exec, s[38:39]
	v_mov_b32_e32 v21, 0
	v_mov_b32_e32 v20, 0
	s_and_saveexec_b64 s[38:39], vcc
	s_cbranch_execz .LBB0_1226
	v_or_b32_e32 v20, 56, v36
	v_mad_i64_i32 v[22:23], s[72:73], v20, s29, v[38:39]
	global_load_dword v20, v[22:23], off nt
.LBB0_1226:
	s_or_b64 exec, exec, s[38:39]
	s_and_saveexec_b64 s[38:39], vcc
	s_cbranch_execz .LBB0_1228
	v_or_b32_e32 v21, 58, v36
	v_mad_i64_i32 v[22:23], s[72:73], v21, s29, v[38:39]
	global_load_dword v21, v[22:23], off nt
.LBB0_1228:
	s_or_b64 exec, exec, s[38:39]
	v_mov_b32_e32 v23, 0
	v_mov_b32_e32 v22, 0
	s_and_saveexec_b64 s[38:39], vcc
	s_cbranch_execz .LBB0_1230
	v_or_b32_e32 v22, 60, v36
	v_mad_i64_i32 v[104:105], s[72:73], v22, s29, v[38:39]
	global_load_dword v22, v[104:105], off nt
.LBB0_1230:
	s_or_b64 exec, exec, s[38:39]
	s_and_saveexec_b64 s[38:39], vcc
	s_cbranch_execz .LBB0_1232
	v_or_b32_e32 v23, 62, v36
	v_mad_i64_i32 v[38:39], s[72:73], v23, s29, v[38:39]
	global_load_dword v23, v[38:39], off nt
.LBB0_1232:
	s_or_b64 exec, exec, s[38:39]
	v_cndmask_b32_e64 v37, 0, 1, s[40:41]
	v_cmp_ne_u32_e64 s[38:39], 1, v37
	s_andn2_b64 vcc, exec, s[40:41]
	v_add_u32_e32 v104, v43, v51
	s_cbranch_vccnz .LBB0_1243
	v_cmp_gt_i32_e32 vcc, s37, v36
	v_ashrrev_i32_e32 v37, 31, v36
	v_lshl_add_u64 v[36:37], v[36:37], 2, s[50:51]
	v_cndmask_b32_e64 v39, -1, 0, vcc
	v_cndmask_b32_e64 v38, v228, 0, vcc
	v_lshl_add_u64 v[36:37], v[36:37], 0, v[38:39]
	global_load_dword v36, v[36:37], off nt
	s_ashr_i32 s65, s64, 31
	s_waitcnt vmcnt(0)
	v_mul_f32_e32 v105, v101, v36
	v_or_b32_e32 v36, s64, v50
	v_cmp_gt_i32_e32 vcc, s37, v36
	v_lshl_add_u64 v[36:37], s[64:65], 0, v[2:3]
	v_lshl_add_u64 v[38:39], v[36:37], 2, s[50:51]
	v_cndmask_b32_e64 v37, -1, 0, vcc
	v_cndmask_b32_e64 v36, v228, 0, vcc
	v_lshl_add_u64 v[36:37], v[38:39], 0, v[36:37]
	global_load_dword v36, v[36:37], off offset:8 nt
	s_waitcnt vmcnt(0)
	v_mul_f32_e32 v106, v100, v36
	v_or_b32_e32 v36, s64, v52
	v_cmp_gt_i32_e32 vcc, s37, v36
	s_nop 1
	v_cndmask_b32_e64 v37, -1, 0, vcc
	v_cndmask_b32_e64 v36, v228, 0, vcc
	v_lshl_add_u64 v[36:37], v[38:39], 0, v[36:37]
	global_load_dword v36, v[36:37], off offset:16 nt
	s_waitcnt vmcnt(0)
	v_mul_f32_e32 v107, v103, v36
	v_or_b32_e32 v36, s64, v53
	v_cmp_gt_i32_e32 vcc, s37, v36
	s_nop 1
	v_cndmask_b32_e64 v37, -1, 0, vcc
	v_cndmask_b32_e64 v36, v228, 0, vcc
	v_lshl_add_u64 v[36:37], v[38:39], 0, v[36:37]
	global_load_dword v36, v[36:37], off offset:24 nt
	s_waitcnt vmcnt(0)
	v_mul_f32_e32 v36, v102, v36
	ds_write_b32 v44, v105
	ds_write2_b32 v104, v106, v107 offset1:66
	ds_write_b32 v104, v36 offset:528
	v_or_b32_e32 v36, s64, v54
	v_cmp_gt_i32_e32 vcc, s37, v36
	v_or_b32_e32 v105, s64, v57
	s_nop 0
	v_cndmask_b32_e64 v37, -1, 0, vcc
	v_cndmask_b32_e64 v36, v228, 0, vcc
	v_lshl_add_u64 v[36:37], v[38:39], 0, v[36:37]
	global_load_dword v36, v[36:37], off offset:32 nt
	v_or_b32_e32 v37, s64, v56
	v_cmp_gt_i32_e32 vcc, s37, v37
	s_nop 1
	v_cndmask_b32_e64 v107, -1, 0, vcc
	v_cndmask_b32_e64 v106, v228, 0, vcc
	v_lshl_add_u64 v[106:107], v[38:39], 0, v[106:107]
	v_cmp_gt_i32_e32 vcc, s37, v105
	v_or_b32_e32 v105, s64, v58
	global_load_dword v37, v[106:107], off offset:40 nt
	v_cndmask_b32_e64 v107, -1, 0, vcc
	v_cndmask_b32_e64 v106, v228, 0, vcc
	v_cmp_gt_i32_e32 vcc, s37, v105
	v_lshl_add_u64 v[106:107], v[38:39], 0, v[106:107]
	global_load_dword v106, v[106:107], off offset:48 nt
	v_cndmask_b32_e64 v109, -1, 0, vcc
	v_cndmask_b32_e64 v108, v228, 0, vcc
	v_lshl_add_u64 v[38:39], v[38:39], 0, v[108:109]
	global_load_dword v107, v[38:39], off offset:56 nt
	s_waitcnt vmcnt(2)
	v_pk_mul_f32 v[36:37], v[32:33], v[36:37]
	s_waitcnt vmcnt(0)
	v_pk_mul_f32 v[38:39], v[34:35], v[106:107]
	s_cbranch_execnz .LBB0_1235

; __device__ __forceinline__ void wconv_item(const float* W, int K, int Norig, int Nphys, bf16_t* WT, const float* gA, const float* gB, int split, int mapid, LAS float* scr, int item, int lane) {
;     ...
;     for (int i = 0; i < 32; ++i) { const int kk = 2 * i + (lane >> 5), k = k0 + kk;
;         float v = wv[i];
;         if (gA) v *= (k < split ? gA[k] : gB[k - split]);
;         scr[kk * 33 + (lane & 31)] = v; }
.LBB0_1235:
	s_waitcnt vmcnt(0)
	v_add_u32_e32 v32, v43, v55
	ds_write2_b32 v32, v36, v37 offset1:66
	ds_write2_b32 v32, v38, v39 offset0:132 offset1:198
	s_and_b64 vcc, exec, s[38:39]
	v_add_u32_e32 v36, v43, v60
	s_cbranch_vccnz .LBB0_1244
	v_or_b32_e32 v32, s64, v59
	s_ashr_i32 s65, s64, 31
	v_cmp_gt_i32_e32 vcc, s37, v32
	v_lshl_add_u64 v[32:33], s[64:65], 0, v[2:3]
	v_lshl_add_u64 v[34:35], v[32:33], 2, s[50:51]
	v_cndmask_b32_e64 v33, -1, 0, vcc
	v_cndmask_b32_e64 v32, v228, 0, vcc
	v_lshl_add_u64 v[32:33], v[34:35], 0, v[32:33]
	global_load_dword v32, v[32:33], off offset:64 nt
	s_waitcnt vmcnt(0)
	v_mul_f32_e32 v37, v97, v32
	v_or_b32_e32 v32, s64, v61
	v_cmp_gt_i32_e32 vcc, s37, v32
	s_nop 1
	v_cndmask_b32_e64 v33, -1, 0, vcc
	v_cndmask_b32_e64 v32, v228, 0, vcc
	v_lshl_add_u64 v[32:33], v[34:35], 0, v[32:33]
	global_load_dword v32, v[32:33], off offset:72 nt
	s_waitcnt vmcnt(0)
	v_mul_f32_e32 v38, v96, v32
	v_or_b32_e32 v32, s64, v62
	v_cmp_gt_i32_e32 vcc, s37, v32
	s_nop 1
	v_cndmask_b32_e64 v33, -1, 0, vcc
	v_cndmask_b32_e64 v32, v228, 0, vcc
	v_lshl_add_u64 v[32:33], v[34:35], 0, v[32:33]
	global_load_dword v32, v[32:33], off offset:80 nt
	s_waitcnt vmcnt(0)
	v_mul_f32_e32 v39, v99, v32
	v_or_b32_e32 v32, s64, v63
	v_cmp_gt_i32_e32 vcc, s37, v32
	s_nop 1
	v_cndmask_b32_e64 v33, -1, 0, vcc
	v_cndmask_b32_e64 v32, v228, 0, vcc
	v_lshl_add_u64 v[32:33], v[34:35], 0, v[32:33]
	global_load_dword v32, v[32:33], off offset:88 nt
	s_waitcnt vmcnt(0)
	v_mul_f32_e32 v32, v98, v32
	ds_write2_b32 v36, v37, v38 offset1:66
	ds_write2_b32 v36, v39, v32 offset0:132 offset1:198
	v_or_b32_e32 v32, s64, v64
	v_cmp_gt_i32_e32 vcc, s37, v32
	v_or_b32_e32 v37, s64, v67
	s_nop 0
	v_cndmask_b32_e64 v33, -1, 0, vcc
	v_cndmask_b32_e64 v32, v228, 0, vcc
	v_lshl_add_u64 v[32:33], v[34:35], 0, v[32:33]
	global_load_dword v32, v[32:33], off offset:96 nt
	v_or_b32_e32 v33, s64, v66
	v_cmp_gt_i32_e32 vcc, s37, v33
	s_nop 1
	v_cndmask_b32_e64 v39, -1, 0, vcc
	v_cndmask_b32_e64 v38, v228, 0, vcc
	v_lshl_add_u64 v[38:39], v[34:35], 0, v[38:39]
	v_cmp_gt_i32_e32 vcc, s37, v37
	v_or_b32_e32 v37, s64, v68
	global_load_dword v33, v[38:39], off offset:104 nt
	v_cndmask_b32_e64 v39, -1, 0, vcc
	v_cndmask_b32_e64 v38, v228, 0, vcc
	v_cmp_gt_i32_e32 vcc, s37, v37
	v_lshl_add_u64 v[38:39], v[34:35], 0, v[38:39]
	global_load_dword v38, v[38:39], off offset:112 nt
	v_cndmask_b32_e64 v101, -1, 0, vcc
	v_cndmask_b32_e64 v100, v228, 0, vcc
	v_lshl_add_u64 v[34:35], v[34:35], 0, v[100:101]
	global_load_dword v39, v[34:35], off offset:120 nt
	s_waitcnt vmcnt(2)
	v_pk_mul_f32 v[32:33], v[28:29], v[32:33]
	s_waitcnt vmcnt(0)
	v_pk_mul_f32 v[34:35], v[30:31], v[38:39]
	s_cbranch_execnz .LBB0_1238

; __device__ __forceinline__ void wconv_item(const float* W, int K, int Norig, int Nphys, bf16_t* WT, const float* gA, const float* gB, int split, int mapid, LAS float* scr, int item, int lane) {
;     ...
;     for (int i = 0; i < 32; ++i) { const int kk = 2 * i + (lane >> 5), k = k0 + kk;
;         float v = wv[i];
;         if (gA) v *= (k < split ? gA[k] : gB[k - split]);
;         scr[kk * 33 + (lane & 31)] = v; }
.LBB0_1238:
	v_add_u32_e32 v28, v43, v65
	ds_write2_b32 v28, v32, v33 offset1:66
	ds_write2_b32 v28, v34, v35 offset0:132 offset1:198
	s_and_b64 vcc, exec, s[38:39]
	v_add_u32_e32 v32, v43, v70
	s_cbranch_vccnz .LBB0_1245
	v_or_b32_e32 v30, s64, v69
	v_cmp_gt_i32_e32 vcc, s37, v30
	v_or_b32_e32 v33, s64, v71
	s_ashr_i32 s65, s64, 31
	v_cndmask_b32_e64 v31, -1, 0, vcc
	v_cndmask_b32_e64 v30, v228, 0, vcc
	v_cmp_gt_i32_e32 vcc, s37, v33
	v_or_b32_e32 v33, s64, v72
	v_lshl_add_u64 v[28:29], s[64:65], 0, v[2:3]
	v_cndmask_b32_e64 v35, -1, 0, vcc
	v_cndmask_b32_e64 v34, v228, 0, vcc
	v_cmp_gt_i32_e32 vcc, s37, v33
	v_or_b32_e32 v33, s64, v73
	v_lshl_add_u64 v[28:29], v[28:29], 2, s[50:51]
	v_cndmask_b32_e64 v37, -1, 0, vcc
	v_cndmask_b32_e64 v36, v228, 0, vcc
	v_cmp_gt_i32_e32 vcc, s37, v33
	v_or_b32_e32 v33, s64, v74
	v_lshl_add_u64 v[30:31], v[28:29], 0, v[30:31]
	v_cndmask_b32_e64 v39, -1, 0, vcc
	v_cndmask_b32_e64 v38, v228, 0, vcc
	v_cmp_gt_i32_e32 vcc, s37, v33
	v_or_b32_e32 v33, s64, v76
	v_lshl_add_u64 v[34:35], v[28:29], 0, v[34:35]
	v_cndmask_b32_e64 v97, -1, 0, vcc
	v_cndmask_b32_e64 v96, v228, 0, vcc
	v_cmp_gt_i32_e32 vcc, s37, v33
	v_or_b32_e32 v33, s64, v77
	v_lshl_add_u64 v[36:37], v[28:29], 0, v[36:37]
	v_cndmask_b32_e64 v99, -1, 0, vcc
	v_cndmask_b32_e64 v98, v228, 0, vcc
	v_cmp_gt_i32_e32 vcc, s37, v33
	v_or_b32_e32 v33, s64, v78
	v_lshl_add_u64 v[38:39], v[28:29], 0, v[38:39]
	v_cndmask_b32_e64 v101, -1, 0, vcc
	v_cndmask_b32_e64 v100, v228, 0, vcc
	v_cmp_gt_i32_e32 vcc, s37, v33
	v_lshl_add_u64 v[96:97], v[28:29], 0, v[96:97]
	v_lshl_add_u64 v[98:99], v[28:29], 0, v[98:99]
	v_cndmask_b32_e64 v103, -1, 0, vcc
	v_cndmask_b32_e64 v102, v228, 0, vcc
	v_lshl_add_u64 v[100:101], v[28:29], 0, v[100:101]
	v_lshl_add_u64 v[28:29], v[28:29], 0, v[102:103]
	global_load_dword v33, v[30:31], off offset:128 nt
	global_load_dword v102, v[34:35], off offset:136 nt
	s_nop 0
	global_load_dword v36, v[36:37], off offset:144 nt
	s_nop 0
	global_load_dword v37, v[38:39], off offset:152 nt
	global_load_dword v30, v[96:97], off offset:160 nt
	global_load_dword v31, v[98:99], off offset:168 nt
	global_load_dword v34, v[100:101], off offset:176 nt
	global_load_dword v35, v[28:29], off offset:184 nt
	s_waitcnt vmcnt(7)
	v_mul_f32_e32 v33, v93, v33
	s_waitcnt vmcnt(6)
	v_mul_f32_e32 v38, v92, v102
	s_waitcnt vmcnt(5)
	v_mul_f32_e32 v36, v95, v36
	s_waitcnt vmcnt(4)
	v_mul_f32_e32 v37, v94, v37
	ds_write2_b32 v32, v33, v38 offset1:66
	ds_write2_b32 v32, v36, v37 offset0:132 offset1:198
	s_waitcnt vmcnt(2)
	v_pk_mul_f32 v[28:29], v[24:25], v[30:31]
	s_waitcnt vmcnt(0)
	v_pk_mul_f32 v[30:31], v[26:27], v[34:35]
	s_cbranch_execnz .LBB0_1241

; __device__ __forceinline__ void wconv_item(const float* W, int K, int Norig, int Nphys, bf16_t* WT, const float* gA, const float* gB, int split, int mapid, LAS float* scr, int item, int lane) {
;     ...
;     for (int i = 0; i < 32; ++i) { const int kk = 2 * i + (lane >> 5), k = k0 + kk;
;         float v = wv[i];
;         if (gA) v *= (k < split ? gA[k] : gB[k - split]);
;         scr[kk * 33 + (lane & 31)] = v; }
.LBB0_1241:
	v_add_u32_e32 v24, v43, v75
	ds_write2_b32 v24, v28, v29 offset1:66
	ds_write2_b32 v24, v30, v31 offset0:132 offset1:198
	s_and_b64 vcc, exec, s[38:39]
	v_add_u32_e32 v28, v43, v80
	s_cbranch_vccnz .LBB0_1246
	v_or_b32_e32 v24, s64, v79
	s_ashr_i32 s65, s64, 31
	v_cmp_gt_i32_e32 vcc, s37, v24
	v_lshl_add_u64 v[24:25], s[64:65], 0, v[2:3]
	v_lshl_add_u64 v[26:27], v[24:25], 2, s[50:51]
	v_cndmask_b32_e64 v25, -1, 0, vcc
	v_cndmask_b32_e64 v24, v228, 0, vcc
	v_lshl_add_u64 v[24:25], v[26:27], 0, v[24:25]
	global_load_dword v24, v[24:25], off offset:192 nt
	s_waitcnt vmcnt(0)
	v_mul_f32_e32 v29, v40, v24
	v_or_b32_e32 v24, s64, v81
	v_cmp_gt_i32_e32 vcc, s37, v24
	s_nop 1
	v_cndmask_b32_e64 v25, -1, 0, vcc
	v_cndmask_b32_e64 v24, v228, 0, vcc
	v_lshl_add_u64 v[24:25], v[26:27], 0, v[24:25]
	global_load_dword v24, v[24:25], off offset:200 nt
	s_waitcnt vmcnt(0)
	v_mul_f32_e32 v30, v0, v24
	v_or_b32_e32 v24, s64, v82
	v_cmp_gt_i32_e32 vcc, s37, v24
	s_nop 1
	v_cndmask_b32_e64 v25, -1, 0, vcc
	v_cndmask_b32_e64 v24, v228, 0, vcc
	v_lshl_add_u64 v[24:25], v[26:27], 0, v[24:25]
	global_load_dword v24, v[24:25], off offset:208 nt
	s_waitcnt vmcnt(0)
	v_mul_f32_e32 v31, v91, v24
	v_or_b32_e32 v24, s64, v83
	v_cmp_gt_i32_e32 vcc, s37, v24
	s_nop 1
	v_cndmask_b32_e64 v25, -1, 0, vcc
	v_cndmask_b32_e64 v24, v228, 0, vcc
	v_lshl_add_u64 v[24:25], v[26:27], 0, v[24:25]
	global_load_dword v24, v[24:25], off offset:216 nt
	s_waitcnt vmcnt(0)
	v_mul_f32_e32 v24, v41, v24
	ds_write2_b32 v28, v29, v30 offset1:66
	ds_write2_b32 v28, v31, v24 offset0:132 offset1:198
	v_or_b32_e32 v24, s64, v84
	v_cmp_gt_i32_e32 vcc, s37, v24
	v_or_b32_e32 v29, s64, v86
	s_nop 0
	v_cndmask_b32_e64 v25, -1, 0, vcc
	v_cndmask_b32_e64 v24, v228, 0, vcc
	v_lshl_add_u64 v[24:25], v[26:27], 0, v[24:25]
	global_load_dword v24, v[24:25], off offset:224 nt
	v_or_b32_e32 v25, s64, v85
	v_cmp_gt_i32_e32 vcc, s37, v25
	s_nop 1
	v_cndmask_b32_e64 v31, -1, 0, vcc
	v_cndmask_b32_e64 v30, v228, 0, vcc
	v_lshl_add_u64 v[30:31], v[26:27], 0, v[30:31]
	v_cmp_gt_i32_e32 vcc, s37, v29
	v_or_b32_e32 v29, s64, v87
	global_load_dword v25, v[30:31], off offset:232 nt
	v_cndmask_b32_e64 v31, -1, 0, vcc
	v_cndmask_b32_e64 v30, v228, 0, vcc
	v_cmp_gt_i32_e32 vcc, s37, v29
	v_lshl_add_u64 v[30:31], v[26:27], 0, v[30:31]
	global_load_dword v30, v[30:31], off offset:240 nt
	v_cndmask_b32_e64 v33, -1, 0, vcc
	v_cndmask_b32_e64 v32, v228, 0, vcc
	v_lshl_add_u64 v[26:27], v[26:27], 0, v[32:33]
	global_load_dword v31, v[26:27], off offset:248 nt
	s_waitcnt vmcnt(2)
	v_pk_mul_f32 v[24:25], v[20:21], v[24:25]
	s_waitcnt vmcnt(0)
	v_pk_mul_f32 v[26:27], v[22:23], v[30:31]
	s_cbranch_execnz .LBB0_1064
	s_branch .LBB0_1247
